# GEMM LDS-DMA loads use scalar base + 32-bit offset (55 sites), removing per-phase 64-bit VALU address adds
# speedup vs baseline: 1.0038x; 1.0038x over previous
; __device__ __forceinline__ int otid(int wv) { int t = (wv << 6) | (int)__builtin_amdgcn_mbcnt_hi(~0u, __builtin_amdgcn_mbcnt_lo(~0u, 0u)); asm volatile("" : "+v"(t)); return t; }
; #define PG8_STAGE(bufoff, gbase, voff) do { _Pragma("unroll") for (int _i = 0; _i < 2; ++_i) \
;         __builtin_amdgcn_global_load_lds((const unsigned*)((const char*)(gbase) + (voff)[_i]), (LAS unsigned*)(lds + (bufoff) + ldsw + _i * 8192), 16, 0, 0); } while (0)
; #define PG8_WAIT_V(n) asm volatile("s_waitcnt vmcnt(" #n ")" ::: "memory")
; #define PG8_BAR __builtin_amdgcn_s_barrier()
; template <class Epi, class Sched, bool AREMAP>
; __device__ __forceinline__ void gemm_phase(LAS unsigned char* lds, const Gemm g, const Sched& S, const Epi& E, int wv) {
;     const int tid = otid(wv), wid = __builtin_amdgcn_readfirstlane(tid >> 6), lane = tid & 63, wr = wid >> 2, wc = wid & 3, fr = lane & 15, fq = lane >> 4;
;     const int K = g.K, nt = K / BK;
;     unsigned voffA[2], voffB[2];
; #pragma unroll
;     for (int i = 0; i < 2; ++i) { int R, C; stage_rc(tid * 16 + i * 8192, R, C); const int Rb = Epi::PERM ? ((R & ~31) + perm32(R & 31)) : R;
;         const int Ra = AREMAP ? ((R >> 6) * 128 + (R & 63)) : R;
;         voffA[i] = (unsigned)(Ra * g.lda + C) * 2u; voffB[i] = (unsigned)(Rb * g.ldb + C) * 2u; }
;     const size_t kstep = (size_t)(BK * 2);
;     const size_t hstepA = (size_t)(AREMAP ? 64 : HALF) * g.lda * 2, hstepB = (size_t)HALF * g.ldb * 2;
;     const size_t tstepA = (size_t)BM * g.lda * 2, tstepB = (size_t)BM * g.ldb * 2;
;     const unsigned ldsw = (unsigned)wid * 1024u;
;     const int aoff = lds_byte(wr * 64 + fr, fq * 8), boff = lds_byte(wc * 32 + fr, fq * 8);
;     ...
;     PG8_STAGE(PG8_SB(0, 0), cB, voffB); PG8_STAGE(PG8_SA(0, 0), cA, voffA); PG8_STAGE(PG8_SB(0, 1), cB + hstepB, voffB); PG8_STAGE(PG8_SA(0, 1), cA + hstepA, voffA);
;     if (wr == 1) PG8_BAR;
;     PG8_WAIT_V(4); PG8_BAR;
;     PG8_STAGE(PG8_SB(1, 0), cB + kstep, voffB); PG8_STAGE(PG8_SA(1, 0), cA + kstep, voffA); PG8_STAGE(PG8_SB(1, 1), cB + hstepB + kstep, voffB);
;     PG8_WAIT_V(6); PG8_BAR;
.LBB0_194:
	s_add_u32 s4, s2, 0x10e00000
	s_addc_u32 s5, s3, 0
	s_lshl_b32 s1, s1, 5
	s_and_b32 s1, s1, 0x60
	s_add_i32 m0, s7, 0x18000
	v_lshl_add_u64 v[8:9], v[8:9], 0, s[86:87]
	s_lshl_b32 s9, s8, 13
	s_lshl_b32 s12, s1, 7
	s_waitcnt vmcnt(4)
	s_barrier
	global_load_lds_dwordx4 v[8:9], off
	v_lshl_add_u64 v[6:7], v[6:7], 0, s[86:87]
	s_add_i32 m0, s7, 0x1a000
	s_add_i32 s35, s7, 0x8000
	s_add_i32 s36, s7, 0xa000
	global_load_lds_dwordx4 v[6:7], off
	v_lshl_add_u64 v[4:5], v[4:5], 0, s[86:87]
	s_mov_b32 m0, s35
	s_add_u32 s10, s16, 0x80080
	global_load_lds_dwordx4 v[4:5], off
	v_lshl_add_u64 v[2:3], v[2:3], 0, s[86:87]
	s_mov_b32 m0, s36
	s_addc_u32 s11, s17, 0
	global_load_lds_dwordx4 v[2:3], off
	s_add_i32 m0, s7, 0x1c000
	s_nop 0
	global_load_lds_dwordx4 v132, s[10:11]
	v_lshl_add_u64 v[2:3], s[10:11], 0, v[136:137]
	s_add_i32 m0, s7, 0x1e000
	s_sext_i32_i8 s46, s0
	global_load_lds_dwordx4 v[2:3], off
	v_lshrrev_b32_e32 v3, 1, v10
	v_and_b32_e32 v3, 24, v3
	v_and_b32_e32 v2, 15, v10
	v_lshlrev_b32_e32 v4, 1, v3
	v_lshl_or_b32 v1, s8, 6, v2
	v_lshl_or_b32 v2, v2, 6, v4
	v_lshlrev_b32_e32 v4, 2, v10
	v_and_b32_e32 v4, 32, v4
	v_bitop3_b32 v5, v2, s9, v4 bitop3:0xde
	v_bitop3_b32 v142, v2, s12, v4 bitop3:0xde
	v_lshlrev_b32_e32 v2, 15, v14
	v_and_b32_e32 v2, 0xffff0000, v2
	v_or_b32_e32 v143, s1, v3
	v_lshl_add_u32 v2, v15, 12, v2
	v_and_b32_e32 v3, 1, v14
	v_lshl_or_b32 v2, v3, 6, v2
	v_lshl_add_u32 v138, v16, 1, v2
	v_lshlrev_b32_e32 v2, 15, v11
	v_and_b32_e32 v2, 0xffff0000, v2
	s_waitcnt vmcnt(6)
	v_lshl_add_u32 v2, v12, 12, v2
	v_and_b32_e32 v3, 1, v11
	v_lshl_or_b32 v2, v3, 6, v2
	s_ashr_i32 s37, s23, 31
	v_mov_b32_e32 v139, v0
	v_lshl_add_u32 v140, v13, 1, v2
	v_mov_b32_e32 v141, v0
	s_mov_b32 s41, 0
	v_add_u32_e32 v144, 0, v5
	s_barrier

; #define PG8_STAGE(bufoff, gbase, voff) do { _Pragma("unroll") for (int _i = 0; _i < 2; ++_i) \
;         __builtin_amdgcn_global_load_lds((const unsigned*)((const char*)(gbase) + (voff)[_i]), (LAS unsigned*)(lds + (bufoff) + ldsw + _i * 8192), 16, 0, 0); } while (0)
; #define PG8_LDA(dst, b, h) do { _Pragma("unroll") for (int m = 0; m < 4; ++m) _Pragma("unroll") for (int k = 0; k < 2; ++k) dst[m][k] = *(const LAS bf16x8*)(lds + PG8_SA(b, h) + aoff + m * 2048 + k * 1024); } while (0)
; #define PG8_LDB(dst, b, h) do { _Pragma("unroll") for (int n = 0; n < 2; ++n) _Pragma("unroll") for (int k = 0; k < 2; ++k) dst[n][k] = *(const LAS bf16x8*)(lds + PG8_SB(b, h) + boff + n * 2048 + k * 1024); } while (0)
; #define PG8_MMA(ai, bj, At, Bt) do { __builtin_amdgcn_s_setprio(1); _Pragma("unroll") for (int m = 0; m < 4; ++m) _Pragma("unroll") for (int n = 0; n < 2; ++n) _Pragma("unroll") for (int k = 0; k < 2; ++k) \
;         acc[ai][bj][m][n] = __builtin_amdgcn_mfma_f32_16x16x32_bf16(Bt[n][k], At[m][k], acc[ai][bj][m][n], 0, 0, 0); __builtin_amdgcn_s_setprio(0); } while (0)
; #define PG8_WAIT_L(n) asm volatile("s_waitcnt lgkmcnt(" #n ")" ::: "memory")
; #define PG8_BAR __builtin_amdgcn_s_barrier()
; #define PG8_SCHED __builtin_amdgcn_sched_barrier(0)
; template <class Epi, class Sched, bool AREMAP>
; __device__ __forceinline__ void gemm_phase(LAS unsigned char* lds, const Gemm g, const Sched& S, const Epi& E, int wv) {
;     ...
;             PG8_LDB(B0, 0, 0); PG8_SCHED; PG8_LDA(At, 0, 0); PG8_STAGE(PG8_SA(1, 1), a1 + hstepA, voffA);
;             PG8_WAIT_L(8); PG8_BAR; PG8_WAIT_L(0); PG8_MMA(0, 0, At, B0); PG8_BAR; PG8_SCHED;
;             PG8_LDB(B1, 0, 1); PG8_STAGE(PG8_SB(0, 0), b2, voffB);
;             PG8_BAR; PG8_WAIT_L(0); PG8_MMA(0, 1, At, B1); PG8_BAR;
;             PG8_LDA(At, 0, 1); PG8_STAGE(PG8_SA(0, 0), a2, voffA);
;             PG8_BAR; PG8_WAIT_L(0); PG8_MMA(1, 0, At, B0); PG8_BAR; PG8_SCHED;
.LBB0_202:
	s_add_u32 s18, s16, 0xfff80080
	s_addc_u32 s19, s17, -1
	s_add_i32 s38, 0, 0x10000
	v_add_u32_e32 v145, s38, v142
	ds_read_b128 v[146:149], v145
	ds_read_b128 v[150:153], v145 offset:1024
	ds_read_b128 v[154:157], v145 offset:2048
	ds_read_b128 v[158:161], v145 offset:3072
	s_cmp_eq_u32 s56, 28
	s_cselect_b32 s21, s11, s19
	s_cselect_b32 s20, s47, s18
	s_cselect_b32 s19, s9, s55
	s_cselect_b32 s18, s52, s53
	s_add_i32 m0, s7, 0xc000
	ds_read_b128 v[162:165], v144
	ds_read_b128 v[166:169], v144 offset:1024
	ds_read_b128 v[170:173], v144 offset:2048
	ds_read_b128 v[174:177], v144 offset:3072
	ds_read_b128 v[178:181], v144 offset:4096
	ds_read_b128 v[182:185], v144 offset:5120
	ds_read_b128 v[196:199], v144 offset:6144
	ds_read_b128 v[200:203], v144 offset:7168
	global_load_lds_dwordx4 v140, s[16:17]
	s_add_i32 m0, s7, 0xe000
	s_nop 0
	global_load_lds_dwordx4 v138, s[16:17]
	s_waitcnt lgkmcnt(8)
	s_barrier
	s_waitcnt lgkmcnt(0)
	s_waitcnt lgkmcnt(0)
	v_mfma_f32_16x16x32_bf16 v[126:129], v[146:149], v[162:165], v[126:129]
	v_mfma_f32_16x16x32_bf16 v[122:125], v[154:157], v[162:165], v[122:125]
	v_mfma_f32_16x16x32_bf16 v[118:121], v[146:149], v[170:173], v[118:121]
	v_mfma_f32_16x16x32_bf16 v[114:117], v[154:157], v[170:173], v[114:117]
	v_mfma_f32_16x16x32_bf16 v[102:105], v[146:149], v[178:181], v[102:105]
	v_mfma_f32_16x16x32_bf16 v[98:101], v[154:157], v[178:181], v[98:101]
	v_mfma_f32_16x16x32_bf16 v[86:89], v[146:149], v[196:199], v[86:89]
	v_mfma_f32_16x16x32_bf16 v[82:85], v[154:157], v[196:199], v[82:85]
	v_mfma_f32_16x16x32_bf16 v[126:129], v[150:153], v[166:169], v[126:129]
	v_mfma_f32_16x16x32_bf16 v[122:125], v[158:161], v[166:169], v[122:125]
	v_mfma_f32_16x16x32_bf16 v[118:121], v[150:153], v[174:177], v[118:121]
	v_mfma_f32_16x16x32_bf16 v[114:117], v[158:161], v[174:177], v[114:117]
	v_mfma_f32_16x16x32_bf16 v[102:105], v[150:153], v[182:185], v[102:105]
	v_mfma_f32_16x16x32_bf16 v[98:101], v[158:161], v[182:185], v[98:101]
	v_mfma_f32_16x16x32_bf16 v[86:89], v[150:153], v[200:203], v[86:89]
	v_mfma_f32_16x16x32_bf16 v[82:85], v[158:161], v[200:203], v[82:85]
	s_barrier
	s_add_i32 s39, 0, 0x14000
	s_add_i32 s38, s38, s29
	v_add_u32_e32 v145, s39, v142
	v_lshl_add_u64 v[186:187], s[18:19], 0, v[132:133]
	s_mov_b32 m0, s38
	ds_read_b128 v[204:207], v145
	ds_read_b128 v[208:211], v145 offset:1024
	ds_read_b128 v[212:215], v145 offset:2048
	ds_read_b128 v[216:219], v145 offset:3072
	global_load_lds_dwordx4 v[186:187], off
	v_lshl_add_u64 v[192:193], s[18:19], 0, v[136:137]
	s_add_i32 m0, s38, 0x2000
	s_nop 0
	global_load_lds_dwordx4 v[192:193], off
	s_barrier
	s_waitcnt lgkmcnt(0)
	s_waitcnt lgkmcnt(0)
	v_mfma_f32_16x16x32_bf16 v[110:113], v[204:207], v[162:165], v[110:113]
	v_mfma_f32_16x16x32_bf16 v[106:109], v[212:215], v[162:165], v[106:109]
	v_mfma_f32_16x16x32_bf16 v[94:97], v[204:207], v[170:173], v[94:97]
	v_mfma_f32_16x16x32_bf16 v[90:93], v[212:215], v[170:173], v[90:93]
	v_mfma_f32_16x16x32_bf16 v[78:81], v[204:207], v[178:181], v[78:81]
	v_mfma_f32_16x16x32_bf16 v[74:77], v[212:215], v[178:181], v[74:77]
	v_mfma_f32_16x16x32_bf16 v[70:73], v[204:207], v[196:199], v[70:73]
	v_mfma_f32_16x16x32_bf16 v[66:69], v[212:215], v[196:199], v[66:69]
	v_mfma_f32_16x16x32_bf16 v[110:113], v[208:211], v[166:169], v[110:113]
	v_mfma_f32_16x16x32_bf16 v[106:109], v[216:219], v[166:169], v[106:109]
	v_mfma_f32_16x16x32_bf16 v[94:97], v[208:211], v[174:177], v[94:97]
	v_mfma_f32_16x16x32_bf16 v[90:93], v[216:219], v[174:177], v[90:93]
	v_mfma_f32_16x16x32_bf16 v[78:81], v[208:211], v[182:185], v[78:81]
	v_mfma_f32_16x16x32_bf16 v[74:77], v[216:219], v[182:185], v[74:77]
	v_mfma_f32_16x16x32_bf16 v[70:73], v[208:211], v[200:203], v[70:73]
	v_mfma_f32_16x16x32_bf16 v[66:69], v[216:219], v[200:203], v[66:69]
	s_mov_b32 m0, s7
	v_lshl_add_u64 v[194:195], s[20:21], 0, v[130:131]
	s_barrier
	ds_read_b128 v[162:165], v144 offset:16384
	ds_read_b128 v[166:169], v144 offset:17408
	ds_read_b128 v[170:173], v144 offset:18432
	ds_read_b128 v[174:177], v144 offset:19456
	ds_read_b128 v[178:181], v144 offset:20480
	ds_read_b128 v[182:185], v144 offset:21504
	ds_read_b128 v[196:199], v144 offset:22528
	ds_read_b128 v[200:203], v144 offset:23552
	global_load_lds_dwordx4 v[194:195], off
	v_lshl_add_u64 v[220:221], s[20:21], 0, v[134:135]
	s_mov_b32 m0, s30
	s_nop 0
	global_load_lds_dwordx4 v[220:221], off
	s_barrier
	s_waitcnt lgkmcnt(0)
	s_waitcnt lgkmcnt(0)
	v_mfma_f32_16x16x32_bf16 v[62:65], v[146:149], v[162:165], v[62:65]
	v_mfma_f32_16x16x32_bf16 v[58:61], v[154:157], v[162:165], v[58:61]
	v_mfma_f32_16x16x32_bf16 v[54:57], v[146:149], v[170:173], v[54:57]
	v_mfma_f32_16x16x32_bf16 v[50:53], v[154:157], v[170:173], v[50:53]
	v_mfma_f32_16x16x32_bf16 v[38:41], v[146:149], v[178:181], v[38:41]
	v_mfma_f32_16x16x32_bf16 v[34:37], v[154:157], v[178:181], v[34:37]
	v_mfma_f32_16x16x32_bf16 v[22:25], v[146:149], v[196:199], v[22:25]
	v_mfma_f32_16x16x32_bf16 v[18:21], v[154:157], v[196:199], v[18:21]
	v_mfma_f32_16x16x32_bf16 v[62:65], v[150:153], v[166:169], v[62:65]
	v_mfma_f32_16x16x32_bf16 v[58:61], v[158:161], v[166:169], v[58:61]
	v_mfma_f32_16x16x32_bf16 v[54:57], v[150:153], v[174:177], v[54:57]
	v_mfma_f32_16x16x32_bf16 v[50:53], v[158:161], v[174:177], v[50:53]
	v_mfma_f32_16x16x32_bf16 v[38:41], v[150:153], v[182:185], v[38:41]
	v_mfma_f32_16x16x32_bf16 v[34:37], v[158:161], v[182:185], v[34:37]
	v_mfma_f32_16x16x32_bf16 v[22:25], v[150:153], v[200:203], v[22:25]
	v_mfma_f32_16x16x32_bf16 v[18:21], v[158:161], v[200:203], v[18:21]
	s_barrier
; #define PG8_STAGE(bufoff, gbase, voff) do { _Pragma("unroll") for (int _i = 0; _i < 2; ++_i) \
;         __builtin_amdgcn_global_load_lds((const unsigned*)((const char*)(gbase) + (voff)[_i]), (LAS unsigned*)(lds + (bufoff) + ldsw + _i * 8192), 16, 0, 0); } while (0)
; #define PG8_LDA(dst, b, h) do { _Pragma("unroll") for (int m = 0; m < 4; ++m) _Pragma("unroll") for (int k = 0; k < 2; ++k) dst[m][k] = *(const LAS bf16x8*)(lds + PG8_SA(b, h) + aoff + m * 2048 + k * 1024); } while (0)
; #define PG8_LDB(dst, b, h) do { _Pragma("unroll") for (int n = 0; n < 2; ++n) _Pragma("unroll") for (int k = 0; k < 2; ++k) dst[n][k] = *(const LAS bf16x8*)(lds + PG8_SB(b, h) + boff + n * 2048 + k * 1024); } while (0)
; #define PG8_MMA(ai, bj, At, Bt) do { __builtin_amdgcn_s_setprio(1); _Pragma("unroll") for (int m = 0; m < 4; ++m) _Pragma("unroll") for (int n = 0; n < 2; ++n) _Pragma("unroll") for (int k = 0; k < 2; ++k) \
;         acc[ai][bj][m][n] = __builtin_amdgcn_mfma_f32_16x16x32_bf16(Bt[n][k], At[m][k], acc[ai][bj][m][n], 0, 0, 0); __builtin_amdgcn_s_setprio(0); } while (0)
; #define PG8_WAIT_V(n) asm volatile("s_waitcnt vmcnt(" #n ")" ::: "memory")
; #define PG8_WAIT_L(n) asm volatile("s_waitcnt lgkmcnt(" #n ")" ::: "memory")
; #define PG8_BAR __builtin_amdgcn_s_barrier()
; #define PG8_SCHED __builtin_amdgcn_sched_barrier(0)
; template <class Epi, class Sched, bool AREMAP>
; __device__ __forceinline__ void gemm_phase(LAS unsigned char* lds, const Gemm g, const Sched& S, const Epi& E, int wv) {
;     ...
;             PG8_STAGE(PG8_SB(0, 1), b2 + hstepB, voffB);
;             PG8_WAIT_V(6); PG8_BAR; PG8_MMA(1, 1, At, B1); PG8_BAR;
;             PG8_LDB(B0, 1, 0); PG8_SCHED; PG8_LDA(At, 1, 0); PG8_STAGE(PG8_SA(0, 1), a2 + hstepA, voffA);
;             PG8_WAIT_L(8); PG8_BAR; PG8_WAIT_L(0); PG8_MMA(0, 0, At, B0); PG8_BAR; PG8_SCHED;
;             PG8_LDB(B1, 1, 1); PG8_STAGE(PG8_SB(1, 0), b3, voffB);
;             PG8_BAR; PG8_WAIT_L(0); PG8_MMA(0, 1, At, B1); PG8_BAR;
;             PG8_LDA(At, 1, 1); PG8_STAGE(PG8_SA(1, 0), a3, voffA);
	s_add_u32 s62, s18, 0x80000
	s_addc_u32 s63, s19, 0
	s_add_i32 s38, s39, s29
	s_mov_b32 m0, s38
	s_nop 0
	global_load_lds_dwordx4 v132, s[62:63]
	s_add_i32 m0, s38, 0x2000
	s_nop 0
	global_load_lds_dwordx4 v136, s[62:63]
	s_waitcnt vmcnt(6)
	s_barrier
	v_mfma_f32_16x16x32_bf16 v[46:49], v[204:207], v[162:165], v[46:49]
	v_mfma_f32_16x16x32_bf16 v[42:45], v[212:215], v[162:165], v[42:45]
	v_mfma_f32_16x16x32_bf16 v[30:33], v[204:207], v[170:173], v[30:33]
	v_mfma_f32_16x16x32_bf16 v[26:29], v[212:215], v[170:173], v[26:29]
	v_mfma_f32_16x16x32_bf16 v[14:17], v[204:207], v[178:181], v[14:17]
	v_mfma_f32_16x16x32_bf16 v[10:13], v[212:215], v[178:181], v[10:13]
	v_mfma_f32_16x16x32_bf16 v[6:9], v[204:207], v[196:199], v[6:9]
	v_mfma_f32_16x16x32_bf16 v[2:5], v[212:215], v[196:199], v[2:5]
	v_mfma_f32_16x16x32_bf16 v[46:49], v[208:211], v[166:169], v[46:49]
	v_mfma_f32_16x16x32_bf16 v[42:45], v[216:219], v[166:169], v[42:45]
	v_mfma_f32_16x16x32_bf16 v[30:33], v[208:211], v[174:177], v[30:33]
	v_mfma_f32_16x16x32_bf16 v[26:29], v[216:219], v[174:177], v[26:29]
	v_mfma_f32_16x16x32_bf16 v[14:17], v[208:211], v[182:185], v[14:17]
	v_mfma_f32_16x16x32_bf16 v[10:13], v[216:219], v[182:185], v[10:13]
	v_mfma_f32_16x16x32_bf16 v[6:9], v[208:211], v[200:203], v[6:9]
	v_mfma_f32_16x16x32_bf16 v[2:5], v[216:219], v[200:203], v[2:5]
	s_add_i32 s38, 0, 0x18000
	v_add_u32_e32 v145, s38, v142
	s_barrier
	ds_read_b128 v[146:149], v145
	ds_read_b128 v[150:153], v145 offset:1024
	ds_read_b128 v[154:157], v145 offset:2048
	ds_read_b128 v[158:161], v145 offset:3072
	s_add_u32 s20, s20, 0x80000
	s_addc_u32 s21, s21, 0
	s_mov_b32 m0, s31
	ds_read_b128 v[162:165], v144 offset:32768
	ds_read_b128 v[166:169], v144 offset:33792
	ds_read_b128 v[170:173], v144 offset:34816
	ds_read_b128 v[174:177], v144 offset:35840
	ds_read_b128 v[178:181], v144 offset:36864
	ds_read_b128 v[182:185], v144 offset:37888
	ds_read_b128 v[196:199], v144 offset:38912
	ds_read_b128 v[200:203], v144 offset:39936
	global_load_lds_dwordx4 v130, s[20:21]
	s_mov_b32 m0, s34
	s_nop 0
	global_load_lds_dwordx4 v134, s[20:21]
	s_waitcnt lgkmcnt(8)
	s_barrier
	s_waitcnt lgkmcnt(0)
	s_waitcnt lgkmcnt(0)
	v_mfma_f32_16x16x32_bf16 v[126:129], v[146:149], v[162:165], v[126:129]
	v_mfma_f32_16x16x32_bf16 v[122:125], v[154:157], v[162:165], v[122:125]
	v_mfma_f32_16x16x32_bf16 v[118:121], v[146:149], v[170:173], v[118:121]
	v_mfma_f32_16x16x32_bf16 v[114:117], v[154:157], v[170:173], v[114:117]
	v_mfma_f32_16x16x32_bf16 v[102:105], v[146:149], v[178:181], v[102:105]
	v_mfma_f32_16x16x32_bf16 v[98:101], v[154:157], v[178:181], v[98:101]
	v_mfma_f32_16x16x32_bf16 v[86:89], v[146:149], v[196:199], v[86:89]
	v_mfma_f32_16x16x32_bf16 v[82:85], v[154:157], v[196:199], v[82:85]
	v_mfma_f32_16x16x32_bf16 v[126:129], v[150:153], v[166:169], v[126:129]
	v_mfma_f32_16x16x32_bf16 v[122:125], v[158:161], v[166:169], v[122:125]
	v_mfma_f32_16x16x32_bf16 v[118:121], v[150:153], v[174:177], v[118:121]
	v_mfma_f32_16x16x32_bf16 v[114:117], v[158:161], v[174:177], v[114:117]
	v_mfma_f32_16x16x32_bf16 v[102:105], v[150:153], v[182:185], v[102:105]
	v_mfma_f32_16x16x32_bf16 v[98:101], v[158:161], v[182:185], v[98:101]
	v_mfma_f32_16x16x32_bf16 v[86:89], v[150:153], v[200:203], v[86:89]
	v_mfma_f32_16x16x32_bf16 v[82:85], v[158:161], v[200:203], v[82:85]
	s_barrier
	s_add_i32 s20, 0, 0x1c000
	s_add_i32 s21, s38, s29
	v_add_u32_e32 v145, s20, v142
	v_lshl_add_u64 v[186:187], v[186:187], 0, s[86:87]
	s_mov_b32 m0, s21
	ds_read_b128 v[204:207], v145
	ds_read_b128 v[208:211], v145 offset:1024
	ds_read_b128 v[212:215], v145 offset:2048
	ds_read_b128 v[216:219], v145 offset:3072
	global_load_lds_dwordx4 v[186:187], off
	v_lshl_add_u64 v[186:187], v[192:193], 0, s[86:87]
	s_add_i32 m0, s21, 0x2000
	s_nop 0
	global_load_lds_dwordx4 v[186:187], off
	s_barrier
	s_waitcnt lgkmcnt(0)
	s_waitcnt lgkmcnt(0)
	v_mfma_f32_16x16x32_bf16 v[110:113], v[204:207], v[162:165], v[110:113]
	v_mfma_f32_16x16x32_bf16 v[106:109], v[212:215], v[162:165], v[106:109]
	v_mfma_f32_16x16x32_bf16 v[94:97], v[204:207], v[170:173], v[94:97]
	v_mfma_f32_16x16x32_bf16 v[90:93], v[212:215], v[170:173], v[90:93]
	v_mfma_f32_16x16x32_bf16 v[78:81], v[204:207], v[178:181], v[78:81]
	v_mfma_f32_16x16x32_bf16 v[74:77], v[212:215], v[178:181], v[74:77]
	v_mfma_f32_16x16x32_bf16 v[70:73], v[204:207], v[196:199], v[70:73]
	v_mfma_f32_16x16x32_bf16 v[66:69], v[212:215], v[196:199], v[66:69]
	v_mfma_f32_16x16x32_bf16 v[110:113], v[208:211], v[166:169], v[110:113]
	v_mfma_f32_16x16x32_bf16 v[106:109], v[216:219], v[166:169], v[106:109]
	v_mfma_f32_16x16x32_bf16 v[94:97], v[208:211], v[174:177], v[94:97]
	v_mfma_f32_16x16x32_bf16 v[90:93], v[216:219], v[174:177], v[90:93]
	v_mfma_f32_16x16x32_bf16 v[78:81], v[208:211], v[182:185], v[78:81]
	v_mfma_f32_16x16x32_bf16 v[74:77], v[216:219], v[182:185], v[74:77]
	v_mfma_f32_16x16x32_bf16 v[70:73], v[208:211], v[200:203], v[70:73]
	v_mfma_f32_16x16x32_bf16 v[66:69], v[216:219], v[200:203], v[66:69]
	s_mov_b32 m0, s35
	v_lshl_add_u64 v[186:187], v[194:195], 0, s[86:87]
	s_barrier
	ds_read_b128 v[162:165], v144 offset:49152
	ds_read_b128 v[166:169], v144 offset:50176
	ds_read_b128 v[170:173], v144 offset:51200
	ds_read_b128 v[174:177], v144 offset:52224
	ds_read_b128 v[178:181], v144 offset:53248
	ds_read_b128 v[182:185], v144 offset:54272
	ds_read_b128 v[196:199], v144 offset:55296
	ds_read_b128 v[200:203], v144 offset:56320
	global_load_lds_dwordx4 v[186:187], off
	v_lshl_add_u64 v[186:187], v[220:221], 0, s[86:87]
	s_mov_b32 m0, s36
	s_nop 0
	global_load_lds_dwordx4 v[186:187], off
	s_barrier
; #define PG8_STAGE(bufoff, gbase, voff) do { _Pragma("unroll") for (int _i = 0; _i < 2; ++_i) \
;         __builtin_amdgcn_global_load_lds((const unsigned*)((const char*)(gbase) + (voff)[_i]), (LAS unsigned*)(lds + (bufoff) + ldsw + _i * 8192), 16, 0, 0); } while (0)
; #define PG8_MMA(ai, bj, At, Bt) do { __builtin_amdgcn_s_setprio(1); _Pragma("unroll") for (int m = 0; m < 4; ++m) _Pragma("unroll") for (int n = 0; n < 2; ++n) _Pragma("unroll") for (int k = 0; k < 2; ++k) \
;         acc[ai][bj][m][n] = __builtin_amdgcn_mfma_f32_16x16x32_bf16(Bt[n][k], At[m][k], acc[ai][bj][m][n], 0, 0, 0); __builtin_amdgcn_s_setprio(0); } while (0)
; #define PG8_WAIT_V(n) asm volatile("s_waitcnt vmcnt(" #n ")" ::: "memory")
; #define PG8_WAIT_L(n) asm volatile("s_waitcnt lgkmcnt(" #n ")" ::: "memory")
; #define PG8_BAR __builtin_amdgcn_s_barrier()
; #define PG8_SCHED __builtin_amdgcn_sched_barrier(0)
; template <class Epi, class Sched, bool AREMAP>
; __device__ __forceinline__ void gemm_phase(LAS unsigned char* lds, const Gemm g, const Sched& S, const Epi& E, int wv) {
;     ...
;             PG8_BAR; PG8_WAIT_L(0); PG8_MMA(1, 0, At, B0); PG8_BAR; PG8_SCHED;
;             PG8_STAGE(PG8_SB(1, 1), b3 + hstepB, voffB);
;             PG8_WAIT_V(6); PG8_BAR; PG8_MMA(1, 1, At, B1); PG8_BAR;
;         }
	s_waitcnt lgkmcnt(0)
	s_waitcnt lgkmcnt(0)
	v_mfma_f32_16x16x32_bf16 v[62:65], v[146:149], v[162:165], v[62:65]
	v_mfma_f32_16x16x32_bf16 v[58:61], v[154:157], v[162:165], v[58:61]
	v_mfma_f32_16x16x32_bf16 v[54:57], v[146:149], v[170:173], v[54:57]
	v_mfma_f32_16x16x32_bf16 v[50:53], v[154:157], v[170:173], v[50:53]
	v_mfma_f32_16x16x32_bf16 v[38:41], v[146:149], v[178:181], v[38:41]
	v_mfma_f32_16x16x32_bf16 v[34:37], v[154:157], v[178:181], v[34:37]
	v_mfma_f32_16x16x32_bf16 v[22:25], v[146:149], v[196:199], v[22:25]
	v_mfma_f32_16x16x32_bf16 v[18:21], v[154:157], v[196:199], v[18:21]
	v_mfma_f32_16x16x32_bf16 v[62:65], v[150:153], v[166:169], v[62:65]
	v_mfma_f32_16x16x32_bf16 v[58:61], v[158:161], v[166:169], v[58:61]
	v_mfma_f32_16x16x32_bf16 v[54:57], v[150:153], v[174:177], v[54:57]
	v_mfma_f32_16x16x32_bf16 v[50:53], v[158:161], v[174:177], v[50:53]
	v_mfma_f32_16x16x32_bf16 v[38:41], v[150:153], v[182:185], v[38:41]
	v_mfma_f32_16x16x32_bf16 v[34:37], v[158:161], v[182:185], v[34:37]
	v_mfma_f32_16x16x32_bf16 v[22:25], v[150:153], v[200:203], v[22:25]
	v_mfma_f32_16x16x32_bf16 v[18:21], v[158:161], v[200:203], v[18:21]
	s_barrier
	s_add_u32 s18, s18, 0x80080
	s_addc_u32 s19, s19, 0
	s_add_i32 s20, s20, s29
	s_mov_b32 m0, s20
	s_nop 0
	global_load_lds_dwordx4 v132, s[18:19]
	s_add_i32 m0, s20, 0x2000
	s_nop 0
	global_load_lds_dwordx4 v136, s[18:19]
	s_waitcnt vmcnt(6)
	s_barrier
	v_mfma_f32_16x16x32_bf16 v[46:49], v[204:207], v[162:165], v[46:49]
	v_mfma_f32_16x16x32_bf16 v[42:45], v[212:215], v[162:165], v[42:45]
	v_mfma_f32_16x16x32_bf16 v[30:33], v[204:207], v[170:173], v[30:33]
	v_mfma_f32_16x16x32_bf16 v[26:29], v[212:215], v[170:173], v[26:29]
	v_mfma_f32_16x16x32_bf16 v[14:17], v[204:207], v[178:181], v[14:17]
	v_mfma_f32_16x16x32_bf16 v[10:13], v[212:215], v[178:181], v[10:13]
	v_mfma_f32_16x16x32_bf16 v[6:9], v[204:207], v[196:199], v[6:9]
	v_mfma_f32_16x16x32_bf16 v[2:5], v[212:215], v[196:199], v[2:5]
	v_mfma_f32_16x16x32_bf16 v[46:49], v[208:211], v[166:169], v[46:49]
	v_mfma_f32_16x16x32_bf16 v[42:45], v[216:219], v[166:169], v[42:45]
	v_mfma_f32_16x16x32_bf16 v[30:33], v[208:211], v[174:177], v[30:33]
	v_mfma_f32_16x16x32_bf16 v[26:29], v[216:219], v[174:177], v[26:29]
	v_mfma_f32_16x16x32_bf16 v[14:17], v[208:211], v[182:185], v[14:17]
	v_mfma_f32_16x16x32_bf16 v[10:13], v[216:219], v[182:185], v[10:13]
	v_mfma_f32_16x16x32_bf16 v[6:9], v[208:211], v[200:203], v[6:9]
	v_mfma_f32_16x16x32_bf16 v[2:5], v[216:219], v[200:203], v[2:5]
	s_add_i32 s56, s56, 2
	s_add_u32 s53, s53, 0x100
	s_addc_u32 s55, s55, 0
	s_add_u32 s16, s16, 0x100
	s_addc_u32 s17, s17, 0
	s_cmp_gt_u32 s56, 29
	s_barrier
	s_cbranch_scc0 .LBB0_202
; __device__ __forceinline__ unsigned cvt_pk_bf16(float lo, float hi) { f32x2_t f = {lo, hi}; bf16x2_t v = __builtin_convertvector(f, bf16x2_t); return __builtin_bit_cast(unsigned, v); }
; #define PG8_WAIT_V(n) asm volatile("s_waitcnt vmcnt(" #n ")" ::: "memory")
; #define PG8_BAR __builtin_amdgcn_s_barrier()
; template <class Epi, class Sched, bool AREMAP>
; __device__ __forceinline__ void gemm_phase(LAS unsigned char* lds, const Gemm g, const Sched& S, const Epi& E, int wv) {
;     ...
;         if (!has_next) break;
; #pragma unroll
;         for (int a = 0; a < 2; ++a)
; #pragma unroll
;             for (int b = 0; b < 2; ++b)
; #pragma unroll
;                 for (int m = 0; m < 4; ++m)
; #pragma unroll
;                     for (int n = 0; n < 2; ++n) acc[a][b][m][n] = (f32x4){0.f, 0.f, 0.f, 0.f};
;         cur = nxt; cA = nA; cB = nB; ++ui;
;     }
;     PG8_WAIT_V(0);
;     if (wr == 0) PG8_BAR;
;     PG8_BAR;
;     __device__ __forceinline__ void operator()(const f32x4 (&acc)[2][2][4][2], const Unit& u, int wr, int wc, int fr, int fq) const {
;         const int row0 = u.pm * BM + wr * 64 + fr; int colt = u.pn * BM; bf16_t* base = O;
;         if (split_cols) { const int t = colt / split_cols; base += (size_t)t * split_stride; colt -= t * split_cols; }
;         const int col0 = colt + wc * 32 + 8 * fq;
; #pragma unroll
;         for (int ai = 0; ai < 2; ++ai)
; #pragma unroll
;             for (int m = 0; m < 4; ++m) { bf16_t* rowp = base + (size_t)(row0 + ai * HALF + m * 16) * ldc + col0;
; #pragma unroll
;                 for (int bj = 0; bj < 2; ++bj) { const f32x4 v0 = acc[ai][bj][m][0], v1 = acc[ai][bj][m][1];
;                     u32x4 w; w.x = cvt_pk_bf16(v0[0], v0[1]); w.y = cvt_pk_bf16(v0[2], v0[3]); w.z = cvt_pk_bf16(v1[0], v1[1]); w.w = cvt_pk_bf16(v1[2], v1[3]);
;                     *(u32x4*)(rowp + bj * HALF) = w; } }
	v_lshl_add_u32 v146, s6, 8, v1
	v_lshl_or_b32 v148, s46, 8, v143
	v_ashrrev_i32_e32 v149, 31, v148
	v_ashrrev_i32_e32 v147, 31, v146
	v_lshl_add_u64 v[148:149], v[148:149], 1, s[4:5]
	v_lshlrev_b64 v[150:151], 14, v[146:147]
	v_lshl_add_u64 v[150:151], v[148:149], 0, v[150:151]
	s_mov_b32 s6, 0x200000
	s_mov_b64 s[16:17], 0x200000
	v_cvt_pk_bf16_f32 v62, v62, v63
	v_cvt_pk_bf16_f32 v63, v64, v65
	v_cvt_pk_bf16_f32 v64, v58, v59
	v_add_co_u32_e32 v58, vcc, s6, v150
	v_cvt_pk_bf16_f32 v70, v70, v71
	v_cvt_pk_bf16_f32 v71, v72, v73
	v_cvt_pk_bf16_f32 v72, v66, v67
	v_lshl_add_u64 v[66:67], v[150:151], 0, s[16:17]
	v_addc_co_u32_e32 v59, vcc, 0, v151, vcc
	v_cvt_pk_bf16_f32 v46, v46, v47
	v_cvt_pk_bf16_f32 v47, v48, v49
	v_cvt_pk_bf16_f32 v48, v42, v43
	v_cvt_pk_bf16_f32 v49, v44, v45
	s_mov_b32 s6, 0x240000
	global_store_dwordx4 v[66:67], v[46:49], off offset:256
	s_mov_b64 s[16:17], 0x240000
	v_cvt_pk_bf16_f32 v110, v110, v111
	v_add_co_u32_e32 v48, vcc, s6, v150
	v_cvt_pk_bf16_f32 v111, v112, v113
	v_cvt_pk_bf16_f32 v112, v106, v107
	v_or_b32_e32 v106, 16, v146
	v_lshl_add_u64 v[46:47], v[150:151], 0, s[16:17]
	v_addc_co_u32_e32 v49, vcc, 0, v151, vcc
	v_cvt_pk_bf16_f32 v30, v30, v31
	v_cvt_pk_bf16_f32 v31, v32, v33
	v_cvt_pk_bf16_f32 v32, v26, v27
	v_cvt_pk_bf16_f32 v33, v28, v29
	s_mov_b32 s6, 0x280000
	v_ashrrev_i32_e32 v107, 31, v106
	v_cvt_pk_bf16_f32 v94, v94, v95
	v_cvt_pk_bf16_f32 v95, v96, v97
	v_cvt_pk_bf16_f32 v96, v90, v91
	v_or_b32_e32 v90, 32, v146
	global_store_dwordx4 v[46:47], v[30:33], off offset:256
	s_mov_b64 s[16:17], 0x280000
	v_cvt_pk_bf16_f32 v113, v108, v109
	v_add_co_u32_e32 v32, vcc, s6, v150
	v_lshlrev_b64 v[106:107], 14, v[106:107]
	v_ashrrev_i32_e32 v91, 31, v90
	v_cvt_pk_bf16_f32 v78, v78, v79
	v_cvt_pk_bf16_f32 v79, v80, v81
	v_cvt_pk_bf16_f32 v80, v74, v75
	v_or_b32_e32 v74, 48, v146
	v_lshl_add_u64 v[30:31], v[150:151], 0, s[16:17]
	v_addc_co_u32_e32 v33, vcc, 0, v151, vcc
	v_cvt_pk_bf16_f32 v14, v14, v15
	v_cvt_pk_bf16_f32 v15, v16, v17
	v_cvt_pk_bf16_f32 v16, v10, v11
	v_cvt_pk_bf16_f32 v17, v12, v13
	global_store_dwordx4 v[150:151], v[110:113], off offset:256
	v_cvt_pk_bf16_f32 v97, v92, v93
	v_lshlrev_b64 v[90:91], 14, v[90:91]
	v_lshl_add_u64 v[110:111], v[148:149], 0, v[106:107]
	v_ashrrev_i32_e32 v75, 31, v74
	global_store_dwordx4 v[30:31], v[14:17], off offset:256
	global_store_dwordx4 v[110:111], v[94:97], off offset:256
	v_cvt_pk_bf16_f32 v81, v76, v77
	v_add_co_u32_e32 v16, vcc, s33, v150
	v_lshl_add_u64 v[94:95], v[148:149], 0, v[90:91]
	v_lshlrev_b64 v[74:75], 14, v[74:75]
	s_mov_b64 s[16:17], 0x2c0000
	v_addc_co_u32_e32 v17, vcc, 0, v151, vcc
	v_cvt_pk_bf16_f32 v126, v126, v127
	v_cvt_pk_bf16_f32 v127, v128, v129
	v_cvt_pk_bf16_f32 v128, v122, v123
	v_cvt_pk_bf16_f32 v129, v124, v125
	v_cvt_pk_bf16_f32 v106, v118, v119
	v_cvt_pk_bf16_f32 v107, v120, v121
	v_cvt_pk_bf16_f32 v108, v114, v115
	v_cvt_pk_bf16_f32 v109, v116, v117
	v_cvt_pk_bf16_f32 v90, v102, v103
	v_cvt_pk_bf16_f32 v91, v104, v105
	v_cvt_pk_bf16_f32 v92, v98, v99
	v_cvt_pk_bf16_f32 v93, v100, v101
	global_store_dwordx4 v[94:95], v[78:81], off offset:256
	v_cvt_pk_bf16_f32 v76, v82, v83
	v_cvt_pk_bf16_f32 v77, v84, v85
	v_lshl_add_u64 v[78:79], v[148:149], 0, v[74:75]
	v_cvt_pk_bf16_f32 v74, v86, v87
	v_cvt_pk_bf16_f32 v75, v88, v89
	v_cvt_pk_bf16_f32 v73, v68, v69
	v_cvt_pk_bf16_f32 v65, v60, v61
	v_cvt_pk_bf16_f32 v42, v54, v55
	v_cvt_pk_bf16_f32 v43, v56, v57
	v_cvt_pk_bf16_f32 v44, v50, v51
	v_cvt_pk_bf16_f32 v45, v52, v53
	v_cvt_pk_bf16_f32 v26, v38, v39
	v_cvt_pk_bf16_f32 v27, v40, v41
	v_cvt_pk_bf16_f32 v28, v34, v35
	v_cvt_pk_bf16_f32 v29, v36, v37
	v_lshl_add_u64 v[14:15], v[150:151], 0, s[16:17]
	v_cvt_pk_bf16_f32 v10, v22, v23
	v_cvt_pk_bf16_f32 v11, v24, v25
	v_cvt_pk_bf16_f32 v12, v18, v19
	v_cvt_pk_bf16_f32 v13, v20, v21
	v_cvt_pk_bf16_f32 v6, v6, v7
	v_cvt_pk_bf16_f32 v7, v8, v9
	v_cvt_pk_bf16_f32 v8, v2, v3
	v_cvt_pk_bf16_f32 v9, v4, v5
	s_and_b64 vcc, exec, s[0:1]
	s_mov_b32 s46, s8
	s_mov_b32 s6, s10
	s_mov_b64 s[16:17], s[14:15]
	s_mov_b64 s[18:19], s[12:13]
	s_mov_b32 s39, 0xb2a5705f
	s_mov_b32 s38, 0x42ce8ed0
	s_mov_b64 s[52:53], 0x41000
	global_store_dwordx4 v[150:151], v[126:129], off
	global_store_dwordx4 v[110:111], v[106:109], off
	global_store_dwordx4 v[94:95], v[90:93], off
	global_store_dwordx4 v[78:79], v[74:77], off
	global_store_dwordx4 v[78:79], v[70:73], off offset:256
	global_store_dwordx4 v[58:59], v[62:65], off
	global_store_dwordx4 v[48:49], v[42:45], off
	global_store_dwordx4 v[32:33], v[26:29], off
	global_store_dwordx4 v[16:17], v[10:13], off
	global_store_dwordx4 v[14:15], v[6:9], off offset:256
	s_cbranch_vccz .LBB0_195
	s_waitcnt vmcnt(0)
	s_cmpk_gt_u32 s25, 0xff
	s_cbranch_scc1 .LBB0_206
	s_barrier

; __device__ __forceinline__ int otid(int wv) { int t = (wv << 6) | (int)__builtin_amdgcn_mbcnt_hi(~0u, __builtin_amdgcn_mbcnt_lo(~0u, 0u)); asm volatile("" : "+v"(t)); return t; }
; #define PG8_STAGE(bufoff, gbase, voff) do { _Pragma("unroll") for (int _i = 0; _i < 2; ++_i) \
;         __builtin_amdgcn_global_load_lds((const unsigned*)((const char*)(gbase) + (voff)[_i]), (LAS unsigned*)(lds + (bufoff) + ldsw + _i * 8192), 16, 0, 0); } while (0)
; #define PG8_WAIT_V(n) asm volatile("s_waitcnt vmcnt(" #n ")" ::: "memory")
; #define PG8_BAR __builtin_amdgcn_s_barrier()
; template <class Epi, class Sched, bool AREMAP>
; __device__ __forceinline__ void gemm_phase(LAS unsigned char* lds, const Gemm g, const Sched& S, const Epi& E, int wv) {
;     const int tid = otid(wv), wid = __builtin_amdgcn_readfirstlane(tid >> 6), lane = tid & 63, wr = wid >> 2, wc = wid & 3, fr = lane & 15, fq = lane >> 4;
;     const int K = g.K, nt = K / BK;
;     unsigned voffA[2], voffB[2];
; #pragma unroll
;     for (int i = 0; i < 2; ++i) { int R, C; stage_rc(tid * 16 + i * 8192, R, C); const int Rb = Epi::PERM ? ((R & ~31) + perm32(R & 31)) : R;
;         const int Ra = AREMAP ? ((R >> 6) * 128 + (R & 63)) : R;
;         voffA[i] = (unsigned)(Ra * g.lda + C) * 2u; voffB[i] = (unsigned)(Rb * g.ldb + C) * 2u; }
;     const size_t kstep = (size_t)(BK * 2);
;     const size_t hstepA = (size_t)(AREMAP ? 64 : HALF) * g.lda * 2, hstepB = (size_t)HALF * g.ldb * 2;
;     const size_t tstepA = (size_t)BM * g.lda * 2, tstepB = (size_t)BM * g.ldb * 2;
;     const unsigned ldsw = (unsigned)wid * 1024u;
;     const int aoff = lds_byte(wr * 64 + fr, fq * 8), boff = lds_byte(wc * 32 + fr, fq * 8);
;     ...
;     PG8_STAGE(PG8_SB(0, 0), cB, voffB); PG8_STAGE(PG8_SA(0, 0), cA, voffA); PG8_STAGE(PG8_SB(0, 1), cB + hstepB, voffB); PG8_STAGE(PG8_SA(0, 1), cA + hstepA, voffA);
;     if (wr == 1) PG8_BAR;
;     PG8_WAIT_V(4); PG8_BAR;
;     PG8_STAGE(PG8_SB(1, 0), cB + kstep, voffB); PG8_STAGE(PG8_SA(1, 0), cA + kstep, voffA); PG8_STAGE(PG8_SB(1, 1), cB + hstepB + kstep, voffB);
;     PG8_WAIT_V(6); PG8_BAR;
.LBB0_391:
	v_lshrrev_b32_e32 v18, 1, v16
	v_and_b32_e32 v18, 24, v18
	s_add_u32 s31, s0, 0x10e00000
	v_and_b32_e32 v17, 15, v16
	v_lshlrev_b32_e32 v19, 1, v18
	v_lshlrev_b32_e32 v16, 2, v16
	s_addc_u32 s34, s1, 0
	v_lshl_or_b32 v1, s6, 6, v17
	v_lshl_or_b32 v17, v17, 6, v19
	s_lshl_b32 s0, s6, 13
	v_and_b32_e32 v16, 32, v16
	v_bitop3_b32 v19, v17, s0, v16 bitop3:0xde
	s_lshl_b32 s0, s3, 5
	s_sext_i32_i8 s46, s2
	s_and_b32 s2, s0, 0x60
	s_add_i32 m0, s5, 0x18000
	v_lshl_add_u64 v[8:9], v[8:9], 0, s[86:87]
	s_lshl_b32 s0, s2, 7
	s_waitcnt vmcnt(4)
	s_barrier
	global_load_lds_dwordx4 v[8:9], off
	v_lshl_add_u64 v[6:7], v[6:7], 0, s[86:87]
	s_add_i32 m0, s5, 0x1a000
	s_add_i32 s35, s5, 0x8000
	s_add_i32 s36, s5, 0xa000
	v_bitop3_b32 v142, v17, s0, v16 bitop3:0xde
	global_load_lds_dwordx4 v[6:7], off
	v_lshl_add_u64 v[4:5], v[4:5], 0, s[86:87]
	s_mov_b32 m0, s35
	s_add_u32 s0, s14, 0x40080
	global_load_lds_dwordx4 v[4:5], off
	v_lshl_add_u64 v[2:3], v[2:3], 0, s[86:87]
	s_mov_b32 m0, s36
	s_addc_u32 s1, s15, 0
	global_load_lds_dwordx4 v[2:3], off
	s_add_i32 m0, s5, 0x1c000
	s_nop 0
	global_load_lds_dwordx4 v134, s[0:1]
	s_add_i32 m0, s5, 0x1e000
	s_ashr_i32 s37, s18, 31
	global_load_lds_dwordx4 v130, s[0:1]
	v_lshlrev_b32_e32 v2, 14, v10
	v_and_b32_e32 v2, 0xffff8000, v2
	v_lshl_add_u32 v2, v11, 11, v2
	v_and_b32_e32 v3, 1, v10
	v_lshl_or_b32 v2, v3, 6, v2
	v_lshl_add_u32 v138, v12, 1, v2
	v_lshlrev_b32_e32 v2, 14, v14
	v_and_b32_e32 v2, 0xffff8000, v2
	s_waitcnt vmcnt(6)
	v_lshl_add_u32 v2, v13, 11, v2
	v_and_b32_e32 v3, 1, v14
	v_lshl_or_b32 v2, v3, 6, v2
	v_or_b32_e32 v143, s2, v18
	v_mov_b32_e32 v139, v0
	v_lshl_add_u32 v140, v15, 1, v2
	v_mov_b32_e32 v141, v0
	s_mov_b32 s41, 0
	v_add_u32_e32 v144, 0, v19
	s_barrier
	s_waitcnt vmcnt(0)

; #define PG8_STAGE(bufoff, gbase, voff) do { _Pragma("unroll") for (int _i = 0; _i < 2; ++_i) \
;         __builtin_amdgcn_global_load_lds((const unsigned*)((const char*)(gbase) + (voff)[_i]), (LAS unsigned*)(lds + (bufoff) + ldsw + _i * 8192), 16, 0, 0); } while (0)
; #define PG8_LDA(dst, b, h) do { _Pragma("unroll") for (int m = 0; m < 4; ++m) _Pragma("unroll") for (int k = 0; k < 2; ++k) dst[m][k] = *(const LAS bf16x8*)(lds + PG8_SA(b, h) + aoff + m * 2048 + k * 1024); } while (0)
; #define PG8_LDB(dst, b, h) do { _Pragma("unroll") for (int n = 0; n < 2; ++n) _Pragma("unroll") for (int k = 0; k < 2; ++k) dst[n][k] = *(const LAS bf16x8*)(lds + PG8_SB(b, h) + boff + n * 2048 + k * 1024); } while (0)
; #define PG8_MMA(ai, bj, At, Bt) do { __builtin_amdgcn_s_setprio(1); _Pragma("unroll") for (int m = 0; m < 4; ++m) _Pragma("unroll") for (int n = 0; n < 2; ++n) _Pragma("unroll") for (int k = 0; k < 2; ++k) \
;         acc[ai][bj][m][n] = __builtin_amdgcn_mfma_f32_16x16x32_bf16(Bt[n][k], At[m][k], acc[ai][bj][m][n], 0, 0, 0); __builtin_amdgcn_s_setprio(0); } while (0)
; #define PG8_WAIT_L(n) asm volatile("s_waitcnt lgkmcnt(" #n ")" ::: "memory")
; #define PG8_BAR __builtin_amdgcn_s_barrier()
; #define PG8_SCHED __builtin_amdgcn_sched_barrier(0)
; template <class Epi, class Sched, bool AREMAP>
; __device__ __forceinline__ void gemm_phase(LAS unsigned char* lds, const Gemm g, const Sched& S, const Epi& E, int wv) {
;     ...
;             PG8_LDB(B0, 0, 0); PG8_SCHED; PG8_LDA(At, 0, 0); PG8_STAGE(PG8_SA(1, 1), a1 + hstepA, voffA);
;             PG8_WAIT_L(8); PG8_BAR; PG8_WAIT_L(0); PG8_MMA(0, 0, At, B0); PG8_BAR; PG8_SCHED;
;             PG8_LDB(B1, 0, 1); PG8_STAGE(PG8_SB(0, 0), b2, voffB);
;             PG8_BAR; PG8_WAIT_L(0); PG8_MMA(0, 1, At, B1); PG8_BAR;
;             PG8_LDA(At, 0, 1); PG8_STAGE(PG8_SA(0, 0), a2, voffA);
;             PG8_BAR; PG8_WAIT_L(0); PG8_MMA(1, 0, At, B0); PG8_BAR; PG8_SCHED;
.LBB0_397:
	s_add_u32 s14, s2, 0xfffc0080
	s_addc_u32 s15, s3, -1
	s_add_i32 s38, 0, 0x10000
	v_add_u32_e32 v145, s38, v142
	ds_read_b128 v[146:149], v145
	ds_read_b128 v[150:153], v145 offset:1024
	ds_read_b128 v[154:157], v145 offset:2048
	ds_read_b128 v[158:161], v145 offset:3072
	s_cmp_eq_u32 s53, 12
	s_cselect_b32 s17, s11, s15
	s_cselect_b32 s16, s10, s14
	s_cselect_b32 s15, s7, s52
	s_cselect_b32 s14, s9, s47
	s_add_i32 m0, s5, 0xc000
	ds_read_b128 v[162:165], v144
	ds_read_b128 v[166:169], v144 offset:1024
	ds_read_b128 v[170:173], v144 offset:2048
	ds_read_b128 v[174:177], v144 offset:3072
	ds_read_b128 v[178:181], v144 offset:4096
	ds_read_b128 v[182:185], v144 offset:5120
	ds_read_b128 v[192:195], v144 offset:6144
	ds_read_b128 v[196:199], v144 offset:7168
	global_load_lds_dwordx4 v140, s[2:3]
	s_add_i32 m0, s5, 0xe000
	s_nop 0
	global_load_lds_dwordx4 v138, s[2:3]
	s_waitcnt lgkmcnt(8)
	s_barrier
	s_waitcnt lgkmcnt(0)
	s_waitcnt lgkmcnt(0)
	v_mfma_f32_16x16x32_bf16 v[126:129], v[146:149], v[162:165], v[126:129]
	v_mfma_f32_16x16x32_bf16 v[122:125], v[154:157], v[162:165], v[122:125]
	v_mfma_f32_16x16x32_bf16 v[118:121], v[146:149], v[170:173], v[118:121]
	v_mfma_f32_16x16x32_bf16 v[114:117], v[154:157], v[170:173], v[114:117]
	v_mfma_f32_16x16x32_bf16 v[102:105], v[146:149], v[178:181], v[102:105]
	v_mfma_f32_16x16x32_bf16 v[98:101], v[154:157], v[178:181], v[98:101]
	v_mfma_f32_16x16x32_bf16 v[86:89], v[146:149], v[192:195], v[86:89]
	v_mfma_f32_16x16x32_bf16 v[82:85], v[154:157], v[192:195], v[82:85]
	v_mfma_f32_16x16x32_bf16 v[126:129], v[150:153], v[166:169], v[126:129]
	v_mfma_f32_16x16x32_bf16 v[122:125], v[158:161], v[166:169], v[122:125]
	v_mfma_f32_16x16x32_bf16 v[118:121], v[150:153], v[174:177], v[118:121]
	v_mfma_f32_16x16x32_bf16 v[114:117], v[158:161], v[174:177], v[114:117]
	v_mfma_f32_16x16x32_bf16 v[102:105], v[150:153], v[182:185], v[102:105]
	v_mfma_f32_16x16x32_bf16 v[98:101], v[158:161], v[182:185], v[98:101]
	v_mfma_f32_16x16x32_bf16 v[86:89], v[150:153], v[196:199], v[86:89]
	v_mfma_f32_16x16x32_bf16 v[82:85], v[158:161], v[196:199], v[82:85]
	s_barrier
	s_add_i32 s39, 0, 0x14000
	s_add_i32 s38, s38, s26
	v_add_u32_e32 v145, s39, v142
	v_lshl_add_u64 v[186:187], s[14:15], 0, v[134:135]
	s_mov_b32 m0, s38
	ds_read_b128 v[200:203], v145
	ds_read_b128 v[204:207], v145 offset:1024
	ds_read_b128 v[208:211], v145 offset:2048
	ds_read_b128 v[212:215], v145 offset:3072
	global_load_lds_dwordx4 v[186:187], off
	v_lshl_add_u64 v[216:217], s[14:15], 0, v[130:131]
	s_add_i32 m0, s38, 0x2000
	s_nop 0
	global_load_lds_dwordx4 v[216:217], off
	s_barrier
	s_waitcnt lgkmcnt(0)
	s_waitcnt lgkmcnt(0)
	v_mfma_f32_16x16x32_bf16 v[110:113], v[200:203], v[162:165], v[110:113]
	v_mfma_f32_16x16x32_bf16 v[106:109], v[208:211], v[162:165], v[106:109]
	v_mfma_f32_16x16x32_bf16 v[94:97], v[200:203], v[170:173], v[94:97]
	v_mfma_f32_16x16x32_bf16 v[90:93], v[208:211], v[170:173], v[90:93]
	v_mfma_f32_16x16x32_bf16 v[78:81], v[200:203], v[178:181], v[78:81]
	v_mfma_f32_16x16x32_bf16 v[74:77], v[208:211], v[178:181], v[74:77]
	v_mfma_f32_16x16x32_bf16 v[70:73], v[200:203], v[192:195], v[70:73]
	v_mfma_f32_16x16x32_bf16 v[66:69], v[208:211], v[192:195], v[66:69]
	v_mfma_f32_16x16x32_bf16 v[110:113], v[204:207], v[166:169], v[110:113]
	v_mfma_f32_16x16x32_bf16 v[106:109], v[212:215], v[166:169], v[106:109]
	v_mfma_f32_16x16x32_bf16 v[94:97], v[204:207], v[174:177], v[94:97]
	v_mfma_f32_16x16x32_bf16 v[90:93], v[212:215], v[174:177], v[90:93]
	v_mfma_f32_16x16x32_bf16 v[78:81], v[204:207], v[182:185], v[78:81]
	v_mfma_f32_16x16x32_bf16 v[74:77], v[212:215], v[182:185], v[74:77]
	v_mfma_f32_16x16x32_bf16 v[70:73], v[204:207], v[196:199], v[70:73]
	v_mfma_f32_16x16x32_bf16 v[66:69], v[212:215], v[196:199], v[66:69]
	s_mov_b32 m0, s5
	v_lshl_add_u64 v[218:219], s[16:17], 0, v[136:137]
	s_barrier
	ds_read_b128 v[162:165], v144 offset:16384
	ds_read_b128 v[166:169], v144 offset:17408
	ds_read_b128 v[170:173], v144 offset:18432
	ds_read_b128 v[174:177], v144 offset:19456
	ds_read_b128 v[178:181], v144 offset:20480
	ds_read_b128 v[182:185], v144 offset:21504
	ds_read_b128 v[192:195], v144 offset:22528
	ds_read_b128 v[196:199], v144 offset:23552
	global_load_lds_dwordx4 v[218:219], off
	v_lshl_add_u64 v[220:221], s[16:17], 0, v[132:133]
	s_mov_b32 m0, s28
	s_nop 0
	global_load_lds_dwordx4 v[220:221], off
	s_barrier
	s_waitcnt lgkmcnt(0)
	s_waitcnt lgkmcnt(0)
	v_mfma_f32_16x16x32_bf16 v[62:65], v[146:149], v[162:165], v[62:65]
	v_mfma_f32_16x16x32_bf16 v[58:61], v[154:157], v[162:165], v[58:61]
	v_mfma_f32_16x16x32_bf16 v[54:57], v[146:149], v[170:173], v[54:57]
	v_mfma_f32_16x16x32_bf16 v[50:53], v[154:157], v[170:173], v[50:53]
	v_mfma_f32_16x16x32_bf16 v[38:41], v[146:149], v[178:181], v[38:41]
	v_mfma_f32_16x16x32_bf16 v[34:37], v[154:157], v[178:181], v[34:37]
	v_mfma_f32_16x16x32_bf16 v[22:25], v[146:149], v[192:195], v[22:25]
	v_mfma_f32_16x16x32_bf16 v[18:21], v[154:157], v[192:195], v[18:21]
	v_mfma_f32_16x16x32_bf16 v[62:65], v[150:153], v[166:169], v[62:65]
	v_mfma_f32_16x16x32_bf16 v[58:61], v[158:161], v[166:169], v[58:61]
	v_mfma_f32_16x16x32_bf16 v[54:57], v[150:153], v[174:177], v[54:57]
	v_mfma_f32_16x16x32_bf16 v[50:53], v[158:161], v[174:177], v[50:53]
	v_mfma_f32_16x16x32_bf16 v[38:41], v[150:153], v[182:185], v[38:41]
	v_mfma_f32_16x16x32_bf16 v[34:37], v[158:161], v[182:185], v[34:37]
	v_mfma_f32_16x16x32_bf16 v[22:25], v[150:153], v[196:199], v[22:25]
	v_mfma_f32_16x16x32_bf16 v[18:21], v[158:161], v[196:199], v[18:21]
	s_barrier
; #define PG8_STAGE(bufoff, gbase, voff) do { _Pragma("unroll") for (int _i = 0; _i < 2; ++_i) \
;         __builtin_amdgcn_global_load_lds((const unsigned*)((const char*)(gbase) + (voff)[_i]), (LAS unsigned*)(lds + (bufoff) + ldsw + _i * 8192), 16, 0, 0); } while (0)
; #define PG8_LDA(dst, b, h) do { _Pragma("unroll") for (int m = 0; m < 4; ++m) _Pragma("unroll") for (int k = 0; k < 2; ++k) dst[m][k] = *(const LAS bf16x8*)(lds + PG8_SA(b, h) + aoff + m * 2048 + k * 1024); } while (0)
; #define PG8_LDB(dst, b, h) do { _Pragma("unroll") for (int n = 0; n < 2; ++n) _Pragma("unroll") for (int k = 0; k < 2; ++k) dst[n][k] = *(const LAS bf16x8*)(lds + PG8_SB(b, h) + boff + n * 2048 + k * 1024); } while (0)
; #define PG8_MMA(ai, bj, At, Bt) do { __builtin_amdgcn_s_setprio(1); _Pragma("unroll") for (int m = 0; m < 4; ++m) _Pragma("unroll") for (int n = 0; n < 2; ++n) _Pragma("unroll") for (int k = 0; k < 2; ++k) \
;         acc[ai][bj][m][n] = __builtin_amdgcn_mfma_f32_16x16x32_bf16(Bt[n][k], At[m][k], acc[ai][bj][m][n], 0, 0, 0); __builtin_amdgcn_s_setprio(0); } while (0)
; #define PG8_WAIT_V(n) asm volatile("s_waitcnt vmcnt(" #n ")" ::: "memory")
; #define PG8_WAIT_L(n) asm volatile("s_waitcnt lgkmcnt(" #n ")" ::: "memory")
; #define PG8_BAR __builtin_amdgcn_s_barrier()
; #define PG8_SCHED __builtin_amdgcn_sched_barrier(0)
; template <class Epi, class Sched, bool AREMAP>
; __device__ __forceinline__ void gemm_phase(LAS unsigned char* lds, const Gemm g, const Sched& S, const Epi& E, int wv) {
;     ...
;             PG8_STAGE(PG8_SB(0, 1), b2 + hstepB, voffB);
;             PG8_WAIT_V(6); PG8_BAR; PG8_MMA(1, 1, At, B1); PG8_BAR;
;             PG8_LDB(B0, 1, 0); PG8_SCHED; PG8_LDA(At, 1, 0); PG8_STAGE(PG8_SA(0, 1), a2 + hstepA, voffA);
;             PG8_WAIT_L(8); PG8_BAR; PG8_WAIT_L(0); PG8_MMA(0, 0, At, B0); PG8_BAR; PG8_SCHED;
;             PG8_LDB(B1, 1, 1); PG8_STAGE(PG8_SB(1, 0), b3, voffB);
;             PG8_BAR; PG8_WAIT_L(0); PG8_MMA(0, 1, At, B1); PG8_BAR;
;             PG8_LDA(At, 1, 1); PG8_STAGE(PG8_SA(1, 0), a3, voffA);
	s_add_u32 s56, s14, 0x40000
	s_addc_u32 s57, s15, 0
	s_add_i32 s38, s39, s26
	s_mov_b32 m0, s38
	s_nop 0
	global_load_lds_dwordx4 v134, s[56:57]
	s_add_i32 m0, s38, 0x2000
	s_nop 0
	global_load_lds_dwordx4 v130, s[56:57]
	s_waitcnt vmcnt(6)
	s_barrier
	v_mfma_f32_16x16x32_bf16 v[46:49], v[200:203], v[162:165], v[46:49]
	v_mfma_f32_16x16x32_bf16 v[42:45], v[208:211], v[162:165], v[42:45]
	v_mfma_f32_16x16x32_bf16 v[30:33], v[200:203], v[170:173], v[30:33]
	v_mfma_f32_16x16x32_bf16 v[26:29], v[208:211], v[170:173], v[26:29]
	v_mfma_f32_16x16x32_bf16 v[14:17], v[200:203], v[178:181], v[14:17]
	v_mfma_f32_16x16x32_bf16 v[10:13], v[208:211], v[178:181], v[10:13]
	v_mfma_f32_16x16x32_bf16 v[6:9], v[200:203], v[192:195], v[6:9]
	v_mfma_f32_16x16x32_bf16 v[2:5], v[208:211], v[192:195], v[2:5]
	v_mfma_f32_16x16x32_bf16 v[46:49], v[204:207], v[166:169], v[46:49]
	v_mfma_f32_16x16x32_bf16 v[42:45], v[212:215], v[166:169], v[42:45]
	v_mfma_f32_16x16x32_bf16 v[30:33], v[204:207], v[174:177], v[30:33]
	v_mfma_f32_16x16x32_bf16 v[26:29], v[212:215], v[174:177], v[26:29]
	v_mfma_f32_16x16x32_bf16 v[14:17], v[204:207], v[182:185], v[14:17]
	v_mfma_f32_16x16x32_bf16 v[10:13], v[212:215], v[182:185], v[10:13]
	v_mfma_f32_16x16x32_bf16 v[6:9], v[204:207], v[196:199], v[6:9]
	v_mfma_f32_16x16x32_bf16 v[2:5], v[212:215], v[196:199], v[2:5]
	s_add_i32 s38, 0, 0x18000
	v_add_u32_e32 v145, s38, v142
	s_barrier
	ds_read_b128 v[146:149], v145
	ds_read_b128 v[150:153], v145 offset:1024
	ds_read_b128 v[154:157], v145 offset:2048
	ds_read_b128 v[158:161], v145 offset:3072
	s_add_u32 s16, s16, 0x40000
	s_addc_u32 s17, s17, 0
	s_mov_b32 m0, s29
	ds_read_b128 v[162:165], v144 offset:32768
	ds_read_b128 v[166:169], v144 offset:33792
	ds_read_b128 v[170:173], v144 offset:34816
	ds_read_b128 v[174:177], v144 offset:35840
	ds_read_b128 v[178:181], v144 offset:36864
	ds_read_b128 v[182:185], v144 offset:37888
	ds_read_b128 v[192:195], v144 offset:38912
	ds_read_b128 v[196:199], v144 offset:39936
	global_load_lds_dwordx4 v136, s[16:17]
	s_mov_b32 m0, s30
	s_nop 0
	global_load_lds_dwordx4 v132, s[16:17]
	s_waitcnt lgkmcnt(8)
	s_barrier
	s_waitcnt lgkmcnt(0)
	s_waitcnt lgkmcnt(0)
	v_mfma_f32_16x16x32_bf16 v[126:129], v[146:149], v[162:165], v[126:129]
	v_mfma_f32_16x16x32_bf16 v[122:125], v[154:157], v[162:165], v[122:125]
	v_mfma_f32_16x16x32_bf16 v[118:121], v[146:149], v[170:173], v[118:121]
	v_mfma_f32_16x16x32_bf16 v[114:117], v[154:157], v[170:173], v[114:117]
	v_mfma_f32_16x16x32_bf16 v[102:105], v[146:149], v[178:181], v[102:105]
	v_mfma_f32_16x16x32_bf16 v[98:101], v[154:157], v[178:181], v[98:101]
	v_mfma_f32_16x16x32_bf16 v[86:89], v[146:149], v[192:195], v[86:89]
	v_mfma_f32_16x16x32_bf16 v[82:85], v[154:157], v[192:195], v[82:85]
	v_mfma_f32_16x16x32_bf16 v[126:129], v[150:153], v[166:169], v[126:129]
	v_mfma_f32_16x16x32_bf16 v[122:125], v[158:161], v[166:169], v[122:125]
	v_mfma_f32_16x16x32_bf16 v[118:121], v[150:153], v[174:177], v[118:121]
	v_mfma_f32_16x16x32_bf16 v[114:117], v[158:161], v[174:177], v[114:117]
	v_mfma_f32_16x16x32_bf16 v[102:105], v[150:153], v[182:185], v[102:105]
	v_mfma_f32_16x16x32_bf16 v[98:101], v[158:161], v[182:185], v[98:101]
	v_mfma_f32_16x16x32_bf16 v[86:89], v[150:153], v[196:199], v[86:89]
	v_mfma_f32_16x16x32_bf16 v[82:85], v[158:161], v[196:199], v[82:85]
	s_barrier
	s_add_i32 s16, 0, 0x1c000
	s_add_i32 s17, s38, s26
	v_add_u32_e32 v145, s16, v142
	v_lshl_add_u64 v[186:187], v[186:187], 0, s[86:87]
	s_mov_b32 m0, s17
	ds_read_b128 v[200:203], v145
	ds_read_b128 v[204:207], v145 offset:1024
	ds_read_b128 v[208:211], v145 offset:2048
	ds_read_b128 v[212:215], v145 offset:3072
	global_load_lds_dwordx4 v[186:187], off
	v_lshl_add_u64 v[186:187], v[216:217], 0, s[86:87]
	s_add_i32 m0, s17, 0x2000
	s_nop 0
	global_load_lds_dwordx4 v[186:187], off
	s_barrier
	s_waitcnt lgkmcnt(0)
	s_waitcnt lgkmcnt(0)
	v_mfma_f32_16x16x32_bf16 v[110:113], v[200:203], v[162:165], v[110:113]
	v_mfma_f32_16x16x32_bf16 v[106:109], v[208:211], v[162:165], v[106:109]
	v_mfma_f32_16x16x32_bf16 v[94:97], v[200:203], v[170:173], v[94:97]
	v_mfma_f32_16x16x32_bf16 v[90:93], v[208:211], v[170:173], v[90:93]
	v_mfma_f32_16x16x32_bf16 v[78:81], v[200:203], v[178:181], v[78:81]
	v_mfma_f32_16x16x32_bf16 v[74:77], v[208:211], v[178:181], v[74:77]
	v_mfma_f32_16x16x32_bf16 v[70:73], v[200:203], v[192:195], v[70:73]
	v_mfma_f32_16x16x32_bf16 v[66:69], v[208:211], v[192:195], v[66:69]
	v_mfma_f32_16x16x32_bf16 v[110:113], v[204:207], v[166:169], v[110:113]
	v_mfma_f32_16x16x32_bf16 v[106:109], v[212:215], v[166:169], v[106:109]
	v_mfma_f32_16x16x32_bf16 v[94:97], v[204:207], v[174:177], v[94:97]
	v_mfma_f32_16x16x32_bf16 v[90:93], v[212:215], v[174:177], v[90:93]
	v_mfma_f32_16x16x32_bf16 v[78:81], v[204:207], v[182:185], v[78:81]
	v_mfma_f32_16x16x32_bf16 v[74:77], v[212:215], v[182:185], v[74:77]
	v_mfma_f32_16x16x32_bf16 v[70:73], v[204:207], v[196:199], v[70:73]
	v_mfma_f32_16x16x32_bf16 v[66:69], v[212:215], v[196:199], v[66:69]
	s_mov_b32 m0, s35
	v_lshl_add_u64 v[186:187], v[218:219], 0, s[86:87]
	s_barrier
	ds_read_b128 v[162:165], v144 offset:49152
	ds_read_b128 v[166:169], v144 offset:50176
	ds_read_b128 v[170:173], v144 offset:51200
	ds_read_b128 v[174:177], v144 offset:52224
	ds_read_b128 v[178:181], v144 offset:53248
	ds_read_b128 v[182:185], v144 offset:54272
	ds_read_b128 v[192:195], v144 offset:55296
	ds_read_b128 v[196:199], v144 offset:56320
	global_load_lds_dwordx4 v[186:187], off
	v_lshl_add_u64 v[186:187], v[220:221], 0, s[86:87]
	s_mov_b32 m0, s36
	s_nop 0
	global_load_lds_dwordx4 v[186:187], off
	s_barrier
; #define PG8_STAGE(bufoff, gbase, voff) do { _Pragma("unroll") for (int _i = 0; _i < 2; ++_i) \
;         __builtin_amdgcn_global_load_lds((const unsigned*)((const char*)(gbase) + (voff)[_i]), (LAS unsigned*)(lds + (bufoff) + ldsw + _i * 8192), 16, 0, 0); } while (0)
; #define PG8_MMA(ai, bj, At, Bt) do { __builtin_amdgcn_s_setprio(1); _Pragma("unroll") for (int m = 0; m < 4; ++m) _Pragma("unroll") for (int n = 0; n < 2; ++n) _Pragma("unroll") for (int k = 0; k < 2; ++k) \
;         acc[ai][bj][m][n] = __builtin_amdgcn_mfma_f32_16x16x32_bf16(Bt[n][k], At[m][k], acc[ai][bj][m][n], 0, 0, 0); __builtin_amdgcn_s_setprio(0); } while (0)
; #define PG8_WAIT_V(n) asm volatile("s_waitcnt vmcnt(" #n ")" ::: "memory")
; #define PG8_WAIT_L(n) asm volatile("s_waitcnt lgkmcnt(" #n ")" ::: "memory")
; #define PG8_BAR __builtin_amdgcn_s_barrier()
; #define PG8_SCHED __builtin_amdgcn_sched_barrier(0)
; template <class Epi, class Sched, bool AREMAP>
; __device__ __forceinline__ void gemm_phase(LAS unsigned char* lds, const Gemm g, const Sched& S, const Epi& E, int wv) {
;     ...
;             PG8_BAR; PG8_WAIT_L(0); PG8_MMA(1, 0, At, B0); PG8_BAR; PG8_SCHED;
;             PG8_STAGE(PG8_SB(1, 1), b3 + hstepB, voffB);
;             PG8_WAIT_V(6); PG8_BAR; PG8_MMA(1, 1, At, B1); PG8_BAR;
;         }
	s_waitcnt lgkmcnt(0)
	s_waitcnt lgkmcnt(0)
	v_mfma_f32_16x16x32_bf16 v[62:65], v[146:149], v[162:165], v[62:65]
	v_mfma_f32_16x16x32_bf16 v[58:61], v[154:157], v[162:165], v[58:61]
	v_mfma_f32_16x16x32_bf16 v[54:57], v[146:149], v[170:173], v[54:57]
	v_mfma_f32_16x16x32_bf16 v[50:53], v[154:157], v[170:173], v[50:53]
	v_mfma_f32_16x16x32_bf16 v[38:41], v[146:149], v[178:181], v[38:41]
	v_mfma_f32_16x16x32_bf16 v[34:37], v[154:157], v[178:181], v[34:37]
	v_mfma_f32_16x16x32_bf16 v[22:25], v[146:149], v[192:195], v[22:25]
	v_mfma_f32_16x16x32_bf16 v[18:21], v[154:157], v[192:195], v[18:21]
	v_mfma_f32_16x16x32_bf16 v[62:65], v[150:153], v[166:169], v[62:65]
	v_mfma_f32_16x16x32_bf16 v[58:61], v[158:161], v[166:169], v[58:61]
	v_mfma_f32_16x16x32_bf16 v[54:57], v[150:153], v[174:177], v[54:57]
	v_mfma_f32_16x16x32_bf16 v[50:53], v[158:161], v[174:177], v[50:53]
	v_mfma_f32_16x16x32_bf16 v[38:41], v[150:153], v[182:185], v[38:41]
	v_mfma_f32_16x16x32_bf16 v[34:37], v[158:161], v[182:185], v[34:37]
	v_mfma_f32_16x16x32_bf16 v[22:25], v[150:153], v[196:199], v[22:25]
	v_mfma_f32_16x16x32_bf16 v[18:21], v[158:161], v[196:199], v[18:21]
	s_barrier
	s_add_u32 s14, s14, 0x40080
	s_addc_u32 s15, s15, 0
	s_add_i32 s16, s16, s26
	s_mov_b32 m0, s16
	s_nop 0
	global_load_lds_dwordx4 v134, s[14:15]
	s_add_i32 m0, s16, 0x2000
	s_nop 0
	global_load_lds_dwordx4 v130, s[14:15]
	s_waitcnt vmcnt(6)
	s_barrier
	v_mfma_f32_16x16x32_bf16 v[46:49], v[200:203], v[162:165], v[46:49]
	v_mfma_f32_16x16x32_bf16 v[42:45], v[208:211], v[162:165], v[42:45]
	v_mfma_f32_16x16x32_bf16 v[30:33], v[200:203], v[170:173], v[30:33]
	v_mfma_f32_16x16x32_bf16 v[26:29], v[208:211], v[170:173], v[26:29]
	v_mfma_f32_16x16x32_bf16 v[14:17], v[200:203], v[178:181], v[14:17]
	v_mfma_f32_16x16x32_bf16 v[10:13], v[208:211], v[178:181], v[10:13]
	v_mfma_f32_16x16x32_bf16 v[6:9], v[200:203], v[192:195], v[6:9]
	v_mfma_f32_16x16x32_bf16 v[2:5], v[208:211], v[192:195], v[2:5]
	v_mfma_f32_16x16x32_bf16 v[46:49], v[204:207], v[166:169], v[46:49]
	v_mfma_f32_16x16x32_bf16 v[42:45], v[212:215], v[166:169], v[42:45]
	v_mfma_f32_16x16x32_bf16 v[30:33], v[204:207], v[174:177], v[30:33]
	v_mfma_f32_16x16x32_bf16 v[26:29], v[212:215], v[174:177], v[26:29]
	v_mfma_f32_16x16x32_bf16 v[14:17], v[204:207], v[182:185], v[14:17]
	v_mfma_f32_16x16x32_bf16 v[10:13], v[212:215], v[182:185], v[10:13]
	v_mfma_f32_16x16x32_bf16 v[6:9], v[204:207], v[196:199], v[6:9]
	v_mfma_f32_16x16x32_bf16 v[2:5], v[212:215], v[196:199], v[2:5]
	s_add_i32 s53, s53, 2
	s_add_u32 s47, s47, 0x100
	s_addc_u32 s52, s52, 0
	s_add_u32 s2, s2, 0x100
	s_addc_u32 s3, s3, 0
	s_cmp_gt_u32 s53, 13
	s_barrier
	s_cbranch_scc0 .LBB0_397
; __device__ __forceinline__ unsigned cvt_pk_bf16(float lo, float hi) { f32x2_t f = {lo, hi}; bf16x2_t v = __builtin_convertvector(f, bf16x2_t); return __builtin_bit_cast(unsigned, v); }
; #define PG8_WAIT_V(n) asm volatile("s_waitcnt vmcnt(" #n ")" ::: "memory")
; #define PG8_BAR __builtin_amdgcn_s_barrier()
; template <class Epi, class Sched, bool AREMAP>
; __device__ __forceinline__ void gemm_phase(LAS unsigned char* lds, const Gemm g, const Sched& S, const Epi& E, int wv) {
;     ...
;     PG8_WAIT_V(0);
;     if (wr == 0) PG8_BAR;
;     PG8_BAR;
;     __device__ __forceinline__ void operator()(const f32x4 (&acc)[2][2][4][2], const Unit& u, int wr, int wc, int fr, int fq) const {
;         const int row0 = u.pm * BM + wr * 64 + fr; int colt = u.pn * BM; bf16_t* base = O;
;         if (split_cols) { const int t = colt / split_cols; base += (size_t)t * split_stride; colt -= t * split_cols; }
;         const int col0 = colt + wc * 32 + 8 * fq;
; #pragma unroll
;         for (int ai = 0; ai < 2; ++ai)
; #pragma unroll
;             for (int m = 0; m < 4; ++m) { bf16_t* rowp = base + (size_t)(row0 + ai * HALF + m * 16) * ldc + col0;
; #pragma unroll
;                 for (int bj = 0; bj < 2; ++bj) { const f32x4 v0 = acc[ai][bj][m][0], v1 = acc[ai][bj][m][1];
;                     u32x4 w; w.x = cvt_pk_bf16(v0[0], v0[1]); w.y = cvt_pk_bf16(v0[2], v0[3]); w.z = cvt_pk_bf16(v1[0], v1[1]); w.w = cvt_pk_bf16(v1[2], v1[3]);
;                     *(u32x4*)(rowp + bj * HALF) = w; } }
	s_ashr_i32 s2, s46, 31
	s_lshr_b32 s2, s2, 29
	s_add_i32 s2, s46, s2
	s_ashr_i32 s2, s2, 3
	s_ashr_i32 s3, s2, 31
	s_lshl_b32 s7, s46, 8
	s_lshl_b64 s[14:15], s[2:3], 27
	s_add_u32 s14, s31, s14
	s_addc_u32 s15, s34, s15
	s_lshl_b32 s2, s2, 11
	s_sub_i32 s2, s7, s2
	v_lshl_add_u32 v146, s4, 8, v1
	v_or_b32_e32 v148, s2, v143
	v_ashrrev_i32_e32 v149, 31, v148
	v_ashrrev_i32_e32 v147, 31, v146
	v_lshl_add_u64 v[148:149], v[148:149], 1, s[14:15]
	v_lshlrev_b64 v[150:151], 12, v[146:147]
	v_lshl_add_u64 v[150:151], v[148:149], 0, v[150:151]
	s_mov_b64 s[2:3], 0x80000
	v_cvt_pk_bf16_f32 v70, v70, v71
	v_cvt_pk_bf16_f32 v71, v72, v73
	v_cvt_pk_bf16_f32 v72, v66, v67
	v_lshl_add_u64 v[66:67], v[150:151], 0, s[2:3]
	s_mov_b32 s2, 0x80000
	v_cvt_pk_bf16_f32 v62, v62, v63
	v_cvt_pk_bf16_f32 v63, v64, v65
	v_cvt_pk_bf16_f32 v64, v58, v59
	v_add_co_u32_e32 v58, vcc, s2, v150
	v_cvt_pk_bf16_f32 v46, v46, v47
	v_cvt_pk_bf16_f32 v47, v48, v49
	v_cvt_pk_bf16_f32 v48, v42, v43
	v_cvt_pk_bf16_f32 v49, v44, v45
	s_mov_b64 s[2:3], 0x90000
	v_addc_co_u32_e32 v59, vcc, 0, v151, vcc
	global_store_dwordx4 v[66:67], v[46:49], off offset:256
	v_cvt_pk_bf16_f32 v30, v30, v31
	v_cvt_pk_bf16_f32 v31, v32, v33
	v_lshl_add_u64 v[46:47], v[150:151], 0, s[2:3]
	s_mov_b32 s2, 0x90000
	v_add_co_u32_e32 v48, vcc, s2, v150
	v_cvt_pk_bf16_f32 v32, v26, v27
	v_cvt_pk_bf16_f32 v33, v28, v29
	s_mov_b64 s[2:3], 0xa0000
	v_cvt_pk_bf16_f32 v110, v110, v111
	v_cvt_pk_bf16_f32 v111, v112, v113
	v_cvt_pk_bf16_f32 v112, v106, v107
	v_or_b32_e32 v106, 16, v146
	v_addc_co_u32_e32 v49, vcc, 0, v151, vcc
	global_store_dwordx4 v[46:47], v[30:33], off offset:256
	v_ashrrev_i32_e32 v107, 31, v106
	v_cvt_pk_bf16_f32 v94, v94, v95
	v_lshl_add_u64 v[30:31], v[150:151], 0, s[2:3]
	s_mov_b32 s2, 0xa0000
	v_cvt_pk_bf16_f32 v95, v96, v97
	v_cvt_pk_bf16_f32 v96, v90, v91
	v_or_b32_e32 v90, 32, v146
	v_add_co_u32_e32 v32, vcc, s2, v150
	v_cvt_pk_bf16_f32 v14, v14, v15
	v_cvt_pk_bf16_f32 v15, v16, v17
	v_cvt_pk_bf16_f32 v16, v10, v11
	v_cvt_pk_bf16_f32 v17, v12, v13
	s_mov_b64 s[2:3], 0xb0000
	v_cvt_pk_bf16_f32 v113, v108, v109
	v_lshlrev_b64 v[106:107], 12, v[106:107]
	v_ashrrev_i32_e32 v91, 31, v90
	v_cvt_pk_bf16_f32 v78, v78, v79
	v_cvt_pk_bf16_f32 v79, v80, v81
	v_cvt_pk_bf16_f32 v80, v74, v75
	v_or_b32_e32 v74, 48, v146
	v_addc_co_u32_e32 v33, vcc, 0, v151, vcc
	global_store_dwordx4 v[30:31], v[14:17], off offset:256
	global_store_dwordx4 v[150:151], v[110:113], off offset:256
	v_cvt_pk_bf16_f32 v97, v92, v93
	v_lshl_add_u64 v[14:15], v[150:151], 0, s[2:3]
	s_mov_b32 s2, 0xb0000
	v_lshl_add_u64 v[110:111], v[148:149], 0, v[106:107]
	v_lshlrev_b64 v[90:91], 12, v[90:91]
	v_ashrrev_i32_e32 v75, 31, v74
	v_add_co_u32_e32 v16, vcc, s2, v150
	global_store_dwordx4 v[110:111], v[94:97], off offset:256
	v_cvt_pk_bf16_f32 v81, v76, v77
	v_lshlrev_b64 v[74:75], 12, v[74:75]
	v_lshl_add_u64 v[94:95], v[148:149], 0, v[90:91]
	v_addc_co_u32_e32 v17, vcc, 0, v151, vcc
	v_cvt_pk_bf16_f32 v126, v126, v127
	v_cvt_pk_bf16_f32 v127, v128, v129
	v_cvt_pk_bf16_f32 v128, v122, v123
	v_cvt_pk_bf16_f32 v129, v124, v125
	v_cvt_pk_bf16_f32 v106, v118, v119
	v_cvt_pk_bf16_f32 v107, v120, v121
	v_cvt_pk_bf16_f32 v108, v114, v115
	v_cvt_pk_bf16_f32 v109, v116, v117
	v_cvt_pk_bf16_f32 v90, v102, v103
	v_cvt_pk_bf16_f32 v91, v104, v105
	v_cvt_pk_bf16_f32 v92, v98, v99
	v_cvt_pk_bf16_f32 v93, v100, v101
	global_store_dwordx4 v[94:95], v[78:81], off offset:256
	v_cvt_pk_bf16_f32 v76, v82, v83
	v_cvt_pk_bf16_f32 v77, v84, v85
	v_lshl_add_u64 v[78:79], v[148:149], 0, v[74:75]
	v_cvt_pk_bf16_f32 v74, v86, v87
	v_cvt_pk_bf16_f32 v75, v88, v89
	v_cvt_pk_bf16_f32 v73, v68, v69
	v_cvt_pk_bf16_f32 v65, v60, v61
	v_cvt_pk_bf16_f32 v42, v54, v55
	v_cvt_pk_bf16_f32 v43, v56, v57
	v_cvt_pk_bf16_f32 v44, v50, v51
	v_cvt_pk_bf16_f32 v45, v52, v53
	v_cvt_pk_bf16_f32 v26, v38, v39
	v_cvt_pk_bf16_f32 v27, v40, v41
	v_cvt_pk_bf16_f32 v28, v34, v35
	v_cvt_pk_bf16_f32 v29, v36, v37
	v_cvt_pk_bf16_f32 v10, v22, v23
	v_cvt_pk_bf16_f32 v11, v24, v25
	v_cvt_pk_bf16_f32 v12, v18, v19
	v_cvt_pk_bf16_f32 v13, v20, v21
	v_cvt_pk_bf16_f32 v6, v6, v7
	v_cvt_pk_bf16_f32 v7, v8, v9
	v_cvt_pk_bf16_f32 v8, v2, v3
	v_cvt_pk_bf16_f32 v9, v4, v5
	s_and_b64 vcc, exec, s[0:1]
	s_mov_b32 s46, s6
	s_mov_b32 s4, s8
	s_mov_b64 s[14:15], s[12:13]
	s_mov_b64 s[16:17], s[10:11]
	s_mov_b32 s39, 0xb2a5705f
	global_store_dwordx4 v[150:151], v[126:129], off
	global_store_dwordx4 v[110:111], v[106:109], off
	global_store_dwordx4 v[94:95], v[90:93], off
	global_store_dwordx4 v[78:79], v[74:77], off
	global_store_dwordx4 v[78:79], v[70:73], off offset:256
	global_store_dwordx4 v[58:59], v[62:65], off
	global_store_dwordx4 v[48:49], v[42:45], off
	global_store_dwordx4 v[32:33], v[26:29], off
	global_store_dwordx4 v[16:17], v[10:13], off
	global_store_dwordx4 v[14:15], v[6:9], off offset:256
	s_cbranch_vccz .LBB0_392
	s_waitcnt vmcnt(0)
	s_cmpk_gt_u32 s20, 0xff
	v_readlane_b32 s31, v254, 22
	v_readlane_b32 s33, v254, 23
	s_mov_b32 s41, 0xe020
	s_cbranch_scc1 .LBB0_401
	s_barrier

; __device__ __forceinline__ int otid(int wv) { int t = (wv << 6) | (int)__builtin_amdgcn_mbcnt_hi(~0u, __builtin_amdgcn_mbcnt_lo(~0u, 0u)); asm volatile("" : "+v"(t)); return t; }
; #define PG8_STAGE(bufoff, gbase, voff) do { _Pragma("unroll") for (int _i = 0; _i < 2; ++_i) \
;         __builtin_amdgcn_global_load_lds((const unsigned*)((const char*)(gbase) + (voff)[_i]), (LAS unsigned*)(lds + (bufoff) + ldsw + _i * 8192), 16, 0, 0); } while (0)
; #define PG8_WAIT_V(n) asm volatile("s_waitcnt vmcnt(" #n ")" ::: "memory")
; #define PG8_BAR __builtin_amdgcn_s_barrier()
; template <class Epi, class Sched, bool AREMAP>
; __device__ __forceinline__ void gemm_phase(LAS unsigned char* lds, const Gemm g, const Sched& S, const Epi& E, int wv) {
;     const int tid = otid(wv), wid = __builtin_amdgcn_readfirstlane(tid >> 6), lane = tid & 63, wr = wid >> 2, wc = wid & 3, fr = lane & 15, fq = lane >> 4;
;     const int K = g.K, nt = K / BK;
;     unsigned voffA[2], voffB[2];
; #pragma unroll
;     for (int i = 0; i < 2; ++i) { int R, C; stage_rc(tid * 16 + i * 8192, R, C); const int Rb = Epi::PERM ? ((R & ~31) + perm32(R & 31)) : R;
;         const int Ra = AREMAP ? ((R >> 6) * 128 + (R & 63)) : R;
;         voffA[i] = (unsigned)(Ra * g.lda + C) * 2u; voffB[i] = (unsigned)(Rb * g.ldb + C) * 2u; }
;     const size_t kstep = (size_t)(BK * 2);
;     const size_t hstepA = (size_t)(AREMAP ? 64 : HALF) * g.lda * 2, hstepB = (size_t)HALF * g.ldb * 2;
;     const size_t tstepA = (size_t)BM * g.lda * 2, tstepB = (size_t)BM * g.ldb * 2;
;     const unsigned ldsw = (unsigned)wid * 1024u;
;     const int aoff = lds_byte(wr * 64 + fr, fq * 8), boff = lds_byte(wc * 32 + fr, fq * 8);
;     ...
;     PG8_STAGE(PG8_SB(0, 0), cB, voffB); PG8_STAGE(PG8_SA(0, 0), cA, voffA); PG8_STAGE(PG8_SB(0, 1), cB + hstepB, voffB); PG8_STAGE(PG8_SA(0, 1), cA + hstepA, voffA);
;     if (wr == 1) PG8_BAR;
;     PG8_WAIT_V(4); PG8_BAR;
;     PG8_STAGE(PG8_SB(1, 0), cB + kstep, voffB); PG8_STAGE(PG8_SA(1, 0), cA + kstep, voffA); PG8_STAGE(PG8_SB(1, 1), cB + hstepB + kstep, voffB);
;     PG8_WAIT_V(6); PG8_BAR;
.LBB0_417:
	s_add_u32 s55, s0, 0x10e00000
	s_addc_u32 s56, s1, 0
	s_ashr_i32 s7, s6, 31
	s_lshl_b64 s[6:7], s[6:7], 18
	s_add_u32 s3, s0, s6
	s_addc_u32 s5, s1, s7
	s_add_u32 s6, s3, 0x30e00000
	v_lshrrev_b32_e32 v18, 1, v13
	s_addc_u32 s7, s5, 0
	v_and_b32_e32 v18, 24, v18
	s_add_u32 s8, s0, 0x28e00000
	v_and_b32_e32 v17, 15, v13
	v_lshlrev_b32_e32 v19, 1, v18
	v_lshlrev_b32_e32 v13, 2, v13
	s_addc_u32 s9, s1, 0
	v_lshl_or_b32 v1, s10, 6, v17
	v_lshl_or_b32 v17, v17, 6, v19
	s_lshl_b32 s0, s10, 13
	v_and_b32_e32 v13, 32, v13
	v_bitop3_b32 v19, v17, s0, v13 bitop3:0xde
	s_lshl_b32 s0, s11, 5
	s_and_b32 s3, s0, 0x60
	s_add_i32 m0, s35, 0x18000
	v_lshl_add_u64 v[8:9], v[8:9], 0, s[86:87]
	s_lshl_b32 s0, s3, 7
	s_waitcnt vmcnt(4)
	s_barrier
	global_load_lds_dwordx4 v[8:9], off
	v_lshl_add_u64 v[6:7], v[6:7], 0, s[86:87]
	s_add_i32 m0, s35, 0x1a000
	s_add_i32 s57, s35, 0x8000
	s_add_i32 s62, s35, 0xa000
	v_bitop3_b32 v186, v17, s0, v13 bitop3:0xde
	global_load_lds_dwordx4 v[6:7], off
	v_lshl_add_u64 v[4:5], v[4:5], 0, s[86:87]
	s_mov_b32 m0, s57
	s_add_u32 s0, s18, 0x80080
	global_load_lds_dwordx4 v[4:5], off
	v_lshl_add_u64 v[2:3], v[2:3], 0, s[86:87]
	s_mov_b32 m0, s62
	s_addc_u32 s1, s19, 0
	global_load_lds_dwordx4 v[2:3], off
	s_add_i32 m0, s35, 0x1c000
	s_nop 0
	global_load_lds_dwordx4 v164, s[0:1]
	s_add_i32 m0, s35, 0x1e000
	s_ashr_i32 s63, s26, 31
	global_load_lds_dwordx4 v168, s[0:1]
	v_lshlrev_b32_e32 v2, 15, v14
	v_and_b32_e32 v2, 0xffff0000, v2
	v_lshl_add_u32 v2, v15, 12, v2
	v_and_b32_e32 v3, 1, v14
	v_lshl_or_b32 v2, v3, 6, v2
	v_lshl_add_u32 v170, v16, 1, v2
	v_lshlrev_b32_e32 v2, 15, v10
	v_and_b32_e32 v2, 0xffff0000, v2
	s_waitcnt vmcnt(6)
	v_lshl_add_u32 v2, v11, 12, v2
	v_and_b32_e32 v3, 1, v10
	v_lshl_or_b32 v2, v3, 6, v2
	v_or_b32_e32 v187, s3, v18
	v_mov_b32_e32 v171, v0
	v_lshl_add_u32 v172, v12, 1, v2
	v_mov_b32_e32 v173, v0
	s_mov_b32 s65, 0
	v_add_u32_e32 v196, 0, v19
	s_barrier
	s_branch .LBB0_419

; #define PG8_STAGE(bufoff, gbase, voff) do { _Pragma("unroll") for (int _i = 0; _i < 2; ++_i) \
;         __builtin_amdgcn_global_load_lds((const unsigned*)((const char*)(gbase) + (voff)[_i]), (LAS unsigned*)(lds + (bufoff) + ldsw + _i * 8192), 16, 0, 0); } while (0)
; #define PG8_LDA(dst, b, h) do { _Pragma("unroll") for (int m = 0; m < 4; ++m) _Pragma("unroll") for (int k = 0; k < 2; ++k) dst[m][k] = *(const LAS bf16x8*)(lds + PG8_SA(b, h) + aoff + m * 2048 + k * 1024); } while (0)
; #define PG8_LDB(dst, b, h) do { _Pragma("unroll") for (int n = 0; n < 2; ++n) _Pragma("unroll") for (int k = 0; k < 2; ++k) dst[n][k] = *(const LAS bf16x8*)(lds + PG8_SB(b, h) + boff + n * 2048 + k * 1024); } while (0)
; #define PG8_MMA(ai, bj, At, Bt) do { __builtin_amdgcn_s_setprio(1); _Pragma("unroll") for (int m = 0; m < 4; ++m) _Pragma("unroll") for (int n = 0; n < 2; ++n) _Pragma("unroll") for (int k = 0; k < 2; ++k) \
;         acc[ai][bj][m][n] = __builtin_amdgcn_mfma_f32_16x16x32_bf16(Bt[n][k], At[m][k], acc[ai][bj][m][n], 0, 0, 0); __builtin_amdgcn_s_setprio(0); } while (0)
; #define PG8_WAIT_L(n) asm volatile("s_waitcnt lgkmcnt(" #n ")" ::: "memory")
; #define PG8_BAR __builtin_amdgcn_s_barrier()
; #define PG8_SCHED __builtin_amdgcn_sched_barrier(0)
; template <class Epi, class Sched, bool AREMAP>
; __device__ __forceinline__ void gemm_phase(LAS unsigned char* lds, const Gemm g, const Sched& S, const Epi& E, int wv) {
;     ...
;             PG8_LDB(B0, 0, 0); PG8_SCHED; PG8_LDA(At, 0, 0); PG8_STAGE(PG8_SA(1, 1), a1 + hstepA, voffA);
;             PG8_WAIT_L(8); PG8_BAR; PG8_WAIT_L(0); PG8_MMA(0, 0, At, B0); PG8_BAR; PG8_SCHED;
;             PG8_LDB(B1, 0, 1); PG8_STAGE(PG8_SB(0, 0), b2, voffB);
;             PG8_BAR; PG8_WAIT_L(0); PG8_MMA(0, 1, At, B1); PG8_BAR;
;             PG8_LDA(At, 0, 1); PG8_STAGE(PG8_SA(0, 0), a2, voffA);
;             PG8_BAR; PG8_WAIT_L(0); PG8_MMA(1, 0, At, B0); PG8_BAR; PG8_SCHED;
.LBB0_426:
	s_add_u32 s20, s18, 0xfff80080
	s_addc_u32 s21, s19, -1
	s_add_i32 s38, 0, 0x10000
	v_add_u32_e32 v142, s38, v186
	ds_read_b128 v[130:133], v142
	ds_read_b128 v[134:137], v142 offset:1024
	ds_read_b128 v[138:141], v142 offset:2048
	ds_read_b128 v[142:145], v142 offset:3072
	s_cmp_eq_u32 s46, 28
	s_cselect_b32 s23, s3, s21
	s_cselect_b32 s22, s5, s20
	s_cselect_b32 s21, s11, s37
	s_cselect_b32 s20, s13, s36
	s_add_i32 m0, s35, 0xc000
	ds_read_b128 v[146:149], v196
	ds_read_b128 v[150:153], v196 offset:1024
	ds_read_b128 v[154:157], v196 offset:2048
	ds_read_b128 v[158:161], v196 offset:3072
	ds_read_b128 v[174:177], v196 offset:4096
	ds_read_b128 v[178:181], v196 offset:5120
	ds_read_b128 v[182:185], v196 offset:6144
	ds_read_b128 v[192:195], v196 offset:7168
	global_load_lds_dwordx4 v172, s[18:19]
	s_add_i32 m0, s35, 0xe000
	s_nop 0
	global_load_lds_dwordx4 v170, s[18:19]
	s_waitcnt lgkmcnt(8)
	s_barrier
	s_waitcnt lgkmcnt(0)
	s_waitcnt lgkmcnt(0)
	v_mfma_f32_16x16x32_bf16 v[126:129], v[130:133], v[146:149], v[126:129]
	v_mfma_f32_16x16x32_bf16 v[122:125], v[138:141], v[146:149], v[122:125]
	v_mfma_f32_16x16x32_bf16 v[110:113], v[130:133], v[154:157], v[110:113]
	v_mfma_f32_16x16x32_bf16 v[106:109], v[138:141], v[154:157], v[106:109]
	v_mfma_f32_16x16x32_bf16 v[94:97], v[130:133], v[174:177], v[94:97]
	v_mfma_f32_16x16x32_bf16 v[90:93], v[138:141], v[174:177], v[90:93]
	v_mfma_f32_16x16x32_bf16 v[78:81], v[130:133], v[182:185], v[78:81]
	v_mfma_f32_16x16x32_bf16 v[74:77], v[138:141], v[182:185], v[74:77]
	v_mfma_f32_16x16x32_bf16 v[126:129], v[134:137], v[150:153], v[126:129]
	v_mfma_f32_16x16x32_bf16 v[122:125], v[142:145], v[150:153], v[122:125]
	v_mfma_f32_16x16x32_bf16 v[110:113], v[134:137], v[158:161], v[110:113]
	v_mfma_f32_16x16x32_bf16 v[106:109], v[142:145], v[158:161], v[106:109]
	v_mfma_f32_16x16x32_bf16 v[94:97], v[134:137], v[178:181], v[94:97]
	v_mfma_f32_16x16x32_bf16 v[90:93], v[142:145], v[178:181], v[90:93]
	v_mfma_f32_16x16x32_bf16 v[78:81], v[134:137], v[192:195], v[78:81]
	v_mfma_f32_16x16x32_bf16 v[74:77], v[142:145], v[192:195], v[74:77]
	s_barrier
	s_add_i32 s39, 0, 0x14000
	s_add_i32 s38, s38, s34
	v_add_u32_e32 v197, s39, v186
	v_lshl_add_u64 v[214:215], s[20:21], 0, v[164:165]
	s_mov_b32 m0, s38
	ds_read_b128 v[198:201], v197
	ds_read_b128 v[202:205], v197 offset:1024
	ds_read_b128 v[206:209], v197 offset:2048
	ds_read_b128 v[210:213], v197 offset:3072
	global_load_lds_dwordx4 v[214:215], off
	v_lshl_add_u64 v[216:217], s[20:21], 0, v[168:169]
	s_add_i32 m0, s38, 0x2000
	s_nop 0
	global_load_lds_dwordx4 v[216:217], off
	s_barrier
	s_waitcnt lgkmcnt(0)
	s_waitcnt lgkmcnt(0)
	v_mfma_f32_16x16x32_bf16 v[118:121], v[198:201], v[146:149], v[118:121]
	v_mfma_f32_16x16x32_bf16 v[114:117], v[206:209], v[146:149], v[114:117]
	v_mfma_f32_16x16x32_bf16 v[102:105], v[198:201], v[154:157], v[102:105]
	v_mfma_f32_16x16x32_bf16 v[98:101], v[206:209], v[154:157], v[98:101]
	v_mfma_f32_16x16x32_bf16 v[86:89], v[198:201], v[174:177], v[86:89]
	v_mfma_f32_16x16x32_bf16 v[82:85], v[206:209], v[174:177], v[82:85]
	v_mfma_f32_16x16x32_bf16 v[70:73], v[198:201], v[182:185], v[70:73]
	v_mfma_f32_16x16x32_bf16 v[66:69], v[206:209], v[182:185], v[66:69]
	v_mfma_f32_16x16x32_bf16 v[118:121], v[202:205], v[150:153], v[118:121]
	v_mfma_f32_16x16x32_bf16 v[114:117], v[210:213], v[150:153], v[114:117]
	v_mfma_f32_16x16x32_bf16 v[102:105], v[202:205], v[158:161], v[102:105]
	v_mfma_f32_16x16x32_bf16 v[98:101], v[210:213], v[158:161], v[98:101]
	v_mfma_f32_16x16x32_bf16 v[86:89], v[202:205], v[178:181], v[86:89]
	v_mfma_f32_16x16x32_bf16 v[82:85], v[210:213], v[178:181], v[82:85]
	v_mfma_f32_16x16x32_bf16 v[70:73], v[202:205], v[192:195], v[70:73]
	v_mfma_f32_16x16x32_bf16 v[66:69], v[210:213], v[192:195], v[66:69]
	s_mov_b32 m0, s35
	v_lshl_add_u64 v[218:219], s[22:23], 0, v[162:163]
	s_barrier
	ds_read_b128 v[146:149], v196 offset:16384
	ds_read_b128 v[150:153], v196 offset:17408
	ds_read_b128 v[154:157], v196 offset:18432
	ds_read_b128 v[158:161], v196 offset:19456
	ds_read_b128 v[174:177], v196 offset:20480
	ds_read_b128 v[178:181], v196 offset:21504
	ds_read_b128 v[182:185], v196 offset:22528
	ds_read_b128 v[192:195], v196 offset:23552
	global_load_lds_dwordx4 v[218:219], off
	v_lshl_add_u64 v[220:221], s[22:23], 0, v[166:167]
	s_mov_b32 m0, s41
	s_nop 0
	global_load_lds_dwordx4 v[220:221], off
	s_barrier
	s_waitcnt lgkmcnt(0)
	s_waitcnt lgkmcnt(0)
	v_mfma_f32_16x16x32_bf16 v[62:65], v[130:133], v[146:149], v[62:65]
	v_mfma_f32_16x16x32_bf16 v[58:61], v[138:141], v[146:149], v[58:61]
	v_mfma_f32_16x16x32_bf16 v[46:49], v[130:133], v[154:157], v[46:49]
	v_mfma_f32_16x16x32_bf16 v[42:45], v[138:141], v[154:157], v[42:45]
	v_mfma_f32_16x16x32_bf16 v[30:33], v[130:133], v[174:177], v[30:33]
	v_mfma_f32_16x16x32_bf16 v[26:29], v[138:141], v[174:177], v[26:29]
	v_mfma_f32_16x16x32_bf16 v[14:17], v[130:133], v[182:185], v[14:17]
	v_mfma_f32_16x16x32_bf16 v[10:13], v[138:141], v[182:185], v[10:13]
	v_mfma_f32_16x16x32_bf16 v[62:65], v[134:137], v[150:153], v[62:65]
	v_mfma_f32_16x16x32_bf16 v[58:61], v[142:145], v[150:153], v[58:61]
	v_mfma_f32_16x16x32_bf16 v[46:49], v[134:137], v[158:161], v[46:49]
	v_mfma_f32_16x16x32_bf16 v[42:45], v[142:145], v[158:161], v[42:45]
	v_mfma_f32_16x16x32_bf16 v[30:33], v[134:137], v[178:181], v[30:33]
	v_mfma_f32_16x16x32_bf16 v[26:29], v[142:145], v[178:181], v[26:29]
	v_mfma_f32_16x16x32_bf16 v[14:17], v[134:137], v[192:195], v[14:17]
	v_mfma_f32_16x16x32_bf16 v[10:13], v[142:145], v[192:195], v[10:13]
	s_barrier
; #define PG8_STAGE(bufoff, gbase, voff) do { _Pragma("unroll") for (int _i = 0; _i < 2; ++_i) \
;         __builtin_amdgcn_global_load_lds((const unsigned*)((const char*)(gbase) + (voff)[_i]), (LAS unsigned*)(lds + (bufoff) + ldsw + _i * 8192), 16, 0, 0); } while (0)
; #define PG8_LDA(dst, b, h) do { _Pragma("unroll") for (int m = 0; m < 4; ++m) _Pragma("unroll") for (int k = 0; k < 2; ++k) dst[m][k] = *(const LAS bf16x8*)(lds + PG8_SA(b, h) + aoff + m * 2048 + k * 1024); } while (0)
; #define PG8_LDB(dst, b, h) do { _Pragma("unroll") for (int n = 0; n < 2; ++n) _Pragma("unroll") for (int k = 0; k < 2; ++k) dst[n][k] = *(const LAS bf16x8*)(lds + PG8_SB(b, h) + boff + n * 2048 + k * 1024); } while (0)
; #define PG8_MMA(ai, bj, At, Bt) do { __builtin_amdgcn_s_setprio(1); _Pragma("unroll") for (int m = 0; m < 4; ++m) _Pragma("unroll") for (int n = 0; n < 2; ++n) _Pragma("unroll") for (int k = 0; k < 2; ++k) \
;         acc[ai][bj][m][n] = __builtin_amdgcn_mfma_f32_16x16x32_bf16(Bt[n][k], At[m][k], acc[ai][bj][m][n], 0, 0, 0); __builtin_amdgcn_s_setprio(0); } while (0)
; #define PG8_WAIT_V(n) asm volatile("s_waitcnt vmcnt(" #n ")" ::: "memory")
; #define PG8_WAIT_L(n) asm volatile("s_waitcnt lgkmcnt(" #n ")" ::: "memory")
; #define PG8_BAR __builtin_amdgcn_s_barrier()
; #define PG8_SCHED __builtin_amdgcn_sched_barrier(0)
; template <class Epi, class Sched, bool AREMAP>
; __device__ __forceinline__ void gemm_phase(LAS unsigned char* lds, const Gemm g, const Sched& S, const Epi& E, int wv) {
;     ...
;             PG8_STAGE(PG8_SB(0, 1), b2 + hstepB, voffB);
;             PG8_WAIT_V(6); PG8_BAR; PG8_MMA(1, 1, At, B1); PG8_BAR;
;             PG8_LDB(B0, 1, 0); PG8_SCHED; PG8_LDA(At, 1, 0); PG8_STAGE(PG8_SA(0, 1), a2 + hstepA, voffA);
;             PG8_WAIT_L(8); PG8_BAR; PG8_WAIT_L(0); PG8_MMA(0, 0, At, B0); PG8_BAR; PG8_SCHED;
;             PG8_LDB(B1, 1, 1); PG8_STAGE(PG8_SB(1, 0), b3, voffB);
;             PG8_BAR; PG8_WAIT_L(0); PG8_MMA(0, 1, At, B1); PG8_BAR;
;             PG8_LDA(At, 1, 1); PG8_STAGE(PG8_SA(1, 0), a3, voffA);
	s_add_u32 s66, s20, 0x80000
	s_addc_u32 s67, s21, 0
	s_add_i32 s38, s39, s34
	s_mov_b32 m0, s38
	s_nop 0
	global_load_lds_dwordx4 v164, s[66:67]
	s_add_i32 m0, s38, 0x2000
	s_nop 0
	global_load_lds_dwordx4 v168, s[66:67]
	s_waitcnt vmcnt(6)
	s_barrier
	v_mfma_f32_16x16x32_bf16 v[54:57], v[198:201], v[146:149], v[54:57]
	v_mfma_f32_16x16x32_bf16 v[50:53], v[206:209], v[146:149], v[50:53]
	v_mfma_f32_16x16x32_bf16 v[38:41], v[198:201], v[154:157], v[38:41]
	v_mfma_f32_16x16x32_bf16 v[34:37], v[206:209], v[154:157], v[34:37]
	v_mfma_f32_16x16x32_bf16 v[22:25], v[198:201], v[174:177], v[22:25]
	v_mfma_f32_16x16x32_bf16 v[18:21], v[206:209], v[174:177], v[18:21]
	v_mfma_f32_16x16x32_bf16 v[6:9], v[198:201], v[182:185], v[6:9]
	v_mfma_f32_16x16x32_bf16 v[2:5], v[206:209], v[182:185], v[2:5]
	v_mfma_f32_16x16x32_bf16 v[54:57], v[202:205], v[150:153], v[54:57]
	v_mfma_f32_16x16x32_bf16 v[50:53], v[210:213], v[150:153], v[50:53]
	v_mfma_f32_16x16x32_bf16 v[38:41], v[202:205], v[158:161], v[38:41]
	v_mfma_f32_16x16x32_bf16 v[34:37], v[210:213], v[158:161], v[34:37]
	v_mfma_f32_16x16x32_bf16 v[22:25], v[202:205], v[178:181], v[22:25]
	v_mfma_f32_16x16x32_bf16 v[18:21], v[210:213], v[178:181], v[18:21]
	v_mfma_f32_16x16x32_bf16 v[6:9], v[202:205], v[192:195], v[6:9]
	v_mfma_f32_16x16x32_bf16 v[2:5], v[210:213], v[192:195], v[2:5]
	s_add_i32 s38, 0, 0x18000
	v_add_u32_e32 v142, s38, v186
	s_barrier
	ds_read_b128 v[130:133], v142
	ds_read_b128 v[134:137], v142 offset:1024
	ds_read_b128 v[138:141], v142 offset:2048
	ds_read_b128 v[142:145], v142 offset:3072
	s_add_u32 s22, s22, 0x80000
	s_addc_u32 s23, s23, 0
	s_mov_b32 m0, s52
	ds_read_b128 v[146:149], v196 offset:32768
	ds_read_b128 v[150:153], v196 offset:33792
	ds_read_b128 v[154:157], v196 offset:34816
	ds_read_b128 v[158:161], v196 offset:35840
	ds_read_b128 v[174:177], v196 offset:36864
	ds_read_b128 v[178:181], v196 offset:37888
	ds_read_b128 v[182:185], v196 offset:38912
	ds_read_b128 v[192:195], v196 offset:39936
	global_load_lds_dwordx4 v162, s[22:23]
	s_mov_b32 m0, s53
	s_nop 0
	global_load_lds_dwordx4 v166, s[22:23]
	s_waitcnt lgkmcnt(8)
	s_barrier
	s_waitcnt lgkmcnt(0)
	s_waitcnt lgkmcnt(0)
	v_mfma_f32_16x16x32_bf16 v[126:129], v[130:133], v[146:149], v[126:129]
	v_mfma_f32_16x16x32_bf16 v[122:125], v[138:141], v[146:149], v[122:125]
	v_mfma_f32_16x16x32_bf16 v[110:113], v[130:133], v[154:157], v[110:113]
	v_mfma_f32_16x16x32_bf16 v[106:109], v[138:141], v[154:157], v[106:109]
	v_mfma_f32_16x16x32_bf16 v[94:97], v[130:133], v[174:177], v[94:97]
	v_mfma_f32_16x16x32_bf16 v[90:93], v[138:141], v[174:177], v[90:93]
	v_mfma_f32_16x16x32_bf16 v[78:81], v[130:133], v[182:185], v[78:81]
	v_mfma_f32_16x16x32_bf16 v[74:77], v[138:141], v[182:185], v[74:77]
	v_mfma_f32_16x16x32_bf16 v[126:129], v[134:137], v[150:153], v[126:129]
	v_mfma_f32_16x16x32_bf16 v[122:125], v[142:145], v[150:153], v[122:125]
	v_mfma_f32_16x16x32_bf16 v[110:113], v[134:137], v[158:161], v[110:113]
	v_mfma_f32_16x16x32_bf16 v[106:109], v[142:145], v[158:161], v[106:109]
	v_mfma_f32_16x16x32_bf16 v[94:97], v[134:137], v[178:181], v[94:97]
	v_mfma_f32_16x16x32_bf16 v[90:93], v[142:145], v[178:181], v[90:93]
	v_mfma_f32_16x16x32_bf16 v[78:81], v[134:137], v[192:195], v[78:81]
	v_mfma_f32_16x16x32_bf16 v[74:77], v[142:145], v[192:195], v[74:77]
	s_barrier
	s_add_i32 s22, 0, 0x1c000
	s_add_i32 s23, s38, s34
	v_add_u32_e32 v197, s22, v186
	v_lshl_add_u64 v[214:215], v[214:215], 0, s[86:87]
	s_mov_b32 m0, s23
	ds_read_b128 v[198:201], v197
	ds_read_b128 v[202:205], v197 offset:1024
	ds_read_b128 v[206:209], v197 offset:2048
	ds_read_b128 v[210:213], v197 offset:3072
	global_load_lds_dwordx4 v[214:215], off
	v_lshl_add_u64 v[214:215], v[216:217], 0, s[86:87]
	s_add_i32 m0, s23, 0x2000
	s_nop 0
	global_load_lds_dwordx4 v[214:215], off
	s_barrier
	s_waitcnt lgkmcnt(0)
	s_waitcnt lgkmcnt(0)
	v_mfma_f32_16x16x32_bf16 v[118:121], v[198:201], v[146:149], v[118:121]
	v_mfma_f32_16x16x32_bf16 v[114:117], v[206:209], v[146:149], v[114:117]
	v_mfma_f32_16x16x32_bf16 v[102:105], v[198:201], v[154:157], v[102:105]
	v_mfma_f32_16x16x32_bf16 v[98:101], v[206:209], v[154:157], v[98:101]
	v_mfma_f32_16x16x32_bf16 v[86:89], v[198:201], v[174:177], v[86:89]
	v_mfma_f32_16x16x32_bf16 v[82:85], v[206:209], v[174:177], v[82:85]
	v_mfma_f32_16x16x32_bf16 v[70:73], v[198:201], v[182:185], v[70:73]
	v_mfma_f32_16x16x32_bf16 v[66:69], v[206:209], v[182:185], v[66:69]
	v_mfma_f32_16x16x32_bf16 v[118:121], v[202:205], v[150:153], v[118:121]
	v_mfma_f32_16x16x32_bf16 v[114:117], v[210:213], v[150:153], v[114:117]
	v_mfma_f32_16x16x32_bf16 v[102:105], v[202:205], v[158:161], v[102:105]
	v_mfma_f32_16x16x32_bf16 v[98:101], v[210:213], v[158:161], v[98:101]
	v_mfma_f32_16x16x32_bf16 v[86:89], v[202:205], v[178:181], v[86:89]
	v_mfma_f32_16x16x32_bf16 v[82:85], v[210:213], v[178:181], v[82:85]
	v_mfma_f32_16x16x32_bf16 v[70:73], v[202:205], v[192:195], v[70:73]
	v_mfma_f32_16x16x32_bf16 v[66:69], v[210:213], v[192:195], v[66:69]
	s_mov_b32 m0, s57
	v_lshl_add_u64 v[214:215], v[218:219], 0, s[86:87]
	s_barrier
; __device__ __forceinline__ int otid(int wv) { int t = (wv << 6) | (int)__builtin_amdgcn_mbcnt_hi(~0u, __builtin_amdgcn_mbcnt_lo(~0u, 0u)); asm volatile("" : "+v"(t)); return t; }
; #define PG8_STAGE(bufoff, gbase, voff) do { _Pragma("unroll") for (int _i = 0; _i < 2; ++_i) \
;         __builtin_amdgcn_global_load_lds((const unsigned*)((const char*)(gbase) + (voff)[_i]), (LAS unsigned*)(lds + (bufoff) + ldsw + _i * 8192), 16, 0, 0); } while (0)
; #define PG8_LDA(dst, b, h) do { _Pragma("unroll") for (int m = 0; m < 4; ++m) _Pragma("unroll") for (int k = 0; k < 2; ++k) dst[m][k] = *(const LAS bf16x8*)(lds + PG8_SA(b, h) + aoff + m * 2048 + k * 1024); } while (0)
; #define PG8_WAIT_V(n) asm volatile("s_waitcnt vmcnt(" #n ")" ::: "memory")
; #define PG8_WAIT_L(n) asm volatile("s_waitcnt lgkmcnt(" #n ")" ::: "memory")
; #define PG8_BAR __builtin_amdgcn_s_barrier()
; template <class Epi, class Sched, bool AREMAP>
; __device__ __forceinline__ void gemm_phase(LAS unsigned char* lds, const Gemm g, const Sched& S, const Epi& E, int wv) {
;     ...
;             PG8_LDA(At, 1, 1); PG8_STAGE(PG8_SA(1, 0), a3, voffA);
;             PG8_BAR; PG8_WAIT_L(0); PG8_MMA(1, 0, At, B0); PG8_BAR; PG8_SCHED;
;             PG8_STAGE(PG8_SB(1, 1), b3 + hstepB, voffB);
;             PG8_WAIT_V(6); PG8_BAR; PG8_MMA(1, 1, At, B1); PG8_BAR;
;     __device__ __forceinline__ void operator()(const f32x4 (&acc)[2][2][4][2], const Unit& u, int wr, int wc, int fr, int fq) const {
;         const int b = u.pn >> 3, pn8 = u.pn & 7;
;         const int row0 = u.pm * BM + wr * 64 + fr, col0 = pn8 * BM + wc * 32 + 8 * fq;
;         const bf16_t* yb = YB + (size_t)b * NTOK * DM;
;         u32x4* sc = (u32x4*)scratch + otid(wv);
; #pragma unroll
;         for (int ai = 0; ai < 2; ++ai)
; #pragma unroll
;             for (int mp = 0; mp < 2; ++mp) {
;                 u32x4 y[2][2], pr[2][2];
; #pragma unroll
;                 for (int mm = 0; mm < 2; ++mm)
; #pragma unroll
;                     for (int bj = 0; bj < 2; ++bj) { const int m = mp * 2 + mm; const size_t off = (size_t)(row0 + ai * HALF + m * 16) * DM + col0;
;                         y[mm][bj] = *(const u32x4*)(yb + off + bj * HALF);
;                         const int slot = (ai * 4 + m) * 2 + bj;
;                         pr[mm][bj] = (u32x4){0u, 0u, 0u, 0u};
;                         if (b > 0) pr[mm][bj] = sc[(size_t)slot * NTHR]; }
	ds_read_b128 v[146:149], v196 offset:49152
	ds_read_b128 v[150:153], v196 offset:50176
	ds_read_b128 v[154:157], v196 offset:51200
	ds_read_b128 v[158:161], v196 offset:52224
	ds_read_b128 v[174:177], v196 offset:53248
	ds_read_b128 v[178:181], v196 offset:54272
	ds_read_b128 v[182:185], v196 offset:55296
	ds_read_b128 v[192:195], v196 offset:56320
	global_load_lds_dwordx4 v[214:215], off
	v_lshl_add_u64 v[214:215], v[220:221], 0, s[86:87]
	s_mov_b32 m0, s62
	s_nop 0
	global_load_lds_dwordx4 v[214:215], off
	s_barrier
	s_waitcnt lgkmcnt(0)
	s_waitcnt lgkmcnt(0)
	v_mfma_f32_16x16x32_bf16 v[62:65], v[130:133], v[146:149], v[62:65]
	v_mfma_f32_16x16x32_bf16 v[58:61], v[138:141], v[146:149], v[58:61]
	v_mfma_f32_16x16x32_bf16 v[46:49], v[130:133], v[154:157], v[46:49]
	v_mfma_f32_16x16x32_bf16 v[42:45], v[138:141], v[154:157], v[42:45]
	v_mfma_f32_16x16x32_bf16 v[30:33], v[130:133], v[174:177], v[30:33]
	v_mfma_f32_16x16x32_bf16 v[26:29], v[138:141], v[174:177], v[26:29]
	v_mfma_f32_16x16x32_bf16 v[14:17], v[130:133], v[182:185], v[14:17]
	v_mfma_f32_16x16x32_bf16 v[10:13], v[138:141], v[182:185], v[10:13]
	v_mfma_f32_16x16x32_bf16 v[62:65], v[134:137], v[150:153], v[62:65]
	v_mfma_f32_16x16x32_bf16 v[58:61], v[142:145], v[150:153], v[58:61]
	v_mfma_f32_16x16x32_bf16 v[46:49], v[134:137], v[158:161], v[46:49]
	v_mfma_f32_16x16x32_bf16 v[42:45], v[142:145], v[158:161], v[42:45]
	v_mfma_f32_16x16x32_bf16 v[30:33], v[134:137], v[178:181], v[30:33]
	v_mfma_f32_16x16x32_bf16 v[26:29], v[142:145], v[178:181], v[26:29]
	v_mfma_f32_16x16x32_bf16 v[14:17], v[134:137], v[192:195], v[14:17]
	v_mfma_f32_16x16x32_bf16 v[10:13], v[142:145], v[192:195], v[10:13]
	s_barrier
	s_add_u32 s20, s20, 0x80080
	s_addc_u32 s21, s21, 0
	s_add_i32 s22, s22, s34
	s_mov_b32 m0, s22
	s_nop 0
	global_load_lds_dwordx4 v164, s[20:21]
	s_add_i32 m0, s22, 0x2000
	s_nop 0
	global_load_lds_dwordx4 v168, s[20:21]
	s_waitcnt vmcnt(6)
	s_barrier
	v_mfma_f32_16x16x32_bf16 v[54:57], v[198:201], v[146:149], v[54:57]
	v_mfma_f32_16x16x32_bf16 v[50:53], v[206:209], v[146:149], v[50:53]
	v_mfma_f32_16x16x32_bf16 v[38:41], v[198:201], v[154:157], v[38:41]
	v_mfma_f32_16x16x32_bf16 v[34:37], v[206:209], v[154:157], v[34:37]
	v_mfma_f32_16x16x32_bf16 v[22:25], v[198:201], v[174:177], v[22:25]
	v_mfma_f32_16x16x32_bf16 v[18:21], v[206:209], v[174:177], v[18:21]
	v_mfma_f32_16x16x32_bf16 v[6:9], v[198:201], v[182:185], v[6:9]
	v_mfma_f32_16x16x32_bf16 v[2:5], v[206:209], v[182:185], v[2:5]
	v_mfma_f32_16x16x32_bf16 v[54:57], v[202:205], v[150:153], v[54:57]
	v_mfma_f32_16x16x32_bf16 v[50:53], v[210:213], v[150:153], v[50:53]
	v_mfma_f32_16x16x32_bf16 v[38:41], v[202:205], v[158:161], v[38:41]
	v_mfma_f32_16x16x32_bf16 v[34:37], v[210:213], v[158:161], v[34:37]
	v_mfma_f32_16x16x32_bf16 v[22:25], v[202:205], v[178:181], v[22:25]
	v_mfma_f32_16x16x32_bf16 v[18:21], v[210:213], v[178:181], v[18:21]
	v_mfma_f32_16x16x32_bf16 v[6:9], v[202:205], v[192:195], v[6:9]
	v_mfma_f32_16x16x32_bf16 v[2:5], v[210:213], v[192:195], v[2:5]
	s_add_i32 s46, s46, 2
	s_add_u32 s36, s36, 0x100
	s_addc_u32 s37, s37, 0
	s_add_u32 s18, s18, 0x100
	s_addc_u32 s19, s19, 0
	s_cmp_gt_u32 s46, 29
	s_barrier
	s_cbranch_scc0 .LBB0_426
	s_ashr_i32 s18, s4, 3
	v_lshl_add_u32 v178, s2, 8, v1
	s_lshl_b32 s2, s4, 8
	s_and_b32 s2, s2, 0x700
	s_ashr_i32 s19, s18, 31
	v_or_b32_e32 v132, s2, v187
	s_lshl_b64 s[2:3], s[18:19], 27
	s_add_u32 s2, s55, s2
	s_addc_u32 s3, s56, s3
	v_mov_b32_e32 v130, v236
	v_lshlrev_b32_e32 v176, 1, v132
	v_mov_b32_e32 v177, v0
	v_ashrrev_i32_e32 v179, 31, v178
	v_lshl_add_u64 v[180:181], s[2:3], 0, v[176:177]
	v_ashrrev_i32_e32 v131, 31, v130
	v_lshlrev_b64 v[184:185], 12, v[178:179]
	v_lshl_add_u64 v[174:175], v[130:131], 4, s[6:7]
	v_lshl_add_u64 v[130:131], v[180:181], 0, v[184:185]
	v_mov_b64_e32 v[250:251], v[130:131]
	s_mov_b32 s20, 0x20000
	s_mov_b32 s21, 0
	v_lshl_add_u64 v[252:253], v[250:251], 0, s[20:21]
	global_load_dwordx4 v[198:201], v[252:253], off
	global_load_dwordx4 v[202:205], v[252:253], off offset:256
	s_mov_b32 s20, 0x30000
	v_lshl_add_u64 v[252:253], v[250:251], 0, s[20:21]
	global_load_dwordx4 v[206:209], v[252:253], off
	global_load_dwordx4 v[210:213], v[252:253], off offset:256
	global_load_dwordx4 v[154:157], v[130:131], off
	s_cmp_gt_i32 s18, 0
	s_cselect_b64 s[2:3], -1, 0
	s_cmp_lt_i32 s18, 1
	s_cbranch_scc1 .LBB0_429
	global_load_dwordx4 v[158:161], v[174:175], off
	s_branch .LBB0_430

; __device__ __forceinline__ int otid(int wv) { int t = (wv << 6) | (int)__builtin_amdgcn_mbcnt_hi(~0u, __builtin_amdgcn_mbcnt_lo(~0u, 0u)); asm volatile("" : "+v"(t)); return t; }
; #define PG8_STAGE(bufoff, gbase, voff) do { _Pragma("unroll") for (int _i = 0; _i < 2; ++_i) \
;         __builtin_amdgcn_global_load_lds((const unsigned*)((const char*)(gbase) + (voff)[_i]), (LAS unsigned*)(lds + (bufoff) + ldsw + _i * 8192), 16, 0, 0); } while (0)
; #define PG8_WAIT_V(n) asm volatile("s_waitcnt vmcnt(" #n ")" ::: "memory")
; #define PG8_BAR __builtin_amdgcn_s_barrier()
; template <class Epi, class Sched, bool AREMAP>
; __device__ __forceinline__ void gemm_phase(LAS unsigned char* lds, const Gemm g, const Sched& S, const Epi& E, int wv) {
;     const int tid = otid(wv), wid = __builtin_amdgcn_readfirstlane(tid >> 6), lane = tid & 63, wr = wid >> 2, wc = wid & 3, fr = lane & 15, fq = lane >> 4;
;     const int K = g.K, nt = K / BK;
;     unsigned voffA[2], voffB[2];
; #pragma unroll
;     for (int i = 0; i < 2; ++i) { int R, C; stage_rc(tid * 16 + i * 8192, R, C); const int Rb = Epi::PERM ? ((R & ~31) + perm32(R & 31)) : R;
;         const int Ra = AREMAP ? ((R >> 6) * 128 + (R & 63)) : R;
;         voffA[i] = (unsigned)(Ra * g.lda + C) * 2u; voffB[i] = (unsigned)(Rb * g.ldb + C) * 2u; }
;     const size_t kstep = (size_t)(BK * 2);
;     const size_t hstepA = (size_t)(AREMAP ? 64 : HALF) * g.lda * 2, hstepB = (size_t)HALF * g.ldb * 2;
;     const size_t tstepA = (size_t)BM * g.lda * 2, tstepB = (size_t)BM * g.ldb * 2;
;     const unsigned ldsw = (unsigned)wid * 1024u;
;     const int aoff = lds_byte(wr * 64 + fr, fq * 8), boff = lds_byte(wc * 32 + fr, fq * 8);
;     ...
;     PG8_STAGE(PG8_SB(0, 0), cB, voffB); PG8_STAGE(PG8_SA(0, 0), cA, voffA); PG8_STAGE(PG8_SB(0, 1), cB + hstepB, voffB); PG8_STAGE(PG8_SA(0, 1), cA + hstepA, voffA);
;     if (wr == 1) PG8_BAR;
;     PG8_WAIT_V(4); PG8_BAR;
;     PG8_STAGE(PG8_SB(1, 0), cB + kstep, voffB); PG8_STAGE(PG8_SA(1, 0), cA + kstep, voffA); PG8_STAGE(PG8_SB(1, 1), cB + hstepB + kstep, voffB);
;     PG8_WAIT_V(6); PG8_BAR;
.LBB0_543:
	v_bfe_u32 v18, v13, 4, 2
	v_and_b32_e32 v19, 15, v13
	v_lshlrev_b32_e32 v20, 4, v18
	v_lshlrev_b32_e32 v13, 2, v13
	v_lshl_or_b32 v249, s0, 6, v19
	v_lshl_or_b32 v19, v19, 6, v20
	s_lshl_b32 s0, s0, 13
	v_and_b32_e32 v13, 32, v13
	v_bitop3_b32 v20, v19, s0, v13 bitop3:0xde
	s_lshl_b32 s0, s1, 5
	s_and_b32 s20, s0, 0x60
	s_add_i32 m0, s29, 0x18000
	v_lshl_add_u64 v[8:9], v[8:9], 0, s[86:87]
	s_lshl_b32 s0, s20, 7
	s_waitcnt vmcnt(4)
	s_barrier
	global_load_lds_dwordx4 v[8:9], off
	v_lshl_add_u64 v[6:7], v[6:7], 0, s[86:87]
	s_add_i32 m0, s29, 0x1a000
	s_add_i32 s57, s29, 0x8000
	s_add_i32 s65, s29, 0xa000
	v_bitop3_b32 v250, v19, s0, v13 bitop3:0xde
	global_load_lds_dwordx4 v[6:7], off
	v_lshl_add_u64 v[4:5], v[4:5], 0, s[86:87]
	s_mov_b32 m0, s57
	s_add_u32 s0, s34, 0x80080
	global_load_lds_dwordx4 v[4:5], off
	v_lshl_add_u64 v[2:3], v[2:3], 0, s[86:87]
	s_mov_b32 m0, s65
	s_addc_u32 s1, s35, 0
	global_load_lds_dwordx4 v[2:3], off
	s_add_i32 m0, s29, 0x1c000
	s_nop 0
	global_load_lds_dwordx4 v196, s[0:1]
	s_add_i32 m0, s29, 0x1e000
	v_lshlrev_b32_e32 v1, 14, v1
	global_load_lds_dwordx4 v198, s[0:1]
	v_lshlrev_b32_e32 v2, 14, v14
	v_and_b32_e32 v2, 0x7fff8000, v2
	v_lshl_add_u32 v2, v15, 11, v2
	v_and_b32_e32 v1, 0x7fff8000, v1
	v_or_b32_e32 v2, v2, v16
	v_lshl_add_u32 v1, v10, 11, v1
	s_waitcnt vmcnt(6)
	s_ashr_i32 s68, s11, 31
	s_ashr_i32 s69, s36, 31
	v_add_lshl_u32 v2, v2, v17, 1
	v_mov_b32_e32 v3, v0
	s_mov_b64 s[0:1], 0x80080
	v_or_b32_e32 v1, v1, v11
	s_cmp_lg_u64 s[12:13], 0
	v_lshl_add_u64 v[200:201], v[2:3], 0, s[0:1]
	v_add_lshl_u32 v2, v1, v12, 1
	s_cselect_b64 s[18:19], -1, 0
	v_lshl_or_b32 v251, v18, 2, s20
	v_lshl_add_u64 v[202:203], v[2:3], 0, s[0:1]
	s_mov_b32 s70, 0
	v_add_u32_e32 v252, 0, v20
	s_barrier
	s_branch .LBB0_545

; #define PG8_STAGE(bufoff, gbase, voff) do { _Pragma("unroll") for (int _i = 0; _i < 2; ++_i) \
;         __builtin_amdgcn_global_load_lds((const unsigned*)((const char*)(gbase) + (voff)[_i]), (LAS unsigned*)(lds + (bufoff) + ldsw + _i * 8192), 16, 0, 0); } while (0)
; #define PG8_LDA(dst, b, h) do { _Pragma("unroll") for (int m = 0; m < 4; ++m) _Pragma("unroll") for (int k = 0; k < 2; ++k) dst[m][k] = *(const LAS bf16x8*)(lds + PG8_SA(b, h) + aoff + m * 2048 + k * 1024); } while (0)
; #define PG8_LDB(dst, b, h) do { _Pragma("unroll") for (int n = 0; n < 2; ++n) _Pragma("unroll") for (int k = 0; k < 2; ++k) dst[n][k] = *(const LAS bf16x8*)(lds + PG8_SB(b, h) + boff + n * 2048 + k * 1024); } while (0)
; #define PG8_MMA(ai, bj, At, Bt) do { __builtin_amdgcn_s_setprio(1); _Pragma("unroll") for (int m = 0; m < 4; ++m) _Pragma("unroll") for (int n = 0; n < 2; ++n) _Pragma("unroll") for (int k = 0; k < 2; ++k) \
;         acc[ai][bj][m][n] = __builtin_amdgcn_mfma_f32_16x16x32_bf16(Bt[n][k], At[m][k], acc[ai][bj][m][n], 0, 0, 0); __builtin_amdgcn_s_setprio(0); } while (0)
; #define PG8_WAIT_L(n) asm volatile("s_waitcnt lgkmcnt(" #n ")" ::: "memory")
; #define PG8_BAR __builtin_amdgcn_s_barrier()
; #define PG8_SCHED __builtin_amdgcn_sched_barrier(0)
; template <class Epi, class Sched, bool AREMAP>
; __device__ __forceinline__ void gemm_phase(LAS unsigned char* lds, const Gemm g, const Sched& S, const Epi& E, int wv) {
;     ...
;             PG8_LDB(B0, 0, 0); PG8_SCHED; PG8_LDA(At, 0, 0); PG8_STAGE(PG8_SA(1, 1), a1 + hstepA, voffA);
;             PG8_WAIT_L(8); PG8_BAR; PG8_WAIT_L(0); PG8_MMA(0, 0, At, B0); PG8_BAR; PG8_SCHED;
;             PG8_LDB(B1, 0, 1); PG8_STAGE(PG8_SB(0, 0), b2, voffB);
;             PG8_BAR; PG8_WAIT_L(0); PG8_MMA(0, 1, At, B1); PG8_BAR;
;             PG8_LDA(At, 0, 1); PG8_STAGE(PG8_SA(0, 0), a2, voffA);
;             PG8_BAR; PG8_WAIT_L(0); PG8_MMA(1, 0, At, B0); PG8_BAR; PG8_SCHED;
.LBB0_552:
	s_add_u32 s34, s2, 0x100
	s_addc_u32 s35, s3, 0
	s_add_i32 s38, 0, 0x10000
	v_add_u32_e32 v1, s38, v250
	ds_read_b128 v[130:133], v1
	ds_read_b128 v[134:137], v1 offset:1024
	ds_read_b128 v[138:141], v1 offset:2048
	ds_read_b128 v[142:145], v1 offset:3072
	s_cmp_eq_u32 s76, 28
	s_cselect_b32 s67, s23, s35
	s_cselect_b32 s66, s72, s34
	s_cselect_b32 s63, s21, s75
	s_cselect_b32 s62, s73, s74
	v_lshl_add_u64 v[178:179], s[2:3], 0, v[202:203]
	s_add_i32 m0, s29, 0xc000
	ds_read_b128 v[146:149], v252
	ds_read_b128 v[150:153], v252 offset:1024
	ds_read_b128 v[154:157], v252 offset:2048
	ds_read_b128 v[158:161], v252 offset:3072
	ds_read_b128 v[162:165], v252 offset:4096
	ds_read_b128 v[166:169], v252 offset:5120
	ds_read_b128 v[170:173], v252 offset:6144
	ds_read_b128 v[174:177], v252 offset:7168
	global_load_lds_dwordx4 v[178:179], off
	v_lshl_add_u64 v[178:179], s[2:3], 0, v[200:201]
	s_add_i32 m0, s29, 0xe000
	s_nop 0
	global_load_lds_dwordx4 v[178:179], off
	s_waitcnt lgkmcnt(8)
	s_barrier
	s_waitcnt lgkmcnt(0)
	s_waitcnt lgkmcnt(0)
	v_mfma_f32_16x16x32_bf16 v[126:129], v[130:133], v[146:149], v[126:129]
	v_mfma_f32_16x16x32_bf16 v[110:113], v[138:141], v[146:149], v[110:113]
	v_mfma_f32_16x16x32_bf16 v[122:125], v[130:133], v[154:157], v[122:125]
	v_mfma_f32_16x16x32_bf16 v[106:109], v[138:141], v[154:157], v[106:109]
	v_mfma_f32_16x16x32_bf16 v[118:121], v[130:133], v[162:165], v[118:121]
	v_mfma_f32_16x16x32_bf16 v[102:105], v[138:141], v[162:165], v[102:105]
	v_mfma_f32_16x16x32_bf16 v[114:117], v[130:133], v[170:173], v[114:117]
	v_mfma_f32_16x16x32_bf16 v[98:101], v[138:141], v[170:173], v[98:101]
	v_mfma_f32_16x16x32_bf16 v[126:129], v[134:137], v[150:153], v[126:129]
	v_mfma_f32_16x16x32_bf16 v[110:113], v[142:145], v[150:153], v[110:113]
	v_mfma_f32_16x16x32_bf16 v[122:125], v[134:137], v[158:161], v[122:125]
	v_mfma_f32_16x16x32_bf16 v[106:109], v[142:145], v[158:161], v[106:109]
	v_mfma_f32_16x16x32_bf16 v[118:121], v[134:137], v[166:169], v[118:121]
	v_mfma_f32_16x16x32_bf16 v[102:105], v[142:145], v[166:169], v[102:105]
	v_mfma_f32_16x16x32_bf16 v[114:117], v[134:137], v[174:177], v[114:117]
	v_mfma_f32_16x16x32_bf16 v[98:101], v[142:145], v[174:177], v[98:101]
	s_barrier
	s_add_i32 s39, 0, 0x14000
	s_add_i32 s2, s38, s53
	v_add_u32_e32 v1, s39, v250
	v_lshl_add_u64 v[186:187], s[62:63], 0, v[196:197]
	s_mov_b32 m0, s2
	ds_read_b128 v[178:181], v1
	ds_read_b128 v[182:185], v1 offset:1024
	ds_read_b128 v[192:195], v1 offset:2048
	ds_read_b128 v[204:207], v1 offset:3072
	global_load_lds_dwordx4 v[186:187], off
	v_lshl_add_u64 v[208:209], s[62:63], 0, v[198:199]
	s_add_i32 m0, s2, 0x2000
	s_nop 0
	global_load_lds_dwordx4 v[208:209], off
	s_barrier
	s_waitcnt lgkmcnt(0)
	s_waitcnt lgkmcnt(0)
	v_mfma_f32_16x16x32_bf16 v[94:97], v[178:181], v[146:149], v[94:97]
	v_mfma_f32_16x16x32_bf16 v[78:81], v[192:195], v[146:149], v[78:81]
	v_mfma_f32_16x16x32_bf16 v[90:93], v[178:181], v[154:157], v[90:93]
	v_mfma_f32_16x16x32_bf16 v[74:77], v[192:195], v[154:157], v[74:77]
	v_mfma_f32_16x16x32_bf16 v[86:89], v[178:181], v[162:165], v[86:89]
	v_mfma_f32_16x16x32_bf16 v[70:73], v[192:195], v[162:165], v[70:73]
	v_mfma_f32_16x16x32_bf16 v[82:85], v[178:181], v[170:173], v[82:85]
	v_mfma_f32_16x16x32_bf16 v[66:69], v[192:195], v[170:173], v[66:69]
	v_mfma_f32_16x16x32_bf16 v[94:97], v[182:185], v[150:153], v[94:97]
	v_mfma_f32_16x16x32_bf16 v[78:81], v[204:207], v[150:153], v[78:81]
	v_mfma_f32_16x16x32_bf16 v[90:93], v[182:185], v[158:161], v[90:93]
	v_mfma_f32_16x16x32_bf16 v[74:77], v[204:207], v[158:161], v[74:77]
	v_mfma_f32_16x16x32_bf16 v[86:89], v[182:185], v[166:169], v[86:89]
	v_mfma_f32_16x16x32_bf16 v[70:73], v[204:207], v[166:169], v[70:73]
	v_mfma_f32_16x16x32_bf16 v[82:85], v[182:185], v[174:177], v[82:85]
	v_mfma_f32_16x16x32_bf16 v[66:69], v[204:207], v[174:177], v[66:69]
	s_mov_b32 m0, s29
	v_lshl_add_u64 v[210:211], s[66:67], 0, v[196:197]
	s_barrier
	ds_read_b128 v[146:149], v252 offset:16384
	ds_read_b128 v[150:153], v252 offset:17408
	ds_read_b128 v[154:157], v252 offset:18432
	ds_read_b128 v[158:161], v252 offset:19456
	ds_read_b128 v[162:165], v252 offset:20480
	ds_read_b128 v[166:169], v252 offset:21504
	ds_read_b128 v[170:173], v252 offset:22528
	ds_read_b128 v[174:177], v252 offset:23552
	global_load_lds_dwordx4 v[210:211], off
	v_lshl_add_u64 v[212:213], s[66:67], 0, v[198:199]
	s_mov_b32 m0, s31
	s_nop 0
	global_load_lds_dwordx4 v[212:213], off
	s_barrier
	s_waitcnt lgkmcnt(0)
	s_waitcnt lgkmcnt(0)
	v_mfma_f32_16x16x32_bf16 v[62:65], v[130:133], v[146:149], v[62:65]
	v_mfma_f32_16x16x32_bf16 v[46:49], v[138:141], v[146:149], v[46:49]
	v_mfma_f32_16x16x32_bf16 v[58:61], v[130:133], v[154:157], v[58:61]
	v_mfma_f32_16x16x32_bf16 v[42:45], v[138:141], v[154:157], v[42:45]
	v_mfma_f32_16x16x32_bf16 v[54:57], v[130:133], v[162:165], v[54:57]
	v_mfma_f32_16x16x32_bf16 v[38:41], v[138:141], v[162:165], v[38:41]
	v_mfma_f32_16x16x32_bf16 v[50:53], v[130:133], v[170:173], v[50:53]
	v_mfma_f32_16x16x32_bf16 v[34:37], v[138:141], v[170:173], v[34:37]
	v_mfma_f32_16x16x32_bf16 v[62:65], v[134:137], v[150:153], v[62:65]
	v_mfma_f32_16x16x32_bf16 v[46:49], v[142:145], v[150:153], v[46:49]
	v_mfma_f32_16x16x32_bf16 v[58:61], v[134:137], v[158:161], v[58:61]
	v_mfma_f32_16x16x32_bf16 v[42:45], v[142:145], v[158:161], v[42:45]
	v_mfma_f32_16x16x32_bf16 v[54:57], v[134:137], v[166:169], v[54:57]
	v_mfma_f32_16x16x32_bf16 v[38:41], v[142:145], v[166:169], v[38:41]
	v_mfma_f32_16x16x32_bf16 v[50:53], v[134:137], v[174:177], v[50:53]
	v_mfma_f32_16x16x32_bf16 v[34:37], v[142:145], v[174:177], v[34:37]
	s_barrier
; #define PG8_STAGE(bufoff, gbase, voff) do { _Pragma("unroll") for (int _i = 0; _i < 2; ++_i) \
;         __builtin_amdgcn_global_load_lds((const unsigned*)((const char*)(gbase) + (voff)[_i]), (LAS unsigned*)(lds + (bufoff) + ldsw + _i * 8192), 16, 0, 0); } while (0)
; #define PG8_LDA(dst, b, h) do { _Pragma("unroll") for (int m = 0; m < 4; ++m) _Pragma("unroll") for (int k = 0; k < 2; ++k) dst[m][k] = *(const LAS bf16x8*)(lds + PG8_SA(b, h) + aoff + m * 2048 + k * 1024); } while (0)
; #define PG8_LDB(dst, b, h) do { _Pragma("unroll") for (int n = 0; n < 2; ++n) _Pragma("unroll") for (int k = 0; k < 2; ++k) dst[n][k] = *(const LAS bf16x8*)(lds + PG8_SB(b, h) + boff + n * 2048 + k * 1024); } while (0)
; #define PG8_MMA(ai, bj, At, Bt) do { __builtin_amdgcn_s_setprio(1); _Pragma("unroll") for (int m = 0; m < 4; ++m) _Pragma("unroll") for (int n = 0; n < 2; ++n) _Pragma("unroll") for (int k = 0; k < 2; ++k) \
;         acc[ai][bj][m][n] = __builtin_amdgcn_mfma_f32_16x16x32_bf16(Bt[n][k], At[m][k], acc[ai][bj][m][n], 0, 0, 0); __builtin_amdgcn_s_setprio(0); } while (0)
; #define PG8_WAIT_V(n) asm volatile("s_waitcnt vmcnt(" #n ")" ::: "memory")
; #define PG8_WAIT_L(n) asm volatile("s_waitcnt lgkmcnt(" #n ")" ::: "memory")
; #define PG8_BAR __builtin_amdgcn_s_barrier()
; #define PG8_SCHED __builtin_amdgcn_sched_barrier(0)
; template <class Epi, class Sched, bool AREMAP>
; __device__ __forceinline__ void gemm_phase(LAS unsigned char* lds, const Gemm g, const Sched& S, const Epi& E, int wv) {
;     ...
;             PG8_STAGE(PG8_SB(0, 1), b2 + hstepB, voffB);
;             PG8_WAIT_V(6); PG8_BAR; PG8_MMA(1, 1, At, B1); PG8_BAR;
;             PG8_LDB(B0, 1, 0); PG8_SCHED; PG8_LDA(At, 1, 0); PG8_STAGE(PG8_SA(0, 1), a2 + hstepA, voffA);
;             PG8_WAIT_L(8); PG8_BAR; PG8_WAIT_L(0); PG8_MMA(0, 0, At, B0); PG8_BAR; PG8_SCHED;
;             PG8_LDB(B1, 1, 1); PG8_STAGE(PG8_SB(1, 0), b3, voffB);
;             PG8_BAR; PG8_WAIT_L(0); PG8_MMA(0, 1, At, B1); PG8_BAR;
;             PG8_LDA(At, 1, 1); PG8_STAGE(PG8_SA(1, 0), a3, voffA);
	s_add_u32 s2, s62, 0x80000
	s_addc_u32 s3, s63, 0
	s_add_i32 s38, s39, s53
	s_mov_b32 m0, s38
	s_nop 0
	global_load_lds_dwordx4 v196, s[2:3]
	s_add_i32 m0, s38, 0x2000
	s_nop 0
	global_load_lds_dwordx4 v198, s[2:3]
	s_waitcnt vmcnt(6)
	s_barrier
	v_mfma_f32_16x16x32_bf16 v[30:33], v[178:181], v[146:149], v[30:33]
	v_mfma_f32_16x16x32_bf16 v[14:17], v[192:195], v[146:149], v[14:17]
	v_mfma_f32_16x16x32_bf16 v[26:29], v[178:181], v[154:157], v[26:29]
	v_mfma_f32_16x16x32_bf16 v[10:13], v[192:195], v[154:157], v[10:13]
	v_mfma_f32_16x16x32_bf16 v[22:25], v[178:181], v[162:165], v[22:25]
	v_mfma_f32_16x16x32_bf16 v[6:9], v[192:195], v[162:165], v[6:9]
	v_mfma_f32_16x16x32_bf16 v[18:21], v[178:181], v[170:173], v[18:21]
	v_mfma_f32_16x16x32_bf16 v[2:5], v[192:195], v[170:173], v[2:5]
	v_mfma_f32_16x16x32_bf16 v[30:33], v[182:185], v[150:153], v[30:33]
	v_mfma_f32_16x16x32_bf16 v[14:17], v[204:207], v[150:153], v[14:17]
	v_mfma_f32_16x16x32_bf16 v[26:29], v[182:185], v[158:161], v[26:29]
	v_mfma_f32_16x16x32_bf16 v[10:13], v[204:207], v[158:161], v[10:13]
	v_mfma_f32_16x16x32_bf16 v[22:25], v[182:185], v[166:169], v[22:25]
	v_mfma_f32_16x16x32_bf16 v[6:9], v[204:207], v[166:169], v[6:9]
	v_mfma_f32_16x16x32_bf16 v[18:21], v[182:185], v[174:177], v[18:21]
	v_mfma_f32_16x16x32_bf16 v[2:5], v[204:207], v[174:177], v[2:5]
	s_add_i32 s38, 0, 0x18000
	v_add_u32_e32 v1, s38, v250
	s_barrier
	ds_read_b128 v[130:133], v1
	ds_read_b128 v[134:137], v1 offset:1024
	ds_read_b128 v[138:141], v1 offset:2048
	ds_read_b128 v[142:145], v1 offset:3072
	s_add_u32 s2, s66, 0x80000
	s_addc_u32 s3, s67, 0
	s_mov_b32 m0, s55
	ds_read_b128 v[146:149], v252 offset:32768
	ds_read_b128 v[150:153], v252 offset:33792
	ds_read_b128 v[154:157], v252 offset:34816
	ds_read_b128 v[158:161], v252 offset:35840
	ds_read_b128 v[162:165], v252 offset:36864
	ds_read_b128 v[166:169], v252 offset:37888
	ds_read_b128 v[170:173], v252 offset:38912
	ds_read_b128 v[174:177], v252 offset:39936
	global_load_lds_dwordx4 v196, s[2:3]
	s_mov_b32 m0, s56
	s_nop 0
	global_load_lds_dwordx4 v198, s[2:3]
	s_waitcnt lgkmcnt(8)
	s_barrier
	s_waitcnt lgkmcnt(0)
	s_waitcnt lgkmcnt(0)
	v_mfma_f32_16x16x32_bf16 v[126:129], v[130:133], v[146:149], v[126:129]
	v_mfma_f32_16x16x32_bf16 v[110:113], v[138:141], v[146:149], v[110:113]
	v_mfma_f32_16x16x32_bf16 v[122:125], v[130:133], v[154:157], v[122:125]
	v_mfma_f32_16x16x32_bf16 v[106:109], v[138:141], v[154:157], v[106:109]
	v_mfma_f32_16x16x32_bf16 v[118:121], v[130:133], v[162:165], v[118:121]
	v_mfma_f32_16x16x32_bf16 v[102:105], v[138:141], v[162:165], v[102:105]
	v_mfma_f32_16x16x32_bf16 v[114:117], v[130:133], v[170:173], v[114:117]
	v_mfma_f32_16x16x32_bf16 v[98:101], v[138:141], v[170:173], v[98:101]
	v_mfma_f32_16x16x32_bf16 v[126:129], v[134:137], v[150:153], v[126:129]
	v_mfma_f32_16x16x32_bf16 v[110:113], v[142:145], v[150:153], v[110:113]
	v_mfma_f32_16x16x32_bf16 v[122:125], v[134:137], v[158:161], v[122:125]
	v_mfma_f32_16x16x32_bf16 v[106:109], v[142:145], v[158:161], v[106:109]
	v_mfma_f32_16x16x32_bf16 v[118:121], v[134:137], v[166:169], v[118:121]
	v_mfma_f32_16x16x32_bf16 v[102:105], v[142:145], v[166:169], v[102:105]
	v_mfma_f32_16x16x32_bf16 v[114:117], v[134:137], v[174:177], v[114:117]
	v_mfma_f32_16x16x32_bf16 v[98:101], v[142:145], v[174:177], v[98:101]
	s_barrier
	s_add_i32 s39, 0, 0x1c000
	s_add_i32 s2, s38, s53
	v_add_u32_e32 v1, s39, v250
	v_lshl_add_u64 v[186:187], v[186:187], 0, s[86:87]
	s_mov_b32 m0, s2
	ds_read_b128 v[178:181], v1
	ds_read_b128 v[182:185], v1 offset:1024
	ds_read_b128 v[192:195], v1 offset:2048
	ds_read_b128 v[204:207], v1 offset:3072
	global_load_lds_dwordx4 v[186:187], off
	v_lshl_add_u64 v[186:187], v[208:209], 0, s[86:87]
	s_add_i32 m0, s2, 0x2000
	s_nop 0
	global_load_lds_dwordx4 v[186:187], off
	s_barrier
; #define PG8_STAGE(bufoff, gbase, voff) do { _Pragma("unroll") for (int _i = 0; _i < 2; ++_i) \
;         __builtin_amdgcn_global_load_lds((const unsigned*)((const char*)(gbase) + (voff)[_i]), (LAS unsigned*)(lds + (bufoff) + ldsw + _i * 8192), 16, 0, 0); } while (0)
; #define PG8_LDA(dst, b, h) do { _Pragma("unroll") for (int m = 0; m < 4; ++m) _Pragma("unroll") for (int k = 0; k < 2; ++k) dst[m][k] = *(const LAS bf16x8*)(lds + PG8_SA(b, h) + aoff + m * 2048 + k * 1024); } while (0)
; #define PG8_MMA(ai, bj, At, Bt) do { __builtin_amdgcn_s_setprio(1); _Pragma("unroll") for (int m = 0; m < 4; ++m) _Pragma("unroll") for (int n = 0; n < 2; ++n) _Pragma("unroll") for (int k = 0; k < 2; ++k) \
;         acc[ai][bj][m][n] = __builtin_amdgcn_mfma_f32_16x16x32_bf16(Bt[n][k], At[m][k], acc[ai][bj][m][n], 0, 0, 0); __builtin_amdgcn_s_setprio(0); } while (0)
; #define PG8_WAIT_V(n) asm volatile("s_waitcnt vmcnt(" #n ")" ::: "memory")
; #define PG8_WAIT_L(n) asm volatile("s_waitcnt lgkmcnt(" #n ")" ::: "memory")
; #define PG8_BAR __builtin_amdgcn_s_barrier()
; #define PG8_SCHED __builtin_amdgcn_sched_barrier(0)
; template <class Epi, class Sched, bool AREMAP>
; __device__ __forceinline__ void gemm_phase(LAS unsigned char* lds, const Gemm g, const Sched& S, const Epi& E, int wv) {
;     ...
;             PG8_BAR; PG8_WAIT_L(0); PG8_MMA(0, 1, At, B1); PG8_BAR;
;             PG8_LDA(At, 1, 1); PG8_STAGE(PG8_SA(1, 0), a3, voffA);
;             PG8_BAR; PG8_WAIT_L(0); PG8_MMA(1, 0, At, B0); PG8_BAR; PG8_SCHED;
;             PG8_STAGE(PG8_SB(1, 1), b3 + hstepB, voffB);
;             PG8_WAIT_V(6); PG8_BAR; PG8_MMA(1, 1, At, B1); PG8_BAR;
;     __device__ __forceinline__ void operator()(const f32x4 (&acc)[2][2][4][2], const Unit& u, int wr, int wc, int fr, int fq) const {
;         const int row0 = u.pm * BM + wr * 64 + fr, col0 = u.pn * BM + wc * 32 + 4 * fq;
;         const float* gv = gate + (size_t)(u.pm >> 3) * 12288 + col0;
; #pragma unroll
;         for (int ai = 0; ai < 2; ++ai) {
;             float mu[4], rs[4];
; #pragma unroll
;             for (int m = 0; m < 4; ++m) { mu[m] = 0.f; rs[m] = 1.f;
;                 if (stats) { const float* sp = stats + (size_t)(row0 + ai * HALF + m * 16) * 2; mu[m] = sp[0]; rs[m] = sp[1]; } }
	s_waitcnt lgkmcnt(0)
	s_waitcnt lgkmcnt(0)
	v_mfma_f32_16x16x32_bf16 v[94:97], v[178:181], v[146:149], v[94:97]
	v_mfma_f32_16x16x32_bf16 v[78:81], v[192:195], v[146:149], v[78:81]
	v_mfma_f32_16x16x32_bf16 v[90:93], v[178:181], v[154:157], v[90:93]
	v_mfma_f32_16x16x32_bf16 v[74:77], v[192:195], v[154:157], v[74:77]
	v_mfma_f32_16x16x32_bf16 v[86:89], v[178:181], v[162:165], v[86:89]
	v_mfma_f32_16x16x32_bf16 v[70:73], v[192:195], v[162:165], v[70:73]
	v_mfma_f32_16x16x32_bf16 v[82:85], v[178:181], v[170:173], v[82:85]
	v_mfma_f32_16x16x32_bf16 v[66:69], v[192:195], v[170:173], v[66:69]
	v_mfma_f32_16x16x32_bf16 v[94:97], v[182:185], v[150:153], v[94:97]
	v_mfma_f32_16x16x32_bf16 v[78:81], v[204:207], v[150:153], v[78:81]
	v_mfma_f32_16x16x32_bf16 v[90:93], v[182:185], v[158:161], v[90:93]
	v_mfma_f32_16x16x32_bf16 v[74:77], v[204:207], v[158:161], v[74:77]
	v_mfma_f32_16x16x32_bf16 v[86:89], v[182:185], v[166:169], v[86:89]
	v_mfma_f32_16x16x32_bf16 v[70:73], v[204:207], v[166:169], v[70:73]
	v_mfma_f32_16x16x32_bf16 v[82:85], v[182:185], v[174:177], v[82:85]
	v_mfma_f32_16x16x32_bf16 v[66:69], v[204:207], v[174:177], v[66:69]
	s_mov_b32 m0, s57
	v_lshl_add_u64 v[186:187], v[210:211], 0, s[86:87]
	s_barrier
	ds_read_b128 v[146:149], v252 offset:49152
	ds_read_b128 v[150:153], v252 offset:50176
	ds_read_b128 v[154:157], v252 offset:51200
	ds_read_b128 v[158:161], v252 offset:52224
	ds_read_b128 v[162:165], v252 offset:53248
	ds_read_b128 v[166:169], v252 offset:54272
	ds_read_b128 v[170:173], v252 offset:55296
	ds_read_b128 v[174:177], v252 offset:56320
	global_load_lds_dwordx4 v[186:187], off
	v_lshl_add_u64 v[186:187], v[212:213], 0, s[86:87]
	s_mov_b32 m0, s65
	s_nop 0
	global_load_lds_dwordx4 v[186:187], off
	s_barrier
	s_waitcnt lgkmcnt(0)
	s_waitcnt lgkmcnt(0)
	v_mfma_f32_16x16x32_bf16 v[62:65], v[130:133], v[146:149], v[62:65]
	v_mfma_f32_16x16x32_bf16 v[46:49], v[138:141], v[146:149], v[46:49]
	v_mfma_f32_16x16x32_bf16 v[58:61], v[130:133], v[154:157], v[58:61]
	v_mfma_f32_16x16x32_bf16 v[42:45], v[138:141], v[154:157], v[42:45]
	v_mfma_f32_16x16x32_bf16 v[54:57], v[130:133], v[162:165], v[54:57]
	v_mfma_f32_16x16x32_bf16 v[38:41], v[138:141], v[162:165], v[38:41]
	v_mfma_f32_16x16x32_bf16 v[50:53], v[130:133], v[170:173], v[50:53]
	v_mfma_f32_16x16x32_bf16 v[34:37], v[138:141], v[170:173], v[34:37]
	v_mfma_f32_16x16x32_bf16 v[62:65], v[134:137], v[150:153], v[62:65]
	v_mfma_f32_16x16x32_bf16 v[46:49], v[142:145], v[150:153], v[46:49]
	v_mfma_f32_16x16x32_bf16 v[58:61], v[134:137], v[158:161], v[58:61]
	v_mfma_f32_16x16x32_bf16 v[42:45], v[142:145], v[158:161], v[42:45]
	v_mfma_f32_16x16x32_bf16 v[54:57], v[134:137], v[166:169], v[54:57]
	v_mfma_f32_16x16x32_bf16 v[38:41], v[142:145], v[166:169], v[38:41]
	v_mfma_f32_16x16x32_bf16 v[50:53], v[134:137], v[174:177], v[50:53]
	v_mfma_f32_16x16x32_bf16 v[34:37], v[142:145], v[174:177], v[34:37]
	s_barrier
	s_add_u32 s2, s62, 0x80080
	s_addc_u32 s3, s63, 0
	s_add_i32 s38, s39, s53
	s_mov_b32 m0, s38
	s_nop 0
	global_load_lds_dwordx4 v196, s[2:3]
	s_add_i32 m0, s38, 0x2000
	s_nop 0
	global_load_lds_dwordx4 v198, s[2:3]
	s_waitcnt vmcnt(6)
	s_barrier
	v_mfma_f32_16x16x32_bf16 v[30:33], v[178:181], v[146:149], v[30:33]
	v_mfma_f32_16x16x32_bf16 v[14:17], v[192:195], v[146:149], v[14:17]
	v_mfma_f32_16x16x32_bf16 v[26:29], v[178:181], v[154:157], v[26:29]
	v_mfma_f32_16x16x32_bf16 v[10:13], v[192:195], v[154:157], v[10:13]
	v_mfma_f32_16x16x32_bf16 v[22:25], v[178:181], v[162:165], v[22:25]
	v_mfma_f32_16x16x32_bf16 v[6:9], v[192:195], v[162:165], v[6:9]
	v_mfma_f32_16x16x32_bf16 v[18:21], v[178:181], v[170:173], v[18:21]
	v_mfma_f32_16x16x32_bf16 v[2:5], v[192:195], v[170:173], v[2:5]
	v_mfma_f32_16x16x32_bf16 v[30:33], v[182:185], v[150:153], v[30:33]
	v_mfma_f32_16x16x32_bf16 v[14:17], v[204:207], v[150:153], v[14:17]
	v_mfma_f32_16x16x32_bf16 v[26:29], v[182:185], v[158:161], v[26:29]
	v_mfma_f32_16x16x32_bf16 v[10:13], v[204:207], v[158:161], v[10:13]
	v_mfma_f32_16x16x32_bf16 v[22:25], v[182:185], v[166:169], v[22:25]
	v_mfma_f32_16x16x32_bf16 v[6:9], v[204:207], v[166:169], v[6:9]
	v_mfma_f32_16x16x32_bf16 v[18:21], v[182:185], v[174:177], v[18:21]
	v_mfma_f32_16x16x32_bf16 v[2:5], v[204:207], v[174:177], v[2:5]
	s_add_i32 s76, s76, 2
	s_add_u32 s74, s74, 0x100
	s_addc_u32 s75, s75, 0
	s_cmp_gt_u32 s76, 29
	s_mov_b64 s[2:3], s[34:35]
	s_barrier
	s_cbranch_scc0 .LBB0_552
	v_lshl_add_u32 v212, s28, 8, v249
	v_cndmask_b32_e64 v1, 0, 1, s[18:19]
	v_mov_b32_e32 v216, 1.0
	v_cmp_ne_u32_e64 s[2:3], 1, v1
	s_andn2_b64 vcc, exec, s[18:19]
	v_ashrrev_i32_e32 v213, 31, v212
	s_cbranch_vccnz .LBB0_556
	v_lshl_add_u64 v[130:131], v[212:213], 3, s[12:13]
	global_load_dwordx2 v[134:135], v[130:131], off
	v_or_b32_e32 v140, 16, v212
	s_and_b64 vcc, exec, s[2:3]
	v_ashrrev_i32_e32 v141, 31, v140
	s_cbranch_vccnz .LBB0_557

; #define PG8_STAGE(bufoff, gbase, voff) do { _Pragma("unroll") for (int _i = 0; _i < 2; ++_i) \
;         __builtin_amdgcn_global_load_lds((const unsigned*)((const char*)(gbase) + (voff)[_i]), (LAS unsigned*)(lds + (bufoff) + ldsw + _i * 8192), 16, 0, 0); } while (0)
; #define PG8_WAIT_V(n) asm volatile("s_waitcnt vmcnt(" #n ")" ::: "memory")
; #define PG8_BAR __builtin_amdgcn_s_barrier()
; template <class Epi, class Sched, bool AREMAP>
; __device__ __forceinline__ void gemm_phase(LAS unsigned char* lds, const Gemm g, const Sched& S, const Epi& E, int wv) {
;     ...
;     PG8_STAGE(PG8_SB(0, 0), cB, voffB); PG8_STAGE(PG8_SA(0, 0), cA, voffA); PG8_STAGE(PG8_SB(0, 1), cB + hstepB, voffB); PG8_STAGE(PG8_SA(0, 1), cA + hstepA, voffA);
;     if (wr == 1) PG8_BAR;
;     PG8_WAIT_V(4); PG8_BAR;
;     PG8_STAGE(PG8_SB(1, 0), cB + kstep, voffB); PG8_STAGE(PG8_SA(1, 0), cA + kstep, voffA); PG8_STAGE(PG8_SB(1, 1), cB + hstepB + kstep, voffB);
;     PG8_WAIT_V(6); PG8_BAR;
;     __device__ __forceinline__ void operator()(const f32x4 (&acc)[2][2][4][2], const Unit& u, int wr, int wc, int fr, int fq) const {
;         const int lane = fq * 16 + fr;
;         const int ch0 = u.pn * 128 + wc * 32 + 8 * fq;
;         const int seg = u.pm * 2 + wr, tok0 = seg * 128 + fr;
;         const int src1 = (lane & 48) | ((fr + 15) & 15), src2 = (lane & 48) | ((fr + 14) & 15);
.LBB0_614:
	s_add_u32 s20, s0, 0x10e00000
	s_addc_u32 s21, s1, 0
	s_add_u32 s22, s0, 0x30e00000
	s_addc_u32 s23, s1, 0
	s_lshl_b32 s0, s3, 5
	s_and_b32 s8, s0, 0x60
	s_add_i32 m0, s10, 0x18000
	v_lshl_add_u64 v[8:9], v[8:9], 0, s[86:87]
	s_lshl_b32 s4, s75, 13
	s_lshl_b32 s3, s8, 7
	s_waitcnt vmcnt(4)
	s_barrier
	global_load_lds_dwordx4 v[8:9], off
	v_lshl_add_u64 v[6:7], v[6:7], 0, s[86:87]
	s_add_i32 m0, s10, 0x1a000
	s_add_i32 s14, s10, 0x8000
	s_add_i32 s15, s10, 0xa000
	global_load_lds_dwordx4 v[6:7], off
	v_lshl_add_u64 v[4:5], v[4:5], 0, s[86:87]
	s_mov_b32 m0, s14
	s_add_u32 s0, s78, 0x80080
	global_load_lds_dwordx4 v[4:5], off
	v_lshl_add_u64 v[2:3], v[2:3], 0, s[86:87]
	s_mov_b32 m0, s15
	s_addc_u32 s1, s79, 0
	global_load_lds_dwordx4 v[2:3], off
	s_add_i32 m0, s10, 0x1c000
	s_nop 0
	global_load_lds_dwordx4 v158, s[0:1]
	s_add_i32 m0, s10, 0x1e000
	v_and_b32_e32 v162, 15, v11
	global_load_lds_dwordx4 v154, s[0:1]
	v_bfe_u32 v2, v11, 4, 2
	v_lshlrev_b32_e32 v3, 4, v2
	v_lshlrev_b32_e32 v4, 2, v11
	s_ashr_i32 s36, s52, 31
	v_lshl_or_b32 v1, v162, 6, v3
	v_and_b32_e32 v4, 32, v4
	s_add_u32 s24, s18, 0x5800
	v_bitop3_b32 v5, v1, s4, v4 bitop3:0xde
	v_bitop3_b32 v1, v1, s3, v4 bitop3:0xde
	v_add_u32_e32 v4, -1, v11
	s_addc_u32 s25, s19, 0
	v_and_or_b32 v4, v4, 15, v3
	v_add_u32_e32 v6, 14, v11
	s_add_u32 s26, s18, 0xb000
	v_and_or_b32 v3, v6, 15, v3
	v_lshlrev_b32_e32 v180, 2, v4
	s_addc_u32 s27, s19, 0
	v_lshl_or_b32 v182, v2, 3, s8
	v_lshlrev_b32_e32 v2, 12, v12
	v_and_b32_e32 v4, 1, v10
	v_lshlrev_b32_e32 v181, 2, v3
	s_add_u32 s28, s18, 0x10800
	v_and_b32_e32 v2, 0xfff80000, v2
	v_lshlrev_b32_e32 v3, 12, v14
	v_lshlrev_b32_e32 v4, 6, v4
	s_addc_u32 s29, s19, 0
	v_or3_b32 v2, v2, v3, v4
	s_add_u32 s30, s18, 0x16000
	v_lshl_add_u32 v166, v13, 1, v2
	v_lshlrev_b32_e32 v2, 12, v16
	v_and_b32_e32 v4, 1, v15
	s_waitcnt vmcnt(6)
	s_addc_u32 s31, s19, 0
	v_and_b32_e32 v2, 0xfff80000, v2
	v_lshlrev_b32_e32 v3, 12, v18
	v_lshlrev_b32_e32 v4, 6, v4
	s_add_u32 s34, s18, 0x1b800
	v_or3_b32 v2, v2, v3, v4
	s_sext_i32_i16 s37, s2
	s_mov_b32 s41, 0
	v_cmp_eq_u32_e64 s[0:1], 0, v162
	v_cmp_lt_u32_e64 s[2:3], 1, v162
	v_cmp_gt_u32_e64 s[4:5], 2, v162
	v_cmp_lt_u32_e64 s[6:7], 13, v162
	v_mov_b32_e32 v163, v0
	v_add_u32_e32 v164, -12, v162
	v_mov_b32_e32 v165, v0
	s_addc_u32 s35, s19, 0
	v_mov_b32_e32 v167, v0
	v_lshl_add_u32 v168, v17, 1, v2
	v_mov_b32_e32 v169, v0
	v_add_u32_e32 v183, 0, v5
	s_barrier
	s_branch .LBB0_616

; #define PG8_STAGE(bufoff, gbase, voff) do { _Pragma("unroll") for (int _i = 0; _i < 2; ++_i) \
;         __builtin_amdgcn_global_load_lds((const unsigned*)((const char*)(gbase) + (voff)[_i]), (LAS unsigned*)(lds + (bufoff) + ldsw + _i * 8192), 16, 0, 0); } while (0)
; #define PG8_LDA(dst, b, h) do { _Pragma("unroll") for (int m = 0; m < 4; ++m) _Pragma("unroll") for (int k = 0; k < 2; ++k) dst[m][k] = *(const LAS bf16x8*)(lds + PG8_SA(b, h) + aoff + m * 2048 + k * 1024); } while (0)
; #define PG8_LDB(dst, b, h) do { _Pragma("unroll") for (int n = 0; n < 2; ++n) _Pragma("unroll") for (int k = 0; k < 2; ++k) dst[n][k] = *(const LAS bf16x8*)(lds + PG8_SB(b, h) + boff + n * 2048 + k * 1024); } while (0)
; #define PG8_MMA(ai, bj, At, Bt) do { __builtin_amdgcn_s_setprio(1); _Pragma("unroll") for (int m = 0; m < 4; ++m) _Pragma("unroll") for (int n = 0; n < 2; ++n) _Pragma("unroll") for (int k = 0; k < 2; ++k) \
;         acc[ai][bj][m][n] = __builtin_amdgcn_mfma_f32_16x16x32_bf16(Bt[n][k], At[m][k], acc[ai][bj][m][n], 0, 0, 0); __builtin_amdgcn_s_setprio(0); } while (0)
; #define PG8_WAIT_L(n) asm volatile("s_waitcnt lgkmcnt(" #n ")" ::: "memory")
; #define PG8_BAR __builtin_amdgcn_s_barrier()
; #define PG8_SCHED __builtin_amdgcn_sched_barrier(0)
; template <class Epi, class Sched, bool AREMAP>
; __device__ __forceinline__ void gemm_phase(LAS unsigned char* lds, const Gemm g, const Sched& S, const Epi& E, int wv) {
;     ...
;             PG8_LDB(B0, 0, 0); PG8_SCHED; PG8_LDA(At, 0, 0); PG8_STAGE(PG8_SA(1, 1), a1 + hstepA, voffA);
;             PG8_WAIT_L(8); PG8_BAR; PG8_WAIT_L(0); PG8_MMA(0, 0, At, B0); PG8_BAR; PG8_SCHED;
;             PG8_LDB(B1, 0, 1); PG8_STAGE(PG8_SB(0, 0), b2, voffB);
;             PG8_BAR; PG8_WAIT_L(0); PG8_MMA(0, 1, At, B1); PG8_BAR;
;             PG8_LDA(At, 0, 1); PG8_STAGE(PG8_SA(0, 0), a2, voffA);
;             PG8_BAR; PG8_WAIT_L(0); PG8_MMA(1, 0, At, B0); PG8_BAR; PG8_SCHED;
.LBB0_619:
	s_add_u32 s38, s78, 0xfffc0080
	s_addc_u32 s39, s79, -1
	s_add_i32 s33, 0, 0x10000
	v_add_u32_e32 v142, s33, v1
	ds_read_b128 v[130:133], v142
	ds_read_b128 v[134:137], v142 offset:1024
	ds_read_b128 v[138:141], v142 offset:2048
	ds_read_b128 v[142:145], v142 offset:3072
	s_cmp_eq_u32 vcc_hi, 28
	s_cselect_b32 s97, s46, s39
	s_cselect_b32 s96, s47, s38
	s_cselect_b32 s81, s63, vcc_lo
	s_cselect_b32 s80, s67, s77
	s_add_i32 m0, s10, 0xc000
	ds_read_b128 v[146:149], v183
	ds_read_b128 v[150:153], v183 offset:1024
	ds_read_b128 v[170:173], v183 offset:2048
	ds_read_b128 v[174:177], v183 offset:3072
	ds_read_b128 v[184:187], v183 offset:4096
	ds_read_b128 v[192:195], v183 offset:5120
	ds_read_b128 v[196:199], v183 offset:6144
	ds_read_b128 v[200:203], v183 offset:7168
	global_load_lds_dwordx4 v168, s[78:79]
	s_add_i32 m0, s10, 0xe000
	s_nop 0
	global_load_lds_dwordx4 v166, s[78:79]
	s_waitcnt lgkmcnt(8)
	s_barrier
	s_waitcnt lgkmcnt(0)
	s_waitcnt lgkmcnt(0)
	v_mfma_f32_16x16x32_bf16 v[126:129], v[130:133], v[146:149], v[126:129]
	v_mfma_f32_16x16x32_bf16 v[62:65], v[138:141], v[146:149], v[62:65]
	v_mfma_f32_16x16x32_bf16 v[118:121], v[130:133], v[170:173], v[118:121]
	v_mfma_f32_16x16x32_bf16 v[54:57], v[138:141], v[170:173], v[54:57]
	v_mfma_f32_16x16x32_bf16 v[110:113], v[130:133], v[184:187], v[110:113]
	v_mfma_f32_16x16x32_bf16 v[46:49], v[138:141], v[184:187], v[46:49]
	v_mfma_f32_16x16x32_bf16 v[102:105], v[130:133], v[196:199], v[102:105]
	v_mfma_f32_16x16x32_bf16 v[38:41], v[138:141], v[196:199], v[38:41]
	v_mfma_f32_16x16x32_bf16 v[126:129], v[134:137], v[150:153], v[126:129]
	v_mfma_f32_16x16x32_bf16 v[62:65], v[142:145], v[150:153], v[62:65]
	v_mfma_f32_16x16x32_bf16 v[118:121], v[134:137], v[174:177], v[118:121]
	v_mfma_f32_16x16x32_bf16 v[54:57], v[142:145], v[174:177], v[54:57]
	v_mfma_f32_16x16x32_bf16 v[110:113], v[134:137], v[192:195], v[110:113]
	v_mfma_f32_16x16x32_bf16 v[46:49], v[142:145], v[192:195], v[46:49]
	v_mfma_f32_16x16x32_bf16 v[102:105], v[134:137], v[200:203], v[102:105]
	v_mfma_f32_16x16x32_bf16 v[38:41], v[142:145], v[200:203], v[38:41]
	s_barrier
	s_add_i32 s58, 0, 0x14000
	v_add_u32_e32 v178, s58, v1
	s_add_i32 s33, s33, s91
	ds_read_b128 v[204:207], v178
	ds_read_b128 v[208:211], v178 offset:1024
	ds_read_b128 v[212:215], v178 offset:2048
	ds_read_b128 v[216:219], v178 offset:3072
	v_lshl_add_u64 v[178:179], s[80:81], 0, v[158:159]
	s_mov_b32 m0, s33
	v_lshl_add_u64 v[220:221], s[80:81], 0, v[154:155]
	global_load_lds_dwordx4 v[178:179], off
	s_add_i32 m0, s33, 0x2000
	s_nop 0
	global_load_lds_dwordx4 v[220:221], off
	s_barrier
	s_waitcnt lgkmcnt(0)
	s_waitcnt lgkmcnt(0)
	v_mfma_f32_16x16x32_bf16 v[122:125], v[204:207], v[146:149], v[122:125]
	v_mfma_f32_16x16x32_bf16 v[58:61], v[212:215], v[146:149], v[58:61]
	v_mfma_f32_16x16x32_bf16 v[114:117], v[204:207], v[170:173], v[114:117]
	v_mfma_f32_16x16x32_bf16 v[50:53], v[212:215], v[170:173], v[50:53]
	v_mfma_f32_16x16x32_bf16 v[106:109], v[204:207], v[184:187], v[106:109]
	v_mfma_f32_16x16x32_bf16 v[42:45], v[212:215], v[184:187], v[42:45]
	v_mfma_f32_16x16x32_bf16 v[98:101], v[204:207], v[196:199], v[98:101]
	v_mfma_f32_16x16x32_bf16 v[34:37], v[212:215], v[196:199], v[34:37]
	v_mfma_f32_16x16x32_bf16 v[122:125], v[208:211], v[150:153], v[122:125]
	v_mfma_f32_16x16x32_bf16 v[58:61], v[216:219], v[150:153], v[58:61]
	v_mfma_f32_16x16x32_bf16 v[114:117], v[208:211], v[174:177], v[114:117]
	v_mfma_f32_16x16x32_bf16 v[50:53], v[216:219], v[174:177], v[50:53]
	v_mfma_f32_16x16x32_bf16 v[106:109], v[208:211], v[192:195], v[106:109]
	v_mfma_f32_16x16x32_bf16 v[42:45], v[216:219], v[192:195], v[42:45]
	v_mfma_f32_16x16x32_bf16 v[98:101], v[208:211], v[200:203], v[98:101]
	v_mfma_f32_16x16x32_bf16 v[34:37], v[216:219], v[200:203], v[34:37]
	s_mov_b32 m0, s10
	v_lshl_add_u64 v[222:223], s[96:97], 0, v[160:161]
	s_barrier
	ds_read_b128 v[146:149], v183 offset:16384
	ds_read_b128 v[150:153], v183 offset:17408
	ds_read_b128 v[170:173], v183 offset:18432
	ds_read_b128 v[174:177], v183 offset:19456
	ds_read_b128 v[184:187], v183 offset:20480
	ds_read_b128 v[192:195], v183 offset:21504
	ds_read_b128 v[196:199], v183 offset:22528
	ds_read_b128 v[200:203], v183 offset:23552
	global_load_lds_dwordx4 v[222:223], off
	v_lshl_add_u64 v[224:225], s[96:97], 0, v[156:157]
	s_mov_b32 m0, s11
	s_nop 0
	global_load_lds_dwordx4 v[224:225], off
	s_barrier
	s_waitcnt lgkmcnt(0)
	s_waitcnt lgkmcnt(0)
	v_mfma_f32_16x16x32_bf16 v[94:97], v[130:133], v[146:149], v[94:97]
	v_mfma_f32_16x16x32_bf16 v[30:33], v[138:141], v[146:149], v[30:33]
	v_mfma_f32_16x16x32_bf16 v[86:89], v[130:133], v[170:173], v[86:89]
	v_mfma_f32_16x16x32_bf16 v[22:25], v[138:141], v[170:173], v[22:25]
	v_mfma_f32_16x16x32_bf16 v[78:81], v[130:133], v[184:187], v[78:81]
	v_mfma_f32_16x16x32_bf16 v[14:17], v[138:141], v[184:187], v[14:17]
	v_mfma_f32_16x16x32_bf16 v[70:73], v[130:133], v[196:199], v[70:73]
	v_mfma_f32_16x16x32_bf16 v[6:9], v[138:141], v[196:199], v[6:9]
	v_mfma_f32_16x16x32_bf16 v[94:97], v[134:137], v[150:153], v[94:97]
	v_mfma_f32_16x16x32_bf16 v[30:33], v[142:145], v[150:153], v[30:33]
	v_mfma_f32_16x16x32_bf16 v[86:89], v[134:137], v[174:177], v[86:89]
	v_mfma_f32_16x16x32_bf16 v[22:25], v[142:145], v[174:177], v[22:25]
	v_mfma_f32_16x16x32_bf16 v[78:81], v[134:137], v[192:195], v[78:81]
	v_mfma_f32_16x16x32_bf16 v[14:17], v[142:145], v[192:195], v[14:17]
	v_mfma_f32_16x16x32_bf16 v[70:73], v[134:137], v[200:203], v[70:73]
	v_mfma_f32_16x16x32_bf16 v[6:9], v[142:145], v[200:203], v[6:9]
	s_barrier
; #define PG8_STAGE(bufoff, gbase, voff) do { _Pragma("unroll") for (int _i = 0; _i < 2; ++_i) \
;         __builtin_amdgcn_global_load_lds((const unsigned*)((const char*)(gbase) + (voff)[_i]), (LAS unsigned*)(lds + (bufoff) + ldsw + _i * 8192), 16, 0, 0); } while (0)
; #define PG8_LDA(dst, b, h) do { _Pragma("unroll") for (int m = 0; m < 4; ++m) _Pragma("unroll") for (int k = 0; k < 2; ++k) dst[m][k] = *(const LAS bf16x8*)(lds + PG8_SA(b, h) + aoff + m * 2048 + k * 1024); } while (0)
; #define PG8_LDB(dst, b, h) do { _Pragma("unroll") for (int n = 0; n < 2; ++n) _Pragma("unroll") for (int k = 0; k < 2; ++k) dst[n][k] = *(const LAS bf16x8*)(lds + PG8_SB(b, h) + boff + n * 2048 + k * 1024); } while (0)
; #define PG8_MMA(ai, bj, At, Bt) do { __builtin_amdgcn_s_setprio(1); _Pragma("unroll") for (int m = 0; m < 4; ++m) _Pragma("unroll") for (int n = 0; n < 2; ++n) _Pragma("unroll") for (int k = 0; k < 2; ++k) \
;         acc[ai][bj][m][n] = __builtin_amdgcn_mfma_f32_16x16x32_bf16(Bt[n][k], At[m][k], acc[ai][bj][m][n], 0, 0, 0); __builtin_amdgcn_s_setprio(0); } while (0)
; #define PG8_WAIT_V(n) asm volatile("s_waitcnt vmcnt(" #n ")" ::: "memory")
; #define PG8_WAIT_L(n) asm volatile("s_waitcnt lgkmcnt(" #n ")" ::: "memory")
; #define PG8_BAR __builtin_amdgcn_s_barrier()
; #define PG8_SCHED __builtin_amdgcn_sched_barrier(0)
; template <class Epi, class Sched, bool AREMAP>
; __device__ __forceinline__ void gemm_phase(LAS unsigned char* lds, const Gemm g, const Sched& S, const Epi& E, int wv) {
;     ...
;             PG8_STAGE(PG8_SB(0, 1), b2 + hstepB, voffB);
;             PG8_WAIT_V(6); PG8_BAR; PG8_MMA(1, 1, At, B1); PG8_BAR;
;             PG8_LDB(B0, 1, 0); PG8_SCHED; PG8_LDA(At, 1, 0); PG8_STAGE(PG8_SA(0, 1), a2 + hstepA, voffA);
;             PG8_WAIT_L(8); PG8_BAR; PG8_WAIT_L(0); PG8_MMA(0, 0, At, B0); PG8_BAR; PG8_SCHED;
;             PG8_LDB(B1, 1, 1); PG8_STAGE(PG8_SB(1, 0), b3, voffB);
;             PG8_BAR; PG8_WAIT_L(0); PG8_MMA(0, 1, At, B1); PG8_BAR;
;             PG8_LDA(At, 1, 1); PG8_STAGE(PG8_SA(1, 0), a3, voffA);
	s_add_u32 s38, s80, 0x80000
	s_addc_u32 s39, s81, 0
	s_add_i32 s33, s58, s91
	s_mov_b32 m0, s33
	s_nop 0
	global_load_lds_dwordx4 v158, s[38:39]
	s_add_i32 m0, s33, 0x2000
	s_nop 0
	global_load_lds_dwordx4 v154, s[38:39]
	s_waitcnt vmcnt(6)
	s_barrier
	v_mfma_f32_16x16x32_bf16 v[90:93], v[204:207], v[146:149], v[90:93]
	v_mfma_f32_16x16x32_bf16 v[26:29], v[212:215], v[146:149], v[26:29]
	v_mfma_f32_16x16x32_bf16 v[82:85], v[204:207], v[170:173], v[82:85]
	v_mfma_f32_16x16x32_bf16 v[18:21], v[212:215], v[170:173], v[18:21]
	v_mfma_f32_16x16x32_bf16 v[74:77], v[204:207], v[184:187], v[74:77]
	v_mfma_f32_16x16x32_bf16 v[10:13], v[212:215], v[184:187], v[10:13]
	v_mfma_f32_16x16x32_bf16 v[66:69], v[204:207], v[196:199], v[66:69]
	v_mfma_f32_16x16x32_bf16 v[2:5], v[212:215], v[196:199], v[2:5]
	v_mfma_f32_16x16x32_bf16 v[90:93], v[208:211], v[150:153], v[90:93]
	v_mfma_f32_16x16x32_bf16 v[26:29], v[216:219], v[150:153], v[26:29]
	v_mfma_f32_16x16x32_bf16 v[82:85], v[208:211], v[174:177], v[82:85]
	v_mfma_f32_16x16x32_bf16 v[18:21], v[216:219], v[174:177], v[18:21]
	v_mfma_f32_16x16x32_bf16 v[74:77], v[208:211], v[192:195], v[74:77]
	v_mfma_f32_16x16x32_bf16 v[10:13], v[216:219], v[192:195], v[10:13]
	v_mfma_f32_16x16x32_bf16 v[66:69], v[208:211], v[200:203], v[66:69]
	v_mfma_f32_16x16x32_bf16 v[2:5], v[216:219], v[200:203], v[2:5]
	s_add_i32 s33, 0, 0x18000
	v_add_u32_e32 v142, s33, v1
	s_barrier
	ds_read_b128 v[130:133], v142
	ds_read_b128 v[134:137], v142 offset:1024
	ds_read_b128 v[138:141], v142 offset:2048
	ds_read_b128 v[142:145], v142 offset:3072
	s_add_u32 s38, s96, 0x40000
	s_addc_u32 s39, s97, 0
	s_mov_b32 m0, s12
	ds_read_b128 v[146:149], v183 offset:32768
	ds_read_b128 v[150:153], v183 offset:33792
	ds_read_b128 v[170:173], v183 offset:34816
	ds_read_b128 v[174:177], v183 offset:35840
	ds_read_b128 v[184:187], v183 offset:36864
	ds_read_b128 v[192:195], v183 offset:37888
	ds_read_b128 v[196:199], v183 offset:38912
	ds_read_b128 v[200:203], v183 offset:39936
	global_load_lds_dwordx4 v160, s[38:39]
	s_mov_b32 m0, s13
	s_nop 0
	global_load_lds_dwordx4 v156, s[38:39]
	s_waitcnt lgkmcnt(8)
	s_barrier
	s_waitcnt lgkmcnt(0)
	s_waitcnt lgkmcnt(0)
	v_mfma_f32_16x16x32_bf16 v[126:129], v[130:133], v[146:149], v[126:129]
	v_mfma_f32_16x16x32_bf16 v[62:65], v[138:141], v[146:149], v[62:65]
	v_mfma_f32_16x16x32_bf16 v[118:121], v[130:133], v[170:173], v[118:121]
	v_mfma_f32_16x16x32_bf16 v[54:57], v[138:141], v[170:173], v[54:57]
	v_mfma_f32_16x16x32_bf16 v[110:113], v[130:133], v[184:187], v[110:113]
	v_mfma_f32_16x16x32_bf16 v[46:49], v[138:141], v[184:187], v[46:49]
	v_mfma_f32_16x16x32_bf16 v[102:105], v[130:133], v[196:199], v[102:105]
	v_mfma_f32_16x16x32_bf16 v[38:41], v[138:141], v[196:199], v[38:41]
	v_mfma_f32_16x16x32_bf16 v[126:129], v[134:137], v[150:153], v[126:129]
	v_mfma_f32_16x16x32_bf16 v[62:65], v[142:145], v[150:153], v[62:65]
	v_mfma_f32_16x16x32_bf16 v[118:121], v[134:137], v[174:177], v[118:121]
	v_mfma_f32_16x16x32_bf16 v[54:57], v[142:145], v[174:177], v[54:57]
	v_mfma_f32_16x16x32_bf16 v[110:113], v[134:137], v[192:195], v[110:113]
	v_mfma_f32_16x16x32_bf16 v[46:49], v[142:145], v[192:195], v[46:49]
	v_mfma_f32_16x16x32_bf16 v[102:105], v[134:137], v[200:203], v[102:105]
	v_mfma_f32_16x16x32_bf16 v[38:41], v[142:145], v[200:203], v[38:41]
	s_barrier
	s_add_i32 s58, 0, 0x1c000
	s_add_i32 s33, s33, s91
	v_add_u32_e32 v216, s58, v1
	v_lshl_add_u64 v[178:179], v[178:179], 0, s[86:87]
	s_mov_b32 m0, s33
	ds_read_b128 v[204:207], v216
	ds_read_b128 v[208:211], v216 offset:1024
	ds_read_b128 v[212:215], v216 offset:2048
	ds_read_b128 v[216:219], v216 offset:3072
	global_load_lds_dwordx4 v[178:179], off
	v_lshl_add_u64 v[178:179], v[220:221], 0, s[86:87]
	s_add_i32 m0, s33, 0x2000
	s_nop 0
	global_load_lds_dwordx4 v[178:179], off
	s_barrier
	s_waitcnt lgkmcnt(0)
	s_waitcnt lgkmcnt(0)
	v_mfma_f32_16x16x32_bf16 v[122:125], v[204:207], v[146:149], v[122:125]
	v_mfma_f32_16x16x32_bf16 v[58:61], v[212:215], v[146:149], v[58:61]
	v_mfma_f32_16x16x32_bf16 v[114:117], v[204:207], v[170:173], v[114:117]
	v_mfma_f32_16x16x32_bf16 v[50:53], v[212:215], v[170:173], v[50:53]
	v_mfma_f32_16x16x32_bf16 v[106:109], v[204:207], v[184:187], v[106:109]
	v_mfma_f32_16x16x32_bf16 v[42:45], v[212:215], v[184:187], v[42:45]
	v_mfma_f32_16x16x32_bf16 v[98:101], v[204:207], v[196:199], v[98:101]
	v_mfma_f32_16x16x32_bf16 v[34:37], v[212:215], v[196:199], v[34:37]
	v_mfma_f32_16x16x32_bf16 v[122:125], v[208:211], v[150:153], v[122:125]
	v_mfma_f32_16x16x32_bf16 v[58:61], v[216:219], v[150:153], v[58:61]
	v_mfma_f32_16x16x32_bf16 v[114:117], v[208:211], v[174:177], v[114:117]
	v_mfma_f32_16x16x32_bf16 v[50:53], v[216:219], v[174:177], v[50:53]
	v_mfma_f32_16x16x32_bf16 v[106:109], v[208:211], v[192:195], v[106:109]
	v_mfma_f32_16x16x32_bf16 v[42:45], v[216:219], v[192:195], v[42:45]
	v_mfma_f32_16x16x32_bf16 v[98:101], v[208:211], v[200:203], v[98:101]
	v_mfma_f32_16x16x32_bf16 v[34:37], v[216:219], v[200:203], v[34:37]
	s_mov_b32 m0, s14
	v_lshl_add_u64 v[178:179], v[222:223], 0, s[86:87]
	s_barrier
	ds_read_b128 v[146:149], v183 offset:49152
	ds_read_b128 v[150:153], v183 offset:50176
	ds_read_b128 v[170:173], v183 offset:51200
	ds_read_b128 v[174:177], v183 offset:52224
	ds_read_b128 v[184:187], v183 offset:53248
	ds_read_b128 v[192:195], v183 offset:54272
	ds_read_b128 v[196:199], v183 offset:55296
	ds_read_b128 v[200:203], v183 offset:56320
	global_load_lds_dwordx4 v[178:179], off
	v_lshl_add_u64 v[178:179], v[224:225], 0, s[86:87]
	s_mov_b32 m0, s15
	s_nop 0
	global_load_lds_dwordx4 v[178:179], off
	s_barrier
; #define PG8_STAGE(bufoff, gbase, voff) do { _Pragma("unroll") for (int _i = 0; _i < 2; ++_i) \
;         __builtin_amdgcn_global_load_lds((const unsigned*)((const char*)(gbase) + (voff)[_i]), (LAS unsigned*)(lds + (bufoff) + ldsw + _i * 8192), 16, 0, 0); } while (0)
; #define PG8_MMA(ai, bj, At, Bt) do { __builtin_amdgcn_s_setprio(1); _Pragma("unroll") for (int m = 0; m < 4; ++m) _Pragma("unroll") for (int n = 0; n < 2; ++n) _Pragma("unroll") for (int k = 0; k < 2; ++k) \
;         acc[ai][bj][m][n] = __builtin_amdgcn_mfma_f32_16x16x32_bf16(Bt[n][k], At[m][k], acc[ai][bj][m][n], 0, 0, 0); __builtin_amdgcn_s_setprio(0); } while (0)
; #define PG8_WAIT_V(n) asm volatile("s_waitcnt vmcnt(" #n ")" ::: "memory")
; #define PG8_WAIT_L(n) asm volatile("s_waitcnt lgkmcnt(" #n ")" ::: "memory")
; #define PG8_BAR __builtin_amdgcn_s_barrier()
; #define PG8_SCHED __builtin_amdgcn_sched_barrier(0)
; template <class Epi, class Sched, bool AREMAP>
; __device__ __forceinline__ void gemm_phase(LAS unsigned char* lds, const Gemm g, const Sched& S, const Epi& E, int wv) {
;     ...
;             PG8_BAR; PG8_WAIT_L(0); PG8_MMA(1, 0, At, B0); PG8_BAR; PG8_SCHED;
;             PG8_STAGE(PG8_SB(1, 1), b3 + hstepB, voffB);
;             PG8_WAIT_V(6); PG8_BAR; PG8_MMA(1, 1, At, B1); PG8_BAR;
	s_waitcnt lgkmcnt(0)
	s_waitcnt lgkmcnt(0)
	v_mfma_f32_16x16x32_bf16 v[94:97], v[130:133], v[146:149], v[94:97]
	v_mfma_f32_16x16x32_bf16 v[30:33], v[138:141], v[146:149], v[30:33]
	v_mfma_f32_16x16x32_bf16 v[86:89], v[130:133], v[170:173], v[86:89]
	v_mfma_f32_16x16x32_bf16 v[22:25], v[138:141], v[170:173], v[22:25]
	v_mfma_f32_16x16x32_bf16 v[78:81], v[130:133], v[184:187], v[78:81]
	v_mfma_f32_16x16x32_bf16 v[14:17], v[138:141], v[184:187], v[14:17]
	v_mfma_f32_16x16x32_bf16 v[70:73], v[130:133], v[196:199], v[70:73]
	v_mfma_f32_16x16x32_bf16 v[6:9], v[138:141], v[196:199], v[6:9]
	v_mfma_f32_16x16x32_bf16 v[94:97], v[134:137], v[150:153], v[94:97]
	v_mfma_f32_16x16x32_bf16 v[30:33], v[142:145], v[150:153], v[30:33]
	v_mfma_f32_16x16x32_bf16 v[86:89], v[134:137], v[174:177], v[86:89]
	v_mfma_f32_16x16x32_bf16 v[22:25], v[142:145], v[174:177], v[22:25]
	v_mfma_f32_16x16x32_bf16 v[78:81], v[134:137], v[192:195], v[78:81]
	v_mfma_f32_16x16x32_bf16 v[14:17], v[142:145], v[192:195], v[14:17]
	v_mfma_f32_16x16x32_bf16 v[70:73], v[134:137], v[200:203], v[70:73]
	v_mfma_f32_16x16x32_bf16 v[6:9], v[142:145], v[200:203], v[6:9]
	s_barrier
	s_add_u32 s38, s80, 0x80080
	s_addc_u32 s39, s81, 0
	s_add_i32 s33, s58, s91
	s_mov_b32 m0, s33
	s_nop 0
	global_load_lds_dwordx4 v158, s[38:39]
	s_add_i32 m0, s33, 0x2000
	s_nop 0
	global_load_lds_dwordx4 v154, s[38:39]
	s_waitcnt vmcnt(6)
	s_barrier
	v_mfma_f32_16x16x32_bf16 v[90:93], v[204:207], v[146:149], v[90:93]
	v_mfma_f32_16x16x32_bf16 v[26:29], v[212:215], v[146:149], v[26:29]
	v_mfma_f32_16x16x32_bf16 v[82:85], v[204:207], v[170:173], v[82:85]
	v_mfma_f32_16x16x32_bf16 v[18:21], v[212:215], v[170:173], v[18:21]
	v_mfma_f32_16x16x32_bf16 v[74:77], v[204:207], v[184:187], v[74:77]
	v_mfma_f32_16x16x32_bf16 v[10:13], v[212:215], v[184:187], v[10:13]
	v_mfma_f32_16x16x32_bf16 v[66:69], v[204:207], v[196:199], v[66:69]
	v_mfma_f32_16x16x32_bf16 v[2:5], v[212:215], v[196:199], v[2:5]
	v_mfma_f32_16x16x32_bf16 v[90:93], v[208:211], v[150:153], v[90:93]
	v_mfma_f32_16x16x32_bf16 v[26:29], v[216:219], v[150:153], v[26:29]
	v_mfma_f32_16x16x32_bf16 v[82:85], v[208:211], v[174:177], v[82:85]
	v_mfma_f32_16x16x32_bf16 v[18:21], v[216:219], v[174:177], v[18:21]
	v_mfma_f32_16x16x32_bf16 v[74:77], v[208:211], v[192:195], v[74:77]
	v_mfma_f32_16x16x32_bf16 v[10:13], v[216:219], v[192:195], v[10:13]
	v_mfma_f32_16x16x32_bf16 v[66:69], v[208:211], v[200:203], v[66:69]
	v_mfma_f32_16x16x32_bf16 v[2:5], v[216:219], v[200:203], v[2:5]
	s_add_i32 vcc_hi, vcc_hi, 2
	s_add_u32 s77, s77, 0x100
	s_addc_u32 vcc_lo, vcc_lo, 0
	s_add_u32 s78, s78, 0x100
	s_addc_u32 s79, s79, 0
	s_cmp_gt_u32 vcc_hi, 29
	s_barrier
	s_cbranch_scc0 .LBB0_619
; __device__ __forceinline__ unsigned cvt_pk_bf16(float lo, float hi) { f32x2_t f = {lo, hi}; bf16x2_t v = __builtin_convertvector(f, bf16x2_t); return __builtin_bit_cast(unsigned, v); }
; __device__ __forceinline__ float sigmoidf_(float x) { return __builtin_amdgcn_rcpf(1.0f + __expf(-x)); }
; #define SHI(lane, v, src) shfl_idx(lane, (v), (src))
;     __device__ __forceinline__ void operator()(const f32x4 (&acc)[2][2][4][2], const Unit& u, int wr, int wc, int fr, int fq) const {
;     ...
; #pragma unroll
;         for (int n = 0; n < 2; ++n) {
;             const int ch = ch0 + 4 * n;
;             f32x4 wv[3], wg[3];
; #pragma unroll
;             for (int k = 0; k < 3; ++k) { wv[k] = *(const f32x4*)(cw + k * NUP + ch); wg[k] = *(const f32x4*)(cw + k * NUP + DFF + ch); }
;             f32x4 pv1 = {0.f, 0.f, 0.f, 0.f}, pv2 = pv1, pg1 = pv1, pg2 = pv1;
; #pragma unroll
;             for (int q = 0; q < 8; ++q) {
;                 const int ai = q >> 2, m = q & 3;
;                 const f32x4 av = acc[ai][0][m][n], ag = acc[ai][1][m][n];
;                 f32x4 rv1, rv2, rg1, rg2;
; #pragma unroll
;                 for (int j = 0; j < 4; ++j) { rv1[j] = SHI(lane, av[j], src1); rv2[j] = SHI(lane, av[j], src2); rg1[j] = SHI(lane, ag[j], src1); rg2[j] = SHI(lane, ag[j], src2); }
;                 const f32x4 sv1 = fr >= 1 ? rv1 : pv1, sv2 = fr >= 2 ? rv2 : pv2, sg1 = fr >= 1 ? rg1 : pg1, sg2 = fr >= 2 ? rg2 : pg2;
;                 const f32x4 ov = wv[2] * av + wv[1] * sv1 + wv[0] * sv2;
;                 const f32x4 og = wg[2] * ag + wg[1] * sg1 + wg[0] * sg2;
;                 u32x2 w;
;                 w.x = cvt_pk_bf16(og[0] * sigmoidf_(og[0]) * ov[0], og[1] * sigmoidf_(og[1]) * ov[1]);
;                 w.y = cvt_pk_bf16(og[2] * sigmoidf_(og[2]) * ov[2], og[3] * sigmoidf_(og[3]) * ov[3]);
;                 *(u32x2*)(act + (size_t)(tok0 + q * 16) * DFF + ch) = w;
;                 if (q == 0 && fr < 2) { float* hp = halo + ((size_t)seg * 4 + fr) * NUP + ch; *(f32x4*)hp = av; *(f32x4*)(hp + DFF) = ag; }
;                 if (q == 7 && fr >= 14) { float* hp = halo + ((size_t)seg * 4 + (fr - 12)) * NUP + ch; *(f32x4*)hp = av; *(f32x4*)(hp + DFF) = ag; }
	v_lshl_or_b32 v170, s37, 7, v182
	s_lshl_b32 s37, s76, 1
	s_add_i32 s46, s37, s75
	s_ashr_i32 s47, s46, 31
	s_lshl_b64 s[76:77], s[46:47], 2
	v_lshl_add_u64 v[130:131], s[76:77], 0, v[162:163]
	s_mov_b32 s33, 0xb000
	v_ashrrev_i32_e32 v171, 31, v170
	v_lshl_or_b32 v184, s46, 7, v162
	v_mad_u64_u32 v[176:177], s[46:47], v130, s33, 0
	v_lshlrev_b64 v[142:143], 2, v[170:171]
	v_mad_i32_i24 v177, v131, s33, v177
	v_lshl_add_u64 v[130:131], s[24:25], 0, v[142:143]
	v_lshl_add_u64 v[138:139], s[26:27], 0, v[142:143]
	global_load_dwordx4 v[130:133], v[130:131], off
	v_lshl_add_u64 v[144:145], s[30:31], 0, v[142:143]
	global_load_dwordx4 v[146:149], v[138:139], off
	v_lshl_add_u64 v[172:173], s[18:19], 0, v[142:143]
	v_lshl_add_u64 v[138:139], s[28:29], 0, v[142:143]
	global_load_dwordx4 v[150:153], v[144:145], off
	global_load_dwordx4 v[134:137], v[172:173], off
	v_lshl_add_u64 v[142:143], s[34:35], 0, v[142:143]
	global_load_dwordx4 v[138:141], v[138:139], off
	v_mov_b32_dpp v199, v126 row_ror:1 row_mask:0xf bank_mask:0xf
	global_load_dwordx4 v[142:145], v[142:143], off
	v_mov_b32_dpp v204, v127 row_ror:1 row_mask:0xf bank_mask:0xf
	v_mov_b32_dpp v206, v128 row_ror:1 row_mask:0xf bank_mask:0xf
	v_mov_b32_dpp v208, v129 row_ror:1 row_mask:0xf bank_mask:0xf
	v_mov_b32_dpp v196, v126 row_ror:2 row_mask:0xf bank_mask:0xf
	v_mov_b32_dpp v186, v122 row_ror:1 row_mask:0xf bank_mask:0xf
	v_mov_b32_dpp v201, v127 row_ror:2 row_mask:0xf bank_mask:0xf
	v_mov_b32_dpp v198, v123 row_ror:1 row_mask:0xf bank_mask:0xf
	v_mov_b32_dpp v203, v128 row_ror:2 row_mask:0xf bank_mask:0xf
	v_mov_b32_dpp v200, v124 row_ror:1 row_mask:0xf bank_mask:0xf
	v_mov_b32_dpp v207, v129 row_ror:2 row_mask:0xf bank_mask:0xf
	v_mov_b32_dpp v205, v125 row_ror:1 row_mask:0xf bank_mask:0xf
	v_mov_b32_dpp v185, v122 row_ror:2 row_mask:0xf bank_mask:0xf
	v_mov_b32_dpp v187, v123 row_ror:2 row_mask:0xf bank_mask:0xf
	v_mov_b32_dpp v197, v124 row_ror:2 row_mask:0xf bank_mask:0xf
	v_mov_b32_dpp v202, v125 row_ror:2 row_mask:0xf bank_mask:0xf
	s_waitcnt lgkmcnt(0)
	v_cndmask_b32_e64 v175, v204, 0, s[0:1]
	v_cndmask_b32_e64 v174, v199, 0, s[0:1]
	v_cndmask_b32_e64 v179, v208, 0, s[0:1]
	v_cndmask_b32_e64 v178, v206, 0, s[0:1]
	v_cndmask_b32_e64 v193, 0, v201, s[2:3]
	v_cndmask_b32_e64 v192, 0, v196, s[2:3]
	v_cndmask_b32_e64 v195, 0, v207, s[2:3]
	v_cndmask_b32_e64 v194, 0, v203, s[2:3]
	v_cndmask_b32_e64 v211, v198, 0, s[0:1]
	v_cndmask_b32_e64 v210, v186, 0, s[0:1]
	v_cndmask_b32_e64 v213, v205, 0, s[0:1]
	v_cndmask_b32_e64 v212, v200, 0, s[0:1]
	v_cndmask_b32_e64 v215, 0, v187, s[2:3]
	v_cndmask_b32_e64 v214, 0, v185, s[2:3]
	v_cndmask_b32_e64 v217, 0, v202, s[2:3]
	v_cndmask_b32_e64 v216, 0, v197, s[2:3]
	s_movk_i32 s33, 0x2c00
	v_lshl_add_u64 v[176:177], s[22:23], 0, v[176:177]
	v_lshl_add_u64 v[176:177], v[170:171], 2, v[176:177]
	s_waitcnt vmcnt(0)
	v_pk_mul_f32 v[178:179], v[148:149], v[178:179]
	v_pk_mul_f32 v[174:175], v[146:147], v[174:175]
	v_pk_fma_f32 v[178:179], v[128:129], v[152:153], v[178:179]
	v_pk_fma_f32 v[174:175], v[126:127], v[150:151], v[174:175]
	v_pk_fma_f32 v[194:195], v[136:137], v[194:195], v[178:179]
	v_pk_fma_f32 v[174:175], v[134:135], v[192:193], v[174:175]
	v_pk_mul_f32 v[178:179], v[140:141], v[212:213]
	v_pk_mul_f32 v[192:193], v[138:139], v[210:211]
	v_pk_fma_f32 v[178:179], v[124:125], v[144:145], v[178:179]
	v_pk_fma_f32 v[192:193], v[122:123], v[142:143], v[192:193]
	v_pk_fma_f32 v[210:211], v[132:133], v[216:217], v[178:179]
	v_pk_fma_f32 v[178:179], v[130:131], v[214:215], v[192:193]
	s_nop 0
	v_mul_f32_e32 v192, 0xbfb8aa3b, v178
	v_mul_f32_e32 v193, 0xbfb8aa3b, v179
	v_exp_f32_e32 v192, v192
	v_exp_f32_e32 v193, v193
	v_add_f32_e32 v192, 1.0, v192
	v_add_f32_e32 v193, 1.0, v193
	v_rcp_f32_e32 v192, v192
	v_rcp_f32_e32 v193, v193
	s_nop 0
	v_pk_mul_f32 v[178:179], v[178:179], v[192:193]
	s_nop 0
	v_pk_mul_f32 v[174:175], v[174:175], v[178:179]
	s_nop 0
	v_cvt_pk_bf16_f32 v178, v174, v175
	v_mul_f32_e32 v174, 0xbfb8aa3b, v210
	v_mul_f32_e32 v175, 0xbfb8aa3b, v211
	v_exp_f32_e32 v174, v174
	v_exp_f32_e32 v175, v175
	v_add_f32_e32 v174, 1.0, v174
	v_add_f32_e32 v175, 1.0, v175
	v_rcp_f32_e32 v174, v174
	v_rcp_f32_e32 v175, v175
	s_nop 0
	v_pk_mul_f32 v[174:175], v[210:211], v[174:175]
	s_nop 0
	v_pk_mul_f32 v[174:175], v[194:195], v[174:175]
	s_nop 0
	v_cvt_pk_bf16_f32 v179, v174, v175
	v_mov_b64_e32 v[174:175], s[20:21]
	v_mad_i64_i32 v[174:175], s[46:47], v184, s33, v[174:175]
	v_lshl_add_u64 v[174:175], v[170:171], 1, v[174:175]
	global_store_dwordx2 v[174:175], v[178:179], off
	s_and_saveexec_b64 s[78:79], s[4:5]
	s_cbranch_execz .LBB0_622
	global_store_dwordx4 v[176:177], v[126:129], off
	s_nop 1
	v_add_co_u32_e32 v126, vcc, 0x5000, v176
	s_nop 1
	v_addc_co_u32_e32 v127, vcc, 0, v177, vcc
	global_store_dwordx4 v[126:127], v[122:125], off offset:2048

; #define PG8_STAGE(bufoff, gbase, voff) do { _Pragma("unroll") for (int _i = 0; _i < 2; ++_i) \
;         __builtin_amdgcn_global_load_lds((const unsigned*)((const char*)(gbase) + (voff)[_i]), (LAS unsigned*)(lds + (bufoff) + ldsw + _i * 8192), 16, 0, 0); } while (0)
; #define PG8_WAIT_V(n) asm volatile("s_waitcnt vmcnt(" #n ")" ::: "memory")
; #define PG8_BAR __builtin_amdgcn_s_barrier()
; template <class Epi, class Sched, bool AREMAP>
; __device__ __forceinline__ void gemm_phase(LAS unsigned char* lds, const Gemm g, const Sched& S, const Epi& E, int wv) {
;     ...
;     for (int i = 0; i < 2; ++i) { int R, C; stage_rc(tid * 16 + i * 8192, R, C); const int Rb = Epi::PERM ? ((R & ~31) + perm32(R & 31)) : R;
;         const int Ra = AREMAP ? ((R >> 6) * 128 + (R & 63)) : R;
;         voffA[i] = (unsigned)(Ra * g.lda + C) * 2u; voffB[i] = (unsigned)(Rb * g.ldb + C) * 2u; }
;     const size_t kstep = (size_t)(BK * 2);
;     const size_t hstepA = (size_t)(AREMAP ? 64 : HALF) * g.lda * 2, hstepB = (size_t)HALF * g.ldb * 2;
;     const size_t tstepA = (size_t)BM * g.lda * 2, tstepB = (size_t)BM * g.ldb * 2;
;     const unsigned ldsw = (unsigned)wid * 1024u;
;     const int aoff = lds_byte(wr * 64 + fr, fq * 8), boff = lds_byte(wc * 32 + fr, fq * 8);
;     ...
;     PG8_STAGE(PG8_SB(0, 0), cB, voffB); PG8_STAGE(PG8_SA(0, 0), cA, voffA); PG8_STAGE(PG8_SB(0, 1), cB + hstepB, voffB); PG8_STAGE(PG8_SA(0, 1), cA + hstepA, voffA);
;     if (wr == 1) PG8_BAR;
;     PG8_WAIT_V(4); PG8_BAR;
;     PG8_STAGE(PG8_SB(1, 0), cB + kstep, voffB); PG8_STAGE(PG8_SA(1, 0), cA + kstep, voffA); PG8_STAGE(PG8_SB(1, 1), cB + hstepB + kstep, voffB);
;     PG8_WAIT_V(6); PG8_BAR;
.LBB0_661:
	v_bfe_u32 v18, v13, 4, 2
	v_and_b32_e32 v19, 15, v13
	v_lshlrev_b32_e32 v20, 4, v18
	v_lshlrev_b32_e32 v13, 2, v13
	v_lshl_or_b32 v249, s0, 6, v19
	v_lshl_or_b32 v19, v19, 6, v20
	s_lshl_b32 s0, s0, 13
	v_and_b32_e32 v13, 32, v13
	v_bitop3_b32 v20, v19, s0, v13 bitop3:0xde
	s_lshl_b32 s0, s1, 5
	s_and_b32 s2, s0, 0x60
	s_add_i32 m0, s35, 0x18000
	v_lshl_add_u64 v[8:9], v[8:9], 0, s[86:87]
	s_lshl_b32 s0, s2, 7
	s_waitcnt vmcnt(4)
	s_barrier
	global_load_lds_dwordx4 v[8:9], off
	v_lshl_add_u64 v[6:7], v[6:7], 0, s[86:87]
	s_add_i32 m0, s35, 0x1a000
	s_add_i32 s46, s35, 0x8000
	s_add_i32 s47, s35, 0xa000
	v_bitop3_b32 v250, v19, s0, v13 bitop3:0xde
	global_load_lds_dwordx4 v[6:7], off
	v_lshl_add_u64 v[4:5], v[4:5], 0, s[86:87]
	s_mov_b32 m0, s46
	s_add_u32 s0, s26, 0x160080
	global_load_lds_dwordx4 v[4:5], off
	v_lshl_add_u64 v[2:3], v[2:3], 0, s[86:87]
	s_mov_b32 m0, s47
	s_addc_u32 s1, s27, 0
	global_load_lds_dwordx4 v[2:3], off
	s_add_i32 m0, s35, 0x1c000
	s_nop 0
	global_load_lds_dwordx4 v196, s[0:1]
	s_add_i32 m0, s35, 0x1e000
	v_lshl_or_b32 v251, v18, 2, s2
	global_load_lds_dwordx4 v198, s[0:1]
	s_movk_i32 s2, 0x1600
	v_lshrrev_b32_e32 v3, 1, v14
	v_mul_lo_u32 v2, v15, s2
	v_mad_u64_u32 v[2:3], s[0:1], v3, s22, v[2:3]
	v_or_b32_e32 v2, v2, v16
	v_add_lshl_u32 v2, v2, v17, 1
	v_mov_b32_e32 v3, v0
	s_mov_b64 s[4:5], 0x160080
	v_lshl_add_u64 v[200:201], v[2:3], 0, s[4:5]
	v_lshrrev_b32_e32 v1, 1, v1
	v_mul_lo_u32 v2, v11, s2
	v_mad_u64_u32 v[2:3], s[0:1], v1, s22, v[2:3]
	s_waitcnt vmcnt(6)
	s_ashr_i32 s52, s11, 31
	s_ashr_i32 s53, s12, 31
	v_or_b32_e32 v1, v2, v10
	s_cmp_lg_u64 s[18:19], 0
	v_add_lshl_u32 v2, v1, v12, 1
	v_mov_b32_e32 v3, v0
	s_cselect_b64 s[20:21], -1, 0
	v_lshl_add_u64 v[202:203], v[2:3], 0, s[4:5]
	s_mov_b32 s55, 0
	v_add_u32_e32 v252, 0, v20
	s_barrier
	s_branch .LBB0_663

; #define PG8_STAGE(bufoff, gbase, voff) do { _Pragma("unroll") for (int _i = 0; _i < 2; ++_i) \
;         __builtin_amdgcn_global_load_lds((const unsigned*)((const char*)(gbase) + (voff)[_i]), (LAS unsigned*)(lds + (bufoff) + ldsw + _i * 8192), 16, 0, 0); } while (0)
; #define PG8_LDA(dst, b, h) do { _Pragma("unroll") for (int m = 0; m < 4; ++m) _Pragma("unroll") for (int k = 0; k < 2; ++k) dst[m][k] = *(const LAS bf16x8*)(lds + PG8_SA(b, h) + aoff + m * 2048 + k * 1024); } while (0)
; #define PG8_LDB(dst, b, h) do { _Pragma("unroll") for (int n = 0; n < 2; ++n) _Pragma("unroll") for (int k = 0; k < 2; ++k) dst[n][k] = *(const LAS bf16x8*)(lds + PG8_SB(b, h) + boff + n * 2048 + k * 1024); } while (0)
; #define PG8_MMA(ai, bj, At, Bt) do { __builtin_amdgcn_s_setprio(1); _Pragma("unroll") for (int m = 0; m < 4; ++m) _Pragma("unroll") for (int n = 0; n < 2; ++n) _Pragma("unroll") for (int k = 0; k < 2; ++k) \
;         acc[ai][bj][m][n] = __builtin_amdgcn_mfma_f32_16x16x32_bf16(Bt[n][k], At[m][k], acc[ai][bj][m][n], 0, 0, 0); __builtin_amdgcn_s_setprio(0); } while (0)
; #define PG8_WAIT_L(n) asm volatile("s_waitcnt lgkmcnt(" #n ")" ::: "memory")
; #define PG8_BAR __builtin_amdgcn_s_barrier()
; #define PG8_SCHED __builtin_amdgcn_sched_barrier(0)
; template <class Epi, class Sched, bool AREMAP>
; __device__ __forceinline__ void gemm_phase(LAS unsigned char* lds, const Gemm g, const Sched& S, const Epi& E, int wv) {
;     ...
;             PG8_LDB(B0, 0, 0); PG8_SCHED; PG8_LDA(At, 0, 0); PG8_STAGE(PG8_SA(1, 1), a1 + hstepA, voffA);
;             PG8_WAIT_L(8); PG8_BAR; PG8_WAIT_L(0); PG8_MMA(0, 0, At, B0); PG8_BAR; PG8_SCHED;
;             PG8_LDB(B1, 0, 1); PG8_STAGE(PG8_SB(0, 0), b2, voffB);
;             PG8_BAR; PG8_WAIT_L(0); PG8_MMA(0, 1, At, B1); PG8_BAR;
;             PG8_LDA(At, 0, 1); PG8_STAGE(PG8_SA(0, 0), a2, voffA);
;             PG8_BAR; PG8_WAIT_L(0); PG8_MMA(1, 0, At, B0); PG8_BAR; PG8_SCHED;
.LBB0_674:
	s_add_u32 s2, s24, 0x100
	s_addc_u32 s3, s25, 0
	s_add_i32 s33, 0, 0x10000
	v_add_u32_e32 v1, s33, v250
	ds_read_b128 v[130:133], v1
	ds_read_b128 v[134:137], v1 offset:1024
	ds_read_b128 v[138:141], v1 offset:2048
	ds_read_b128 v[142:145], v1 offset:3072
	s_cmpk_eq_i32 s67, 0x54
	s_cselect_b32 s29, s23, s3
	s_cselect_b32 s28, s22, s2
	s_cselect_b32 s27, s5, s66
	s_cselect_b32 s26, s4, s65
	v_lshl_add_u64 v[178:179], s[24:25], 0, v[202:203]
	s_add_i32 m0, s35, 0xc000
	ds_read_b128 v[146:149], v252
	ds_read_b128 v[150:153], v252 offset:1024
	ds_read_b128 v[154:157], v252 offset:2048
	ds_read_b128 v[158:161], v252 offset:3072
	ds_read_b128 v[162:165], v252 offset:4096
	ds_read_b128 v[166:169], v252 offset:5120
	ds_read_b128 v[170:173], v252 offset:6144
	ds_read_b128 v[174:177], v252 offset:7168
	global_load_lds_dwordx4 v[178:179], off
	v_lshl_add_u64 v[178:179], s[24:25], 0, v[200:201]
	s_add_i32 m0, s35, 0xe000
	s_nop 0
	global_load_lds_dwordx4 v[178:179], off
	s_waitcnt lgkmcnt(8)
	s_barrier
	s_waitcnt lgkmcnt(0)
	s_waitcnt lgkmcnt(0)
	v_mfma_f32_16x16x32_bf16 v[126:129], v[130:133], v[146:149], v[126:129]
	v_mfma_f32_16x16x32_bf16 v[110:113], v[138:141], v[146:149], v[110:113]
	v_mfma_f32_16x16x32_bf16 v[122:125], v[130:133], v[154:157], v[122:125]
	v_mfma_f32_16x16x32_bf16 v[106:109], v[138:141], v[154:157], v[106:109]
	v_mfma_f32_16x16x32_bf16 v[118:121], v[130:133], v[162:165], v[118:121]
	v_mfma_f32_16x16x32_bf16 v[102:105], v[138:141], v[162:165], v[102:105]
	v_mfma_f32_16x16x32_bf16 v[114:117], v[130:133], v[170:173], v[114:117]
	v_mfma_f32_16x16x32_bf16 v[98:101], v[138:141], v[170:173], v[98:101]
	v_mfma_f32_16x16x32_bf16 v[126:129], v[134:137], v[150:153], v[126:129]
	v_mfma_f32_16x16x32_bf16 v[110:113], v[142:145], v[150:153], v[110:113]
	v_mfma_f32_16x16x32_bf16 v[122:125], v[134:137], v[158:161], v[122:125]
	v_mfma_f32_16x16x32_bf16 v[106:109], v[142:145], v[158:161], v[106:109]
	v_mfma_f32_16x16x32_bf16 v[118:121], v[134:137], v[166:169], v[118:121]
	v_mfma_f32_16x16x32_bf16 v[102:105], v[142:145], v[166:169], v[102:105]
	v_mfma_f32_16x16x32_bf16 v[114:117], v[134:137], v[174:177], v[114:117]
	v_mfma_f32_16x16x32_bf16 v[98:101], v[142:145], v[174:177], v[98:101]
	s_barrier
	s_add_i32 s38, 0, 0x14000
	s_add_i32 s24, s33, s34
	v_add_u32_e32 v1, s38, v250
	v_lshl_add_u64 v[186:187], s[26:27], 0, v[196:197]
	s_mov_b32 m0, s24
	ds_read_b128 v[178:181], v1
	ds_read_b128 v[182:185], v1 offset:1024
	ds_read_b128 v[192:195], v1 offset:2048
	ds_read_b128 v[204:207], v1 offset:3072
	global_load_lds_dwordx4 v[186:187], off
	v_lshl_add_u64 v[208:209], s[26:27], 0, v[198:199]
	s_add_i32 m0, s24, 0x2000
	s_nop 0
	global_load_lds_dwordx4 v[208:209], off
	s_barrier
	s_waitcnt lgkmcnt(0)
	s_waitcnt lgkmcnt(0)
	v_mfma_f32_16x16x32_bf16 v[94:97], v[178:181], v[146:149], v[94:97]
	v_mfma_f32_16x16x32_bf16 v[78:81], v[192:195], v[146:149], v[78:81]
	v_mfma_f32_16x16x32_bf16 v[90:93], v[178:181], v[154:157], v[90:93]
	v_mfma_f32_16x16x32_bf16 v[74:77], v[192:195], v[154:157], v[74:77]
	v_mfma_f32_16x16x32_bf16 v[86:89], v[178:181], v[162:165], v[86:89]
	v_mfma_f32_16x16x32_bf16 v[70:73], v[192:195], v[162:165], v[70:73]
	v_mfma_f32_16x16x32_bf16 v[82:85], v[178:181], v[170:173], v[82:85]
	v_mfma_f32_16x16x32_bf16 v[66:69], v[192:195], v[170:173], v[66:69]
	v_mfma_f32_16x16x32_bf16 v[94:97], v[182:185], v[150:153], v[94:97]
	v_mfma_f32_16x16x32_bf16 v[78:81], v[204:207], v[150:153], v[78:81]
	v_mfma_f32_16x16x32_bf16 v[90:93], v[182:185], v[158:161], v[90:93]
	v_mfma_f32_16x16x32_bf16 v[74:77], v[204:207], v[158:161], v[74:77]
	v_mfma_f32_16x16x32_bf16 v[86:89], v[182:185], v[166:169], v[86:89]
	v_mfma_f32_16x16x32_bf16 v[70:73], v[204:207], v[166:169], v[70:73]
	v_mfma_f32_16x16x32_bf16 v[82:85], v[182:185], v[174:177], v[82:85]
	v_mfma_f32_16x16x32_bf16 v[66:69], v[204:207], v[174:177], v[66:69]
	s_mov_b32 m0, s35
	v_lshl_add_u64 v[210:211], s[28:29], 0, v[196:197]
	s_barrier
	ds_read_b128 v[146:149], v252 offset:16384
	ds_read_b128 v[150:153], v252 offset:17408
	ds_read_b128 v[154:157], v252 offset:18432
	ds_read_b128 v[158:161], v252 offset:19456
	ds_read_b128 v[162:165], v252 offset:20480
	ds_read_b128 v[166:169], v252 offset:21504
	ds_read_b128 v[170:173], v252 offset:22528
	ds_read_b128 v[174:177], v252 offset:23552
	global_load_lds_dwordx4 v[210:211], off
	v_lshl_add_u64 v[212:213], s[28:29], 0, v[198:199]
	s_mov_b32 m0, s36
	s_nop 0
	global_load_lds_dwordx4 v[212:213], off
	s_barrier
	s_waitcnt lgkmcnt(0)
	s_waitcnt lgkmcnt(0)
	v_mfma_f32_16x16x32_bf16 v[62:65], v[130:133], v[146:149], v[62:65]
	v_mfma_f32_16x16x32_bf16 v[46:49], v[138:141], v[146:149], v[46:49]
	v_mfma_f32_16x16x32_bf16 v[58:61], v[130:133], v[154:157], v[58:61]
	v_mfma_f32_16x16x32_bf16 v[42:45], v[138:141], v[154:157], v[42:45]
	v_mfma_f32_16x16x32_bf16 v[54:57], v[130:133], v[162:165], v[54:57]
	v_mfma_f32_16x16x32_bf16 v[38:41], v[138:141], v[162:165], v[38:41]
	v_mfma_f32_16x16x32_bf16 v[50:53], v[130:133], v[170:173], v[50:53]
	v_mfma_f32_16x16x32_bf16 v[34:37], v[138:141], v[170:173], v[34:37]
	v_mfma_f32_16x16x32_bf16 v[62:65], v[134:137], v[150:153], v[62:65]
	v_mfma_f32_16x16x32_bf16 v[46:49], v[142:145], v[150:153], v[46:49]
	v_mfma_f32_16x16x32_bf16 v[58:61], v[134:137], v[158:161], v[58:61]
	v_mfma_f32_16x16x32_bf16 v[42:45], v[142:145], v[158:161], v[42:45]
	v_mfma_f32_16x16x32_bf16 v[54:57], v[134:137], v[166:169], v[54:57]
	v_mfma_f32_16x16x32_bf16 v[38:41], v[142:145], v[166:169], v[38:41]
	v_mfma_f32_16x16x32_bf16 v[50:53], v[134:137], v[174:177], v[50:53]
	v_mfma_f32_16x16x32_bf16 v[34:37], v[142:145], v[174:177], v[34:37]
	s_barrier
; #define PG8_STAGE(bufoff, gbase, voff) do { _Pragma("unroll") for (int _i = 0; _i < 2; ++_i) \
;         __builtin_amdgcn_global_load_lds((const unsigned*)((const char*)(gbase) + (voff)[_i]), (LAS unsigned*)(lds + (bufoff) + ldsw + _i * 8192), 16, 0, 0); } while (0)
; #define PG8_LDA(dst, b, h) do { _Pragma("unroll") for (int m = 0; m < 4; ++m) _Pragma("unroll") for (int k = 0; k < 2; ++k) dst[m][k] = *(const LAS bf16x8*)(lds + PG8_SA(b, h) + aoff + m * 2048 + k * 1024); } while (0)
; #define PG8_LDB(dst, b, h) do { _Pragma("unroll") for (int n = 0; n < 2; ++n) _Pragma("unroll") for (int k = 0; k < 2; ++k) dst[n][k] = *(const LAS bf16x8*)(lds + PG8_SB(b, h) + boff + n * 2048 + k * 1024); } while (0)
; #define PG8_MMA(ai, bj, At, Bt) do { __builtin_amdgcn_s_setprio(1); _Pragma("unroll") for (int m = 0; m < 4; ++m) _Pragma("unroll") for (int n = 0; n < 2; ++n) _Pragma("unroll") for (int k = 0; k < 2; ++k) \
;         acc[ai][bj][m][n] = __builtin_amdgcn_mfma_f32_16x16x32_bf16(Bt[n][k], At[m][k], acc[ai][bj][m][n], 0, 0, 0); __builtin_amdgcn_s_setprio(0); } while (0)
; #define PG8_WAIT_V(n) asm volatile("s_waitcnt vmcnt(" #n ")" ::: "memory")
; #define PG8_WAIT_L(n) asm volatile("s_waitcnt lgkmcnt(" #n ")" ::: "memory")
; #define PG8_BAR __builtin_amdgcn_s_barrier()
; #define PG8_SCHED __builtin_amdgcn_sched_barrier(0)
; template <class Epi, class Sched, bool AREMAP>
; __device__ __forceinline__ void gemm_phase(LAS unsigned char* lds, const Gemm g, const Sched& S, const Epi& E, int wv) {
;     ...
;             PG8_STAGE(PG8_SB(0, 1), b2 + hstepB, voffB);
;             PG8_WAIT_V(6); PG8_BAR; PG8_MMA(1, 1, At, B1); PG8_BAR;
;             PG8_LDB(B0, 1, 0); PG8_SCHED; PG8_LDA(At, 1, 0); PG8_STAGE(PG8_SA(0, 1), a2 + hstepA, voffA);
;             PG8_WAIT_L(8); PG8_BAR; PG8_WAIT_L(0); PG8_MMA(0, 0, At, B0); PG8_BAR; PG8_SCHED;
;             PG8_LDB(B1, 1, 1); PG8_STAGE(PG8_SB(1, 0), b3, voffB);
;             PG8_BAR; PG8_WAIT_L(0); PG8_MMA(0, 1, At, B1); PG8_BAR;
;             PG8_LDA(At, 1, 1); PG8_STAGE(PG8_SA(1, 0), a3, voffA);
	s_add_u32 s24, s26, 0x160000
	s_addc_u32 s25, s27, 0
	s_add_i32 s33, s38, s34
	s_mov_b32 m0, s33
	s_nop 0
	global_load_lds_dwordx4 v196, s[24:25]
	s_add_i32 m0, s33, 0x2000
	s_nop 0
	global_load_lds_dwordx4 v198, s[24:25]
	s_waitcnt vmcnt(6)
	s_barrier
	v_mfma_f32_16x16x32_bf16 v[30:33], v[178:181], v[146:149], v[30:33]
	v_mfma_f32_16x16x32_bf16 v[14:17], v[192:195], v[146:149], v[14:17]
	v_mfma_f32_16x16x32_bf16 v[26:29], v[178:181], v[154:157], v[26:29]
	v_mfma_f32_16x16x32_bf16 v[10:13], v[192:195], v[154:157], v[10:13]
	v_mfma_f32_16x16x32_bf16 v[22:25], v[178:181], v[162:165], v[22:25]
	v_mfma_f32_16x16x32_bf16 v[6:9], v[192:195], v[162:165], v[6:9]
	v_mfma_f32_16x16x32_bf16 v[18:21], v[178:181], v[170:173], v[18:21]
	v_mfma_f32_16x16x32_bf16 v[2:5], v[192:195], v[170:173], v[2:5]
	v_mfma_f32_16x16x32_bf16 v[30:33], v[182:185], v[150:153], v[30:33]
	v_mfma_f32_16x16x32_bf16 v[14:17], v[204:207], v[150:153], v[14:17]
	v_mfma_f32_16x16x32_bf16 v[26:29], v[182:185], v[158:161], v[26:29]
	v_mfma_f32_16x16x32_bf16 v[10:13], v[204:207], v[158:161], v[10:13]
	v_mfma_f32_16x16x32_bf16 v[22:25], v[182:185], v[166:169], v[22:25]
	v_mfma_f32_16x16x32_bf16 v[6:9], v[204:207], v[166:169], v[6:9]
	v_mfma_f32_16x16x32_bf16 v[18:21], v[182:185], v[174:177], v[18:21]
	v_mfma_f32_16x16x32_bf16 v[2:5], v[204:207], v[174:177], v[2:5]
	s_add_i32 s33, 0, 0x18000
	v_add_u32_e32 v1, s33, v250
	s_barrier
	ds_read_b128 v[130:133], v1
	ds_read_b128 v[134:137], v1 offset:1024
	ds_read_b128 v[138:141], v1 offset:2048
	ds_read_b128 v[142:145], v1 offset:3072
	s_add_u32 s24, s28, 0x160000
	s_addc_u32 s25, s29, 0
	s_mov_b32 m0, s37
	ds_read_b128 v[146:149], v252 offset:32768
	ds_read_b128 v[150:153], v252 offset:33792
	ds_read_b128 v[154:157], v252 offset:34816
	ds_read_b128 v[158:161], v252 offset:35840
	ds_read_b128 v[162:165], v252 offset:36864
	ds_read_b128 v[166:169], v252 offset:37888
	ds_read_b128 v[170:173], v252 offset:38912
	ds_read_b128 v[174:177], v252 offset:39936
	global_load_lds_dwordx4 v196, s[24:25]
	s_mov_b32 m0, s41
	s_nop 0
	global_load_lds_dwordx4 v198, s[24:25]
	s_waitcnt lgkmcnt(8)
	s_barrier
	s_waitcnt lgkmcnt(0)
	s_waitcnt lgkmcnt(0)
	v_mfma_f32_16x16x32_bf16 v[126:129], v[130:133], v[146:149], v[126:129]
	v_mfma_f32_16x16x32_bf16 v[110:113], v[138:141], v[146:149], v[110:113]
	v_mfma_f32_16x16x32_bf16 v[122:125], v[130:133], v[154:157], v[122:125]
	v_mfma_f32_16x16x32_bf16 v[106:109], v[138:141], v[154:157], v[106:109]
	v_mfma_f32_16x16x32_bf16 v[118:121], v[130:133], v[162:165], v[118:121]
	v_mfma_f32_16x16x32_bf16 v[102:105], v[138:141], v[162:165], v[102:105]
	v_mfma_f32_16x16x32_bf16 v[114:117], v[130:133], v[170:173], v[114:117]
	v_mfma_f32_16x16x32_bf16 v[98:101], v[138:141], v[170:173], v[98:101]
	v_mfma_f32_16x16x32_bf16 v[126:129], v[134:137], v[150:153], v[126:129]
	v_mfma_f32_16x16x32_bf16 v[110:113], v[142:145], v[150:153], v[110:113]
	v_mfma_f32_16x16x32_bf16 v[122:125], v[134:137], v[158:161], v[122:125]
	v_mfma_f32_16x16x32_bf16 v[106:109], v[142:145], v[158:161], v[106:109]
	v_mfma_f32_16x16x32_bf16 v[118:121], v[134:137], v[166:169], v[118:121]
	v_mfma_f32_16x16x32_bf16 v[102:105], v[142:145], v[166:169], v[102:105]
	v_mfma_f32_16x16x32_bf16 v[114:117], v[134:137], v[174:177], v[114:117]
	v_mfma_f32_16x16x32_bf16 v[98:101], v[142:145], v[174:177], v[98:101]
	s_barrier
	s_add_i32 s28, 0, 0x1c000
	s_add_i32 s24, s33, s34
	v_add_u32_e32 v1, s28, v250
	v_lshl_add_u64 v[186:187], v[186:187], 0, s[86:87]
	s_mov_b32 m0, s24
	ds_read_b128 v[178:181], v1
	ds_read_b128 v[182:185], v1 offset:1024
	ds_read_b128 v[192:195], v1 offset:2048
	ds_read_b128 v[204:207], v1 offset:3072
	global_load_lds_dwordx4 v[186:187], off
	v_lshl_add_u64 v[186:187], v[208:209], 0, s[86:87]
	s_add_i32 m0, s24, 0x2000
	s_nop 0
	global_load_lds_dwordx4 v[186:187], off
	s_barrier
; #define PG8_STAGE(bufoff, gbase, voff) do { _Pragma("unroll") for (int _i = 0; _i < 2; ++_i) \
;         __builtin_amdgcn_global_load_lds((const unsigned*)((const char*)(gbase) + (voff)[_i]), (LAS unsigned*)(lds + (bufoff) + ldsw + _i * 8192), 16, 0, 0); } while (0)
; #define PG8_LDA(dst, b, h) do { _Pragma("unroll") for (int m = 0; m < 4; ++m) _Pragma("unroll") for (int k = 0; k < 2; ++k) dst[m][k] = *(const LAS bf16x8*)(lds + PG8_SA(b, h) + aoff + m * 2048 + k * 1024); } while (0)
; #define PG8_MMA(ai, bj, At, Bt) do { __builtin_amdgcn_s_setprio(1); _Pragma("unroll") for (int m = 0; m < 4; ++m) _Pragma("unroll") for (int n = 0; n < 2; ++n) _Pragma("unroll") for (int k = 0; k < 2; ++k) \
;         acc[ai][bj][m][n] = __builtin_amdgcn_mfma_f32_16x16x32_bf16(Bt[n][k], At[m][k], acc[ai][bj][m][n], 0, 0, 0); __builtin_amdgcn_s_setprio(0); } while (0)
; #define PG8_WAIT_V(n) asm volatile("s_waitcnt vmcnt(" #n ")" ::: "memory")
; #define PG8_WAIT_L(n) asm volatile("s_waitcnt lgkmcnt(" #n ")" ::: "memory")
; #define PG8_BAR __builtin_amdgcn_s_barrier()
; #define PG8_SCHED __builtin_amdgcn_sched_barrier(0)
; template <class Epi, class Sched, bool AREMAP>
; __device__ __forceinline__ void gemm_phase(LAS unsigned char* lds, const Gemm g, const Sched& S, const Epi& E, int wv) {
;     ...
;             PG8_LDA(At, 1, 1); PG8_STAGE(PG8_SA(1, 0), a3, voffA);
;             PG8_BAR; PG8_WAIT_L(0); PG8_MMA(1, 0, At, B0); PG8_BAR; PG8_SCHED;
;             PG8_STAGE(PG8_SB(1, 1), b3 + hstepB, voffB);
;             PG8_WAIT_V(6); PG8_BAR; PG8_MMA(1, 1, At, B1); PG8_BAR;
;         }
;         E(acc, cur, wr, wc, fr, fq);
;     __device__ __forceinline__ void operator()(const f32x4 (&acc)[2][2][4][2], const Unit& u, int wr, int wc, int fr, int fq) const {
;         const int row0 = u.pm * BM + wr * 64 + fr, col0 = u.pn * BM + wc * 32 + 4 * fq;
;         const float* gv = gate + (size_t)(u.pm >> 3) * 12288 + col0;
; #pragma unroll
;         for (int ai = 0; ai < 2; ++ai) {
;             float mu[4], rs[4];
; #pragma unroll
;             for (int m = 0; m < 4; ++m) { mu[m] = 0.f; rs[m] = 1.f;
;                 if (stats) { const float* sp = stats + (size_t)(row0 + ai * HALF + m * 16) * 2; mu[m] = sp[0]; rs[m] = sp[1]; } }
	s_waitcnt lgkmcnt(0)
	s_waitcnt lgkmcnt(0)
	v_mfma_f32_16x16x32_bf16 v[94:97], v[178:181], v[146:149], v[94:97]
	v_mfma_f32_16x16x32_bf16 v[78:81], v[192:195], v[146:149], v[78:81]
	v_mfma_f32_16x16x32_bf16 v[90:93], v[178:181], v[154:157], v[90:93]
	v_mfma_f32_16x16x32_bf16 v[74:77], v[192:195], v[154:157], v[74:77]
	v_mfma_f32_16x16x32_bf16 v[86:89], v[178:181], v[162:165], v[86:89]
	v_mfma_f32_16x16x32_bf16 v[70:73], v[192:195], v[162:165], v[70:73]
	v_mfma_f32_16x16x32_bf16 v[82:85], v[178:181], v[170:173], v[82:85]
	v_mfma_f32_16x16x32_bf16 v[66:69], v[192:195], v[170:173], v[66:69]
	v_mfma_f32_16x16x32_bf16 v[94:97], v[182:185], v[150:153], v[94:97]
	v_mfma_f32_16x16x32_bf16 v[78:81], v[204:207], v[150:153], v[78:81]
	v_mfma_f32_16x16x32_bf16 v[90:93], v[182:185], v[158:161], v[90:93]
	v_mfma_f32_16x16x32_bf16 v[74:77], v[204:207], v[158:161], v[74:77]
	v_mfma_f32_16x16x32_bf16 v[86:89], v[182:185], v[166:169], v[86:89]
	v_mfma_f32_16x16x32_bf16 v[70:73], v[204:207], v[166:169], v[70:73]
	v_mfma_f32_16x16x32_bf16 v[82:85], v[182:185], v[174:177], v[82:85]
	v_mfma_f32_16x16x32_bf16 v[66:69], v[204:207], v[174:177], v[66:69]
	s_mov_b32 m0, s46
	v_lshl_add_u64 v[186:187], v[210:211], 0, s[86:87]
	s_barrier
	ds_read_b128 v[146:149], v252 offset:49152
	ds_read_b128 v[150:153], v252 offset:50176
	ds_read_b128 v[154:157], v252 offset:51200
	ds_read_b128 v[158:161], v252 offset:52224
	ds_read_b128 v[162:165], v252 offset:53248
	ds_read_b128 v[166:169], v252 offset:54272
	ds_read_b128 v[170:173], v252 offset:55296
	ds_read_b128 v[174:177], v252 offset:56320
	global_load_lds_dwordx4 v[186:187], off
	v_lshl_add_u64 v[186:187], v[212:213], 0, s[86:87]
	s_mov_b32 m0, s47
	s_nop 0
	global_load_lds_dwordx4 v[186:187], off
	s_barrier
	s_waitcnt lgkmcnt(0)
	s_waitcnt lgkmcnt(0)
	v_mfma_f32_16x16x32_bf16 v[62:65], v[130:133], v[146:149], v[62:65]
	v_mfma_f32_16x16x32_bf16 v[46:49], v[138:141], v[146:149], v[46:49]
	v_mfma_f32_16x16x32_bf16 v[58:61], v[130:133], v[154:157], v[58:61]
	v_mfma_f32_16x16x32_bf16 v[42:45], v[138:141], v[154:157], v[42:45]
	v_mfma_f32_16x16x32_bf16 v[54:57], v[130:133], v[162:165], v[54:57]
	v_mfma_f32_16x16x32_bf16 v[38:41], v[138:141], v[162:165], v[38:41]
	v_mfma_f32_16x16x32_bf16 v[50:53], v[130:133], v[170:173], v[50:53]
	v_mfma_f32_16x16x32_bf16 v[34:37], v[138:141], v[170:173], v[34:37]
	v_mfma_f32_16x16x32_bf16 v[62:65], v[134:137], v[150:153], v[62:65]
	v_mfma_f32_16x16x32_bf16 v[46:49], v[142:145], v[150:153], v[46:49]
	v_mfma_f32_16x16x32_bf16 v[58:61], v[134:137], v[158:161], v[58:61]
	v_mfma_f32_16x16x32_bf16 v[42:45], v[142:145], v[158:161], v[42:45]
	v_mfma_f32_16x16x32_bf16 v[54:57], v[134:137], v[166:169], v[54:57]
	v_mfma_f32_16x16x32_bf16 v[38:41], v[142:145], v[166:169], v[38:41]
	v_mfma_f32_16x16x32_bf16 v[50:53], v[134:137], v[174:177], v[50:53]
	v_mfma_f32_16x16x32_bf16 v[34:37], v[142:145], v[174:177], v[34:37]
	s_barrier
	s_add_u32 s24, s26, 0x160080
	s_addc_u32 s25, s27, 0
	s_add_i32 s26, s28, s34
	s_mov_b32 m0, s26
	s_nop 0
	global_load_lds_dwordx4 v196, s[24:25]
	s_add_i32 m0, s26, 0x2000
	s_nop 0
	global_load_lds_dwordx4 v198, s[24:25]
	s_waitcnt vmcnt(6)
	s_barrier
	v_mfma_f32_16x16x32_bf16 v[30:33], v[178:181], v[146:149], v[30:33]
	v_mfma_f32_16x16x32_bf16 v[14:17], v[192:195], v[146:149], v[14:17]
	v_mfma_f32_16x16x32_bf16 v[26:29], v[178:181], v[154:157], v[26:29]
	v_mfma_f32_16x16x32_bf16 v[10:13], v[192:195], v[154:157], v[10:13]
	v_mfma_f32_16x16x32_bf16 v[22:25], v[178:181], v[162:165], v[22:25]
	v_mfma_f32_16x16x32_bf16 v[6:9], v[192:195], v[162:165], v[6:9]
	v_mfma_f32_16x16x32_bf16 v[18:21], v[178:181], v[170:173], v[18:21]
	v_mfma_f32_16x16x32_bf16 v[2:5], v[192:195], v[170:173], v[2:5]
	v_mfma_f32_16x16x32_bf16 v[30:33], v[182:185], v[150:153], v[30:33]
	v_mfma_f32_16x16x32_bf16 v[14:17], v[204:207], v[150:153], v[14:17]
	v_mfma_f32_16x16x32_bf16 v[26:29], v[182:185], v[158:161], v[26:29]
	v_mfma_f32_16x16x32_bf16 v[10:13], v[204:207], v[158:161], v[10:13]
	v_mfma_f32_16x16x32_bf16 v[22:25], v[182:185], v[166:169], v[22:25]
	v_mfma_f32_16x16x32_bf16 v[6:9], v[204:207], v[166:169], v[6:9]
	v_mfma_f32_16x16x32_bf16 v[18:21], v[182:185], v[174:177], v[18:21]
	v_mfma_f32_16x16x32_bf16 v[2:5], v[204:207], v[174:177], v[2:5]
	s_add_i32 s67, s67, 2
	s_add_u32 s65, s65, 0x100
	s_addc_u32 s66, s66, 0
	s_cmpk_gt_u32 s67, 0x55
	s_mov_b64 s[24:25], s[2:3]
	s_barrier
	s_cbranch_scc0 .LBB0_674
	v_lshl_add_u32 v212, s62, 8, v249
	v_cndmask_b32_e64 v1, 0, 1, s[20:21]
	v_mov_b32_e32 v216, 1.0
	v_cmp_ne_u32_e64 s[2:3], 1, v1
	s_andn2_b64 vcc, exec, s[20:21]
	v_ashrrev_i32_e32 v213, 31, v212
	s_cbranch_vccnz .LBB0_677
	v_lshl_add_u64 v[130:131], v[212:213], 3, s[18:19]
	global_load_dwordx2 v[134:135], v[130:131], off
	s_branch .LBB0_678
